# kpair variant: A-fragment-major with boustrophedon B order + dropwaits + rotary
# speedup vs baseline: 1.0930x; 1.0067x over previous
.LBB0_642:
	ds_read_b128 v[148:151], v139
	ds_read_b128 v[152:155], v139 offset:1024
	ds_read_b128 v[156:159], v139 offset:2048
	ds_read_b128 v[160:163], v139 offset:3072
	ds_read_b128 v[164:167], v140
	ds_read_b128 v[168:171], v140 offset:1024
	ds_read_b128 v[172:175], v140 offset:2048
	ds_read_b128 v[176:179], v140 offset:3072
	s_add_i32 s18, s71, 0xffe80080
	s_cmp_eq_u32 s58, s73
	s_cselect_b32 s74, s69, s18
	s_cselect_b32 s76, s70, s72
	s_or_b32 s75, s74, 0x80
	s_add_i32 s18, s71, 0xfff80000
	s_mov_b32 m0, s59
	ds_read_b128 v[180:183], v141
	ds_read_b128 v[184:187], v141 offset:1024
	ds_read_b128 v[188:191], v141 offset:2048
	ds_read_b128 v[192:195], v141 offset:3072
	ds_read_b128 v[196:199], v141 offset:4096
	ds_read_b128 v[200:203], v141 offset:5120
	ds_read_b128 v[204:207], v141 offset:6144
	ds_read_b128 v[208:211], v141 offset:7168
	buffer_load_dwordx4 v137, s[12:15], s18 offen lds
	s_mov_b32 m0, s60
	s_nop 0
	buffer_load_dwordx4 v137, s[12:15], s71 offen lds
	s_waitcnt vmcnt(8)
	s_waitcnt lgkmcnt(0)
	s_setprio 1
	v_mfma_f32_16x16x32_bf16 v[118:121], v[148:151], v[180:183], v[118:121]
	s_barrier
	v_mfma_f32_16x16x32_bf16 v[118:121], v[152:155], v[184:187], v[118:121]
	v_mfma_f32_16x16x32_bf16 v[114:117], v[156:159], v[180:183], v[114:117]
	v_mfma_f32_16x16x32_bf16 v[114:117], v[160:163], v[184:187], v[114:117]
	v_mfma_f32_16x16x32_bf16 v[126:129], v[164:167], v[180:183], v[126:129]
	v_mfma_f32_16x16x32_bf16 v[126:129], v[168:171], v[184:187], v[126:129]
	v_mfma_f32_16x16x32_bf16 v[122:125], v[172:175], v[180:183], v[122:125]
	v_mfma_f32_16x16x32_bf16 v[122:125], v[176:179], v[184:187], v[122:125]
	v_mfma_f32_16x16x32_bf16 v[98:101], v[172:175], v[188:191], v[98:101]
	v_mfma_f32_16x16x32_bf16 v[98:101], v[176:179], v[192:195], v[98:101]
	v_mfma_f32_16x16x32_bf16 v[106:109], v[164:167], v[188:191], v[106:109]
	v_mfma_f32_16x16x32_bf16 v[106:109], v[168:171], v[192:195], v[106:109]
	v_mfma_f32_16x16x32_bf16 v[102:105], v[156:159], v[188:191], v[102:105]
	v_mfma_f32_16x16x32_bf16 v[102:105], v[160:163], v[192:195], v[102:105]
	v_mfma_f32_16x16x32_bf16 v[110:113], v[148:151], v[188:191], v[110:113]
	v_mfma_f32_16x16x32_bf16 v[110:113], v[152:155], v[192:195], v[110:113]
	v_mfma_f32_16x16x32_bf16 v[94:97], v[148:151], v[196:199], v[94:97]
	v_mfma_f32_16x16x32_bf16 v[94:97], v[152:155], v[200:203], v[94:97]
	v_mfma_f32_16x16x32_bf16 v[86:89], v[156:159], v[196:199], v[86:89]
	v_mfma_f32_16x16x32_bf16 v[86:89], v[160:163], v[200:203], v[86:89]
	v_mfma_f32_16x16x32_bf16 v[90:93], v[164:167], v[196:199], v[90:93]
	v_mfma_f32_16x16x32_bf16 v[90:93], v[168:171], v[200:203], v[90:93]
	v_mfma_f32_16x16x32_bf16 v[82:85], v[172:175], v[196:199], v[82:85]
	v_mfma_f32_16x16x32_bf16 v[82:85], v[176:179], v[200:203], v[82:85]
	v_mfma_f32_16x16x32_bf16 v[70:73], v[172:175], v[204:207], v[70:73]
	v_mfma_f32_16x16x32_bf16 v[70:73], v[176:179], v[208:211], v[70:73]
	v_mfma_f32_16x16x32_bf16 v[74:77], v[164:167], v[204:207], v[74:77]
	v_mfma_f32_16x16x32_bf16 v[74:77], v[168:171], v[208:211], v[74:77]
	v_mfma_f32_16x16x32_bf16 v[66:69], v[156:159], v[204:207], v[66:69]
	v_mfma_f32_16x16x32_bf16 v[66:69], v[160:163], v[208:211], v[66:69]
	v_mfma_f32_16x16x32_bf16 v[78:81], v[148:151], v[204:207], v[78:81]
	v_mfma_f32_16x16x32_bf16 v[78:81], v[152:155], v[208:211], v[78:81]
	s_setprio 0
	s_barrier
	s_mov_b32 m0, s30
	s_mov_b32 s18, s14
	s_mov_b32 s19, s15
	ds_read_b128 v[180:183], v141 offset:16384
	ds_read_b128 v[184:187], v141 offset:17408
	ds_read_b128 v[188:191], v141 offset:18432
	ds_read_b128 v[192:195], v141 offset:19456
	ds_read_b128 v[196:199], v141 offset:20480
	ds_read_b128 v[200:203], v141 offset:21504
	ds_read_b128 v[204:207], v141 offset:22528
	ds_read_b128 v[208:211], v141 offset:23552
	buffer_load_dwordx4 v138, s[16:19], s76 offen lds
	s_add_i32 s77, s76, 0x80000
	s_mov_b32 m0, s31
	s_nop 0
	buffer_load_dwordx4 v138, s[16:19], s77 offen lds
	s_add_i32 s77, s76, 0x100000
	s_mov_b32 m0, s44
	s_nop 0
	buffer_load_dwordx4 v138, s[16:19], s77 offen lds
	s_add_i32 s77, s76, 0x180000
	s_mov_b32 m0, s45
	s_nop 0
	buffer_load_dwordx4 v138, s[16:19], s77 offen lds
	s_mov_b32 m0, s27
	s_add_i32 s77, s74, 0x80000
	buffer_load_dwordx4 v137, s[12:15], s74 offen lds
	s_mov_b32 m0, s46
	s_nop 0
	buffer_load_dwordx4 v137, s[12:15], s77 offen lds
	s_waitcnt vmcnt(8)
	s_waitcnt lgkmcnt(0)
	s_setprio 1
	v_mfma_f32_16x16x32_bf16 v[62:65], v[148:151], v[180:183], v[62:65]
	s_barrier
	v_mfma_f32_16x16x32_bf16 v[62:65], v[152:155], v[184:187], v[62:65]
	v_mfma_f32_16x16x32_bf16 v[54:57], v[156:159], v[180:183], v[54:57]
	v_mfma_f32_16x16x32_bf16 v[54:57], v[160:163], v[184:187], v[54:57]
	v_mfma_f32_16x16x32_bf16 v[58:61], v[164:167], v[180:183], v[58:61]
	v_mfma_f32_16x16x32_bf16 v[58:61], v[168:171], v[184:187], v[58:61]
	v_mfma_f32_16x16x32_bf16 v[50:53], v[172:175], v[180:183], v[50:53]
	v_mfma_f32_16x16x32_bf16 v[50:53], v[176:179], v[184:187], v[50:53]
	v_mfma_f32_16x16x32_bf16 v[34:37], v[172:175], v[188:191], v[34:37]
	v_mfma_f32_16x16x32_bf16 v[34:37], v[176:179], v[192:195], v[34:37]
	v_mfma_f32_16x16x32_bf16 v[42:45], v[164:167], v[188:191], v[42:45]
	v_mfma_f32_16x16x32_bf16 v[42:45], v[168:171], v[192:195], v[42:45]
	v_mfma_f32_16x16x32_bf16 v[38:41], v[156:159], v[188:191], v[38:41]
	v_mfma_f32_16x16x32_bf16 v[38:41], v[160:163], v[192:195], v[38:41]
	v_mfma_f32_16x16x32_bf16 v[46:49], v[148:151], v[188:191], v[46:49]
	v_mfma_f32_16x16x32_bf16 v[46:49], v[152:155], v[192:195], v[46:49]
	v_mfma_f32_16x16x32_bf16 v[30:33], v[148:151], v[196:199], v[30:33]
	v_mfma_f32_16x16x32_bf16 v[30:33], v[152:155], v[200:203], v[30:33]
	v_mfma_f32_16x16x32_bf16 v[22:25], v[156:159], v[196:199], v[22:25]
	v_mfma_f32_16x16x32_bf16 v[22:25], v[160:163], v[200:203], v[22:25]
	v_mfma_f32_16x16x32_bf16 v[26:29], v[164:167], v[196:199], v[26:29]
	v_mfma_f32_16x16x32_bf16 v[26:29], v[168:171], v[200:203], v[26:29]
	v_mfma_f32_16x16x32_bf16 v[18:21], v[172:175], v[196:199], v[18:21]
	v_mfma_f32_16x16x32_bf16 v[18:21], v[176:179], v[200:203], v[18:21]
	v_mfma_f32_16x16x32_bf16 v[2:5], v[172:175], v[204:207], v[2:5]
	v_mfma_f32_16x16x32_bf16 v[2:5], v[176:179], v[208:211], v[2:5]
	v_mfma_f32_16x16x32_bf16 v[10:13], v[164:167], v[204:207], v[10:13]
	v_mfma_f32_16x16x32_bf16 v[10:13], v[168:171], v[208:211], v[10:13]
	v_mfma_f32_16x16x32_bf16 v[6:9], v[156:159], v[204:207], v[6:9]
	v_mfma_f32_16x16x32_bf16 v[6:9], v[160:163], v[208:211], v[6:9]
	v_mfma_f32_16x16x32_bf16 v[14:17], v[148:151], v[204:207], v[14:17]
	v_mfma_f32_16x16x32_bf16 v[14:17], v[152:155], v[208:211], v[14:17]
	s_setprio 0
	s_barrier
	ds_read_b128 v[148:151], v142
	ds_read_b128 v[152:155], v142 offset:1024
	ds_read_b128 v[156:159], v142 offset:2048
	ds_read_b128 v[160:163], v142 offset:3072
	ds_read_b128 v[164:167], v143
	ds_read_b128 v[168:171], v143 offset:1024
	ds_read_b128 v[172:175], v143 offset:2048
	ds_read_b128 v[176:179], v143 offset:3072
	s_mov_b32 m0, s47
	s_add_i32 s77, s74, 0x100000
	ds_read_b128 v[180:183], v141 offset:32768
	ds_read_b128 v[184:187], v141 offset:33792
	ds_read_b128 v[188:191], v141 offset:34816
	ds_read_b128 v[192:195], v141 offset:35840
	ds_read_b128 v[196:199], v141 offset:36864
	ds_read_b128 v[200:203], v141 offset:37888
	ds_read_b128 v[204:207], v141 offset:38912
	ds_read_b128 v[208:211], v141 offset:39936
	buffer_load_dwordx4 v137, s[12:15], s77 offen lds
	s_add_i32 s77, s74, 0x180000
	s_mov_b32 m0, s48
	s_nop 0
	buffer_load_dwordx4 v137, s[12:15], s77 offen lds
	s_waitcnt vmcnt(8)
	s_waitcnt lgkmcnt(0)
	s_setprio 1
	v_mfma_f32_16x16x32_bf16 v[118:121], v[148:151], v[180:183], v[118:121]
	s_barrier
	v_mfma_f32_16x16x32_bf16 v[118:121], v[152:155], v[184:187], v[118:121]
	v_mfma_f32_16x16x32_bf16 v[114:117], v[156:159], v[180:183], v[114:117]
	v_mfma_f32_16x16x32_bf16 v[114:117], v[160:163], v[184:187], v[114:117]
	v_mfma_f32_16x16x32_bf16 v[126:129], v[164:167], v[180:183], v[126:129]
	v_mfma_f32_16x16x32_bf16 v[126:129], v[168:171], v[184:187], v[126:129]
	v_mfma_f32_16x16x32_bf16 v[122:125], v[172:175], v[180:183], v[122:125]
	v_mfma_f32_16x16x32_bf16 v[122:125], v[176:179], v[184:187], v[122:125]
	v_mfma_f32_16x16x32_bf16 v[98:101], v[172:175], v[188:191], v[98:101]
	v_mfma_f32_16x16x32_bf16 v[98:101], v[176:179], v[192:195], v[98:101]
	v_mfma_f32_16x16x32_bf16 v[106:109], v[164:167], v[188:191], v[106:109]
	v_mfma_f32_16x16x32_bf16 v[106:109], v[168:171], v[192:195], v[106:109]
	v_mfma_f32_16x16x32_bf16 v[102:105], v[156:159], v[188:191], v[102:105]
	v_mfma_f32_16x16x32_bf16 v[102:105], v[160:163], v[192:195], v[102:105]
	v_mfma_f32_16x16x32_bf16 v[110:113], v[148:151], v[188:191], v[110:113]
	v_mfma_f32_16x16x32_bf16 v[110:113], v[152:155], v[192:195], v[110:113]
	v_mfma_f32_16x16x32_bf16 v[94:97], v[148:151], v[196:199], v[94:97]
	v_mfma_f32_16x16x32_bf16 v[94:97], v[152:155], v[200:203], v[94:97]
	v_mfma_f32_16x16x32_bf16 v[86:89], v[156:159], v[196:199], v[86:89]
	v_mfma_f32_16x16x32_bf16 v[86:89], v[160:163], v[200:203], v[86:89]
	v_mfma_f32_16x16x32_bf16 v[90:93], v[164:167], v[196:199], v[90:93]
	v_mfma_f32_16x16x32_bf16 v[90:93], v[168:171], v[200:203], v[90:93]
	v_mfma_f32_16x16x32_bf16 v[82:85], v[172:175], v[196:199], v[82:85]
	v_mfma_f32_16x16x32_bf16 v[82:85], v[176:179], v[200:203], v[82:85]
	v_mfma_f32_16x16x32_bf16 v[70:73], v[172:175], v[204:207], v[70:73]
	v_mfma_f32_16x16x32_bf16 v[70:73], v[176:179], v[208:211], v[70:73]
	v_mfma_f32_16x16x32_bf16 v[74:77], v[164:167], v[204:207], v[74:77]
	v_mfma_f32_16x16x32_bf16 v[74:77], v[168:171], v[208:211], v[74:77]
	v_mfma_f32_16x16x32_bf16 v[66:69], v[156:159], v[204:207], v[66:69]
	v_mfma_f32_16x16x32_bf16 v[66:69], v[160:163], v[208:211], v[66:69]
	v_mfma_f32_16x16x32_bf16 v[78:81], v[148:151], v[204:207], v[78:81]
	v_mfma_f32_16x16x32_bf16 v[78:81], v[152:155], v[208:211], v[78:81]
	s_setprio 0
	s_barrier
	s_mov_b32 m0, s50
	s_or_b32 s77, s76, 0x80
	ds_read_b128 v[180:183], v141 offset:49152
	ds_read_b128 v[184:187], v141 offset:50176
	ds_read_b128 v[188:191], v141 offset:51200
	ds_read_b128 v[192:195], v141 offset:52224
	ds_read_b128 v[196:199], v141 offset:53248
	ds_read_b128 v[200:203], v141 offset:54272
	ds_read_b128 v[204:207], v141 offset:55296
	ds_read_b128 v[208:211], v141 offset:56320
	buffer_load_dwordx4 v138, s[16:19], s77 offen lds
	s_add_i32 s77, s76, 0x80080
	s_mov_b32 m0, s51
	s_add_i32 s74, s74, 0x80080
	buffer_load_dwordx4 v138, s[16:19], s77 offen lds
	s_add_i32 s77, s76, 0x100080
	s_mov_b32 m0, s54
	s_add_i32 s76, s76, 0x180080
	buffer_load_dwordx4 v138, s[16:19], s77 offen lds
	s_mov_b32 m0, s55
	s_nop 0
	buffer_load_dwordx4 v138, s[16:19], s76 offen lds
	s_mov_b32 m0, s52
	s_nop 0
	buffer_load_dwordx4 v137, s[12:15], s75 offen lds
	s_mov_b32 m0, s53
	s_nop 0
	buffer_load_dwordx4 v137, s[12:15], s74 offen lds
	s_waitcnt vmcnt(8)
	s_waitcnt lgkmcnt(0)
	s_setprio 1
	v_mfma_f32_16x16x32_bf16 v[62:65], v[148:151], v[180:183], v[62:65]
	s_barrier
	v_mfma_f32_16x16x32_bf16 v[62:65], v[152:155], v[184:187], v[62:65]
	v_mfma_f32_16x16x32_bf16 v[54:57], v[156:159], v[180:183], v[54:57]
	v_mfma_f32_16x16x32_bf16 v[54:57], v[160:163], v[184:187], v[54:57]
	v_mfma_f32_16x16x32_bf16 v[58:61], v[164:167], v[180:183], v[58:61]
	v_mfma_f32_16x16x32_bf16 v[58:61], v[168:171], v[184:187], v[58:61]
	v_mfma_f32_16x16x32_bf16 v[50:53], v[172:175], v[180:183], v[50:53]
	v_mfma_f32_16x16x32_bf16 v[50:53], v[176:179], v[184:187], v[50:53]
	v_mfma_f32_16x16x32_bf16 v[34:37], v[172:175], v[188:191], v[34:37]
	v_mfma_f32_16x16x32_bf16 v[34:37], v[176:179], v[192:195], v[34:37]
	v_mfma_f32_16x16x32_bf16 v[42:45], v[164:167], v[188:191], v[42:45]
	v_mfma_f32_16x16x32_bf16 v[42:45], v[168:171], v[192:195], v[42:45]
	v_mfma_f32_16x16x32_bf16 v[38:41], v[156:159], v[188:191], v[38:41]
	v_mfma_f32_16x16x32_bf16 v[38:41], v[160:163], v[192:195], v[38:41]
	v_mfma_f32_16x16x32_bf16 v[46:49], v[148:151], v[188:191], v[46:49]
	v_mfma_f32_16x16x32_bf16 v[46:49], v[152:155], v[192:195], v[46:49]
	v_mfma_f32_16x16x32_bf16 v[30:33], v[148:151], v[196:199], v[30:33]
	v_mfma_f32_16x16x32_bf16 v[30:33], v[152:155], v[200:203], v[30:33]
	v_mfma_f32_16x16x32_bf16 v[22:25], v[156:159], v[196:199], v[22:25]
	v_mfma_f32_16x16x32_bf16 v[22:25], v[160:163], v[200:203], v[22:25]
	v_mfma_f32_16x16x32_bf16 v[26:29], v[164:167], v[196:199], v[26:29]
	v_mfma_f32_16x16x32_bf16 v[26:29], v[168:171], v[200:203], v[26:29]
	v_mfma_f32_16x16x32_bf16 v[18:21], v[172:175], v[196:199], v[18:21]
	v_mfma_f32_16x16x32_bf16 v[18:21], v[176:179], v[200:203], v[18:21]
	v_mfma_f32_16x16x32_bf16 v[2:5], v[172:175], v[204:207], v[2:5]
	v_mfma_f32_16x16x32_bf16 v[2:5], v[176:179], v[208:211], v[2:5]
	v_mfma_f32_16x16x32_bf16 v[10:13], v[164:167], v[204:207], v[10:13]
	v_mfma_f32_16x16x32_bf16 v[10:13], v[168:171], v[208:211], v[10:13]
	v_mfma_f32_16x16x32_bf16 v[6:9], v[156:159], v[204:207], v[6:9]
	v_mfma_f32_16x16x32_bf16 v[6:9], v[160:163], v[208:211], v[6:9]
	v_mfma_f32_16x16x32_bf16 v[14:17], v[148:151], v[204:207], v[14:17]
	v_mfma_f32_16x16x32_bf16 v[14:17], v[152:155], v[208:211], v[14:17]
	s_setprio 0
	s_barrier
	s_add_i32 s73, s73, 2
	s_addk_i32 s71, 0x100
	s_addk_i32 s72, 0x100
	s_cmp_ge_i32 s73, s3
	s_cbranch_scc0 .LBB0_642
	s_and_b64 vcc, exec, s[42:43]
	s_cbranch_vccz .LBB0_645

.LBB0_799:
	ds_read_b128 v[134:137], v210
	ds_read_b128 v[138:141], v210 offset:1024
	ds_read_b128 v[142:145], v210 offset:2048
	ds_read_b128 v[148:151], v210 offset:3072
	ds_read_b128 v[152:155], v211
	ds_read_b128 v[156:159], v211 offset:1024
	ds_read_b128 v[160:163], v211 offset:2048
	ds_read_b128 v[164:167], v211 offset:3072
	s_add_i32 s18, s77, 0xffbf8080
	s_cmp_eq_u32 s62, s79
	s_cselect_b32 s80, s6, s18
	s_cselect_b32 s82, s7, s78
	s_or_b32 s81, s80, 0x80
	s_add_i32 s18, s77, 0xffea8000
	s_mov_b32 m0, s63
	ds_read_b128 v[168:171], v212
	ds_read_b128 v[172:175], v212 offset:1024
	ds_read_b128 v[176:179], v212 offset:2048
	ds_read_b128 v[180:183], v212 offset:3072
	ds_read_b128 v[184:187], v212 offset:4096
	ds_read_b128 v[188:191], v212 offset:5120
	ds_read_b128 v[192:195], v212 offset:6144
	ds_read_b128 v[196:199], v212 offset:7168
	buffer_load_dwordx4 v208, s[12:15], s18 offen lds
	s_mov_b32 m0, s66
	s_nop 0
	buffer_load_dwordx4 v208, s[12:15], s77 offen lds
	s_waitcnt vmcnt(8)
	s_waitcnt lgkmcnt(0)
	s_setprio 1
	v_mfma_f32_16x16x32_bf16 v[126:129], v[134:137], v[168:171], v[126:129]
	s_barrier
	v_mfma_f32_16x16x32_bf16 v[126:129], v[138:141], v[172:175], v[126:129]
	v_mfma_f32_16x16x32_bf16 v[122:125], v[142:145], v[168:171], v[122:125]
	v_mfma_f32_16x16x32_bf16 v[122:125], v[148:151], v[172:175], v[122:125]
	v_mfma_f32_16x16x32_bf16 v[110:113], v[152:155], v[168:171], v[110:113]
	v_mfma_f32_16x16x32_bf16 v[110:113], v[156:159], v[172:175], v[110:113]
	v_mfma_f32_16x16x32_bf16 v[102:105], v[160:163], v[168:171], v[102:105]
	v_mfma_f32_16x16x32_bf16 v[102:105], v[164:167], v[172:175], v[102:105]
	v_mfma_f32_16x16x32_bf16 v[86:89], v[160:163], v[176:179], v[86:89]
	v_mfma_f32_16x16x32_bf16 v[86:89], v[164:167], v[180:183], v[86:89]
	v_mfma_f32_16x16x32_bf16 v[94:97], v[152:155], v[176:179], v[94:97]
	v_mfma_f32_16x16x32_bf16 v[94:97], v[156:159], v[180:183], v[94:97]
	v_mfma_f32_16x16x32_bf16 v[114:117], v[142:145], v[176:179], v[114:117]
	v_mfma_f32_16x16x32_bf16 v[114:117], v[148:151], v[180:183], v[114:117]
	v_mfma_f32_16x16x32_bf16 v[118:121], v[134:137], v[176:179], v[118:121]
	v_mfma_f32_16x16x32_bf16 v[118:121], v[138:141], v[180:183], v[118:121]
	v_mfma_f32_16x16x32_bf16 v[106:109], v[134:137], v[184:187], v[106:109]
	v_mfma_f32_16x16x32_bf16 v[106:109], v[138:141], v[188:191], v[106:109]
	v_mfma_f32_16x16x32_bf16 v[98:101], v[142:145], v[184:187], v[98:101]
	v_mfma_f32_16x16x32_bf16 v[98:101], v[148:151], v[188:191], v[98:101]
	v_mfma_f32_16x16x32_bf16 v[78:81], v[152:155], v[184:187], v[78:81]
	v_mfma_f32_16x16x32_bf16 v[78:81], v[156:159], v[188:191], v[78:81]
	v_mfma_f32_16x16x32_bf16 v[74:77], v[160:163], v[184:187], v[74:77]
	v_mfma_f32_16x16x32_bf16 v[74:77], v[164:167], v[188:191], v[74:77]
	v_mfma_f32_16x16x32_bf16 v[66:69], v[160:163], v[192:195], v[66:69]
	v_mfma_f32_16x16x32_bf16 v[66:69], v[164:167], v[196:199], v[66:69]
	v_mfma_f32_16x16x32_bf16 v[70:73], v[152:155], v[192:195], v[70:73]
	v_mfma_f32_16x16x32_bf16 v[70:73], v[156:159], v[196:199], v[70:73]
	v_mfma_f32_16x16x32_bf16 v[82:85], v[142:145], v[192:195], v[82:85]
	v_mfma_f32_16x16x32_bf16 v[82:85], v[148:151], v[196:199], v[82:85]
	v_mfma_f32_16x16x32_bf16 v[90:93], v[134:137], v[192:195], v[90:93]
	v_mfma_f32_16x16x32_bf16 v[90:93], v[138:141], v[196:199], v[90:93]
	s_setprio 0
	s_barrier
	s_mov_b32 m0, s25
	s_mov_b32 s18, s14
	s_mov_b32 s19, s15
	ds_read_b128 v[168:171], v212 offset:16384
	ds_read_b128 v[172:175], v212 offset:17408
	ds_read_b128 v[176:179], v212 offset:18432
	ds_read_b128 v[180:183], v212 offset:19456
	ds_read_b128 v[184:187], v212 offset:20480
	ds_read_b128 v[188:191], v212 offset:21504
	ds_read_b128 v[192:195], v212 offset:22528
	ds_read_b128 v[196:199], v212 offset:23552
	buffer_load_dwordx4 v209, s[16:19], s82 offen lds
	s_add_i32 s83, s82, 0x158000
	s_mov_b32 m0, s27
	s_nop 0
	buffer_load_dwordx4 v209, s[16:19], s83 offen lds
	s_add_i32 s83, s82, 0x2b0000
	s_mov_b32 m0, s30
	s_nop 0
	buffer_load_dwordx4 v209, s[16:19], s83 offen lds
	s_add_i32 s83, s82, 0x408000
	s_mov_b32 m0, s31
	s_nop 0
	buffer_load_dwordx4 v209, s[16:19], s83 offen lds
	s_mov_b32 m0, s21
	s_add_i32 s83, s80, 0x158000
	buffer_load_dwordx4 v208, s[12:15], s80 offen lds
	s_mov_b32 m0, s48
	s_nop 0
	buffer_load_dwordx4 v208, s[12:15], s83 offen lds
	s_waitcnt vmcnt(8)
	s_waitcnt lgkmcnt(0)
	s_setprio 1
	v_mfma_f32_16x16x32_bf16 v[62:65], v[134:137], v[168:171], v[62:65]
	s_barrier
	v_mfma_f32_16x16x32_bf16 v[62:65], v[138:141], v[172:175], v[62:65]
	v_mfma_f32_16x16x32_bf16 v[58:61], v[142:145], v[168:171], v[58:61]
	v_mfma_f32_16x16x32_bf16 v[58:61], v[148:151], v[172:175], v[58:61]
	v_mfma_f32_16x16x32_bf16 v[46:49], v[152:155], v[168:171], v[46:49]
	v_mfma_f32_16x16x32_bf16 v[46:49], v[156:159], v[172:175], v[46:49]
	v_mfma_f32_16x16x32_bf16 v[38:41], v[160:163], v[168:171], v[38:41]
	v_mfma_f32_16x16x32_bf16 v[38:41], v[164:167], v[172:175], v[38:41]
	v_mfma_f32_16x16x32_bf16 v[22:25], v[160:163], v[176:179], v[22:25]
	v_mfma_f32_16x16x32_bf16 v[22:25], v[164:167], v[180:183], v[22:25]
	v_mfma_f32_16x16x32_bf16 v[30:33], v[152:155], v[176:179], v[30:33]
	v_mfma_f32_16x16x32_bf16 v[30:33], v[156:159], v[180:183], v[30:33]
	v_mfma_f32_16x16x32_bf16 v[50:53], v[142:145], v[176:179], v[50:53]
	v_mfma_f32_16x16x32_bf16 v[50:53], v[148:151], v[180:183], v[50:53]
	v_mfma_f32_16x16x32_bf16 v[54:57], v[134:137], v[176:179], v[54:57]
	v_mfma_f32_16x16x32_bf16 v[54:57], v[138:141], v[180:183], v[54:57]
	v_mfma_f32_16x16x32_bf16 v[42:45], v[134:137], v[184:187], v[42:45]
	v_mfma_f32_16x16x32_bf16 v[42:45], v[138:141], v[188:191], v[42:45]
	v_mfma_f32_16x16x32_bf16 v[34:37], v[142:145], v[184:187], v[34:37]
	v_mfma_f32_16x16x32_bf16 v[34:37], v[148:151], v[188:191], v[34:37]
	v_mfma_f32_16x16x32_bf16 v[14:17], v[152:155], v[184:187], v[14:17]
	v_mfma_f32_16x16x32_bf16 v[14:17], v[156:159], v[188:191], v[14:17]
	v_mfma_f32_16x16x32_bf16 v[10:13], v[160:163], v[184:187], v[10:13]
	v_mfma_f32_16x16x32_bf16 v[10:13], v[164:167], v[188:191], v[10:13]
	v_mfma_f32_16x16x32_bf16 v[2:5], v[160:163], v[192:195], v[2:5]
	v_mfma_f32_16x16x32_bf16 v[2:5], v[164:167], v[196:199], v[2:5]
	v_mfma_f32_16x16x32_bf16 v[6:9], v[152:155], v[192:195], v[6:9]
	v_mfma_f32_16x16x32_bf16 v[6:9], v[156:159], v[196:199], v[6:9]
	v_mfma_f32_16x16x32_bf16 v[18:21], v[142:145], v[192:195], v[18:21]
	v_mfma_f32_16x16x32_bf16 v[18:21], v[148:151], v[196:199], v[18:21]
	v_mfma_f32_16x16x32_bf16 v[26:29], v[134:137], v[192:195], v[26:29]
	v_mfma_f32_16x16x32_bf16 v[26:29], v[138:141], v[196:199], v[26:29]
	s_setprio 0
	s_barrier
	ds_read_b128 v[134:137], v213
	ds_read_b128 v[138:141], v213 offset:1024
	ds_read_b128 v[142:145], v213 offset:2048
	ds_read_b128 v[148:151], v213 offset:3072
	ds_read_b128 v[152:155], v214
	ds_read_b128 v[156:159], v214 offset:1024
	ds_read_b128 v[160:163], v214 offset:2048
	ds_read_b128 v[164:167], v214 offset:3072
	s_mov_b32 m0, s49
	s_add_i32 s83, s80, 0x2b0000
	ds_read_b128 v[168:171], v212 offset:32768
	ds_read_b128 v[172:175], v212 offset:33792
	ds_read_b128 v[176:179], v212 offset:34816
	ds_read_b128 v[180:183], v212 offset:35840
	ds_read_b128 v[184:187], v212 offset:36864
	ds_read_b128 v[188:191], v212 offset:37888
	ds_read_b128 v[192:195], v212 offset:38912
	ds_read_b128 v[196:199], v212 offset:39936
	buffer_load_dwordx4 v208, s[12:15], s83 offen lds
	s_add_i32 s83, s80, 0x408000
	s_mov_b32 m0, s50
	s_nop 0
	buffer_load_dwordx4 v208, s[12:15], s83 offen lds
	s_waitcnt vmcnt(8)
	s_waitcnt lgkmcnt(0)
	s_setprio 1
	v_mfma_f32_16x16x32_bf16 v[126:129], v[134:137], v[168:171], v[126:129]
	s_barrier
	v_mfma_f32_16x16x32_bf16 v[126:129], v[138:141], v[172:175], v[126:129]
	v_mfma_f32_16x16x32_bf16 v[122:125], v[142:145], v[168:171], v[122:125]
	v_mfma_f32_16x16x32_bf16 v[122:125], v[148:151], v[172:175], v[122:125]
	v_mfma_f32_16x16x32_bf16 v[110:113], v[152:155], v[168:171], v[110:113]
	v_mfma_f32_16x16x32_bf16 v[110:113], v[156:159], v[172:175], v[110:113]
	v_mfma_f32_16x16x32_bf16 v[102:105], v[160:163], v[168:171], v[102:105]
	v_mfma_f32_16x16x32_bf16 v[102:105], v[164:167], v[172:175], v[102:105]
	v_mfma_f32_16x16x32_bf16 v[86:89], v[160:163], v[176:179], v[86:89]
	v_mfma_f32_16x16x32_bf16 v[86:89], v[164:167], v[180:183], v[86:89]
	v_mfma_f32_16x16x32_bf16 v[94:97], v[152:155], v[176:179], v[94:97]
	v_mfma_f32_16x16x32_bf16 v[94:97], v[156:159], v[180:183], v[94:97]
	v_mfma_f32_16x16x32_bf16 v[114:117], v[142:145], v[176:179], v[114:117]
	v_mfma_f32_16x16x32_bf16 v[114:117], v[148:151], v[180:183], v[114:117]
	v_mfma_f32_16x16x32_bf16 v[118:121], v[134:137], v[176:179], v[118:121]
	v_mfma_f32_16x16x32_bf16 v[118:121], v[138:141], v[180:183], v[118:121]
	v_mfma_f32_16x16x32_bf16 v[106:109], v[134:137], v[184:187], v[106:109]
	v_mfma_f32_16x16x32_bf16 v[106:109], v[138:141], v[188:191], v[106:109]
	v_mfma_f32_16x16x32_bf16 v[98:101], v[142:145], v[184:187], v[98:101]
	v_mfma_f32_16x16x32_bf16 v[98:101], v[148:151], v[188:191], v[98:101]
	v_mfma_f32_16x16x32_bf16 v[78:81], v[152:155], v[184:187], v[78:81]
	v_mfma_f32_16x16x32_bf16 v[78:81], v[156:159], v[188:191], v[78:81]
	v_mfma_f32_16x16x32_bf16 v[74:77], v[160:163], v[184:187], v[74:77]
	v_mfma_f32_16x16x32_bf16 v[74:77], v[164:167], v[188:191], v[74:77]
	v_mfma_f32_16x16x32_bf16 v[66:69], v[160:163], v[192:195], v[66:69]
	v_mfma_f32_16x16x32_bf16 v[66:69], v[164:167], v[196:199], v[66:69]
	v_mfma_f32_16x16x32_bf16 v[70:73], v[152:155], v[192:195], v[70:73]
	v_mfma_f32_16x16x32_bf16 v[70:73], v[156:159], v[196:199], v[70:73]
	v_mfma_f32_16x16x32_bf16 v[82:85], v[142:145], v[192:195], v[82:85]
	v_mfma_f32_16x16x32_bf16 v[82:85], v[148:151], v[196:199], v[82:85]
	v_mfma_f32_16x16x32_bf16 v[90:93], v[134:137], v[192:195], v[90:93]
	v_mfma_f32_16x16x32_bf16 v[90:93], v[138:141], v[196:199], v[90:93]
	s_setprio 0
	s_barrier
	s_mov_b32 m0, s54
	s_or_b32 s83, s82, 0x80
	ds_read_b128 v[168:171], v212 offset:49152
	ds_read_b128 v[172:175], v212 offset:50176
	ds_read_b128 v[176:179], v212 offset:51200
	ds_read_b128 v[180:183], v212 offset:52224
	ds_read_b128 v[184:187], v212 offset:53248
	ds_read_b128 v[188:191], v212 offset:54272
	ds_read_b128 v[192:195], v212 offset:55296
	ds_read_b128 v[196:199], v212 offset:56320
	buffer_load_dwordx4 v209, s[16:19], s83 offen lds
	s_add_i32 s83, s82, 0x158080
	s_mov_b32 m0, s55
	s_add_i32 s80, s80, 0x158080
	buffer_load_dwordx4 v209, s[16:19], s83 offen lds
	s_add_i32 s83, s82, 0x2b0080
	s_mov_b32 m0, s58
	s_add_i32 s82, s82, 0x408080
	buffer_load_dwordx4 v209, s[16:19], s83 offen lds
	s_mov_b32 m0, s59
	s_nop 0
	buffer_load_dwordx4 v209, s[16:19], s82 offen lds
	s_mov_b32 m0, s56
	s_nop 0
	buffer_load_dwordx4 v208, s[12:15], s81 offen lds
	s_mov_b32 m0, s57
	s_nop 0
	buffer_load_dwordx4 v208, s[12:15], s80 offen lds
	s_waitcnt vmcnt(8)
	s_waitcnt lgkmcnt(0)
	s_setprio 1
	v_mfma_f32_16x16x32_bf16 v[62:65], v[134:137], v[168:171], v[62:65]
	s_barrier
	v_mfma_f32_16x16x32_bf16 v[62:65], v[138:141], v[172:175], v[62:65]
	v_mfma_f32_16x16x32_bf16 v[58:61], v[142:145], v[168:171], v[58:61]
	v_mfma_f32_16x16x32_bf16 v[58:61], v[148:151], v[172:175], v[58:61]
	v_mfma_f32_16x16x32_bf16 v[46:49], v[152:155], v[168:171], v[46:49]
	v_mfma_f32_16x16x32_bf16 v[46:49], v[156:159], v[172:175], v[46:49]
	v_mfma_f32_16x16x32_bf16 v[38:41], v[160:163], v[168:171], v[38:41]
	v_mfma_f32_16x16x32_bf16 v[38:41], v[164:167], v[172:175], v[38:41]
	v_mfma_f32_16x16x32_bf16 v[22:25], v[160:163], v[176:179], v[22:25]
	v_mfma_f32_16x16x32_bf16 v[22:25], v[164:167], v[180:183], v[22:25]
	v_mfma_f32_16x16x32_bf16 v[30:33], v[152:155], v[176:179], v[30:33]
	v_mfma_f32_16x16x32_bf16 v[30:33], v[156:159], v[180:183], v[30:33]
	v_mfma_f32_16x16x32_bf16 v[50:53], v[142:145], v[176:179], v[50:53]
	v_mfma_f32_16x16x32_bf16 v[50:53], v[148:151], v[180:183], v[50:53]
	v_mfma_f32_16x16x32_bf16 v[54:57], v[134:137], v[176:179], v[54:57]
	v_mfma_f32_16x16x32_bf16 v[54:57], v[138:141], v[180:183], v[54:57]
	v_mfma_f32_16x16x32_bf16 v[42:45], v[134:137], v[184:187], v[42:45]
	v_mfma_f32_16x16x32_bf16 v[42:45], v[138:141], v[188:191], v[42:45]
	v_mfma_f32_16x16x32_bf16 v[34:37], v[142:145], v[184:187], v[34:37]
	v_mfma_f32_16x16x32_bf16 v[34:37], v[148:151], v[188:191], v[34:37]
	v_mfma_f32_16x16x32_bf16 v[14:17], v[152:155], v[184:187], v[14:17]
	v_mfma_f32_16x16x32_bf16 v[14:17], v[156:159], v[188:191], v[14:17]
	v_mfma_f32_16x16x32_bf16 v[10:13], v[160:163], v[184:187], v[10:13]
	v_mfma_f32_16x16x32_bf16 v[10:13], v[164:167], v[188:191], v[10:13]
	v_mfma_f32_16x16x32_bf16 v[2:5], v[160:163], v[192:195], v[2:5]
	v_mfma_f32_16x16x32_bf16 v[2:5], v[164:167], v[196:199], v[2:5]
	v_mfma_f32_16x16x32_bf16 v[6:9], v[152:155], v[192:195], v[6:9]
	v_mfma_f32_16x16x32_bf16 v[6:9], v[156:159], v[196:199], v[6:9]
	v_mfma_f32_16x16x32_bf16 v[18:21], v[142:145], v[192:195], v[18:21]
	v_mfma_f32_16x16x32_bf16 v[18:21], v[148:151], v[196:199], v[18:21]
	v_mfma_f32_16x16x32_bf16 v[26:29], v[134:137], v[192:195], v[26:29]
	v_mfma_f32_16x16x32_bf16 v[26:29], v[138:141], v[196:199], v[26:29]
	s_setprio 0
	s_barrier
	s_add_i32 s79, s79, 2
	s_addk_i32 s77, 0x100
	s_addk_i32 s78, 0x100
	s_cmp_ge_i32 s79, s3
	s_cbranch_scc0 .LBB0_799
	v_pk_mul_f32 v[184:185], v[128:129], 0.5 op_sel_hi:[1,0]
	v_pk_mul_f32 v[186:187], v[126:127], 0.5 op_sel_hi:[1,0]
	v_pk_mul_f32 v[188:189], v[124:125], 0.5 op_sel_hi:[1,0]
	v_pk_mul_f32 v[190:191], v[122:123], 0.5 op_sel_hi:[1,0]
	v_pk_mul_f32 v[198:199], v[112:113], 0.5 op_sel_hi:[1,0]
	v_pk_mul_f32 v[196:197], v[110:111], 0.5 op_sel_hi:[1,0]
	v_pk_mul_f32 v[194:195], v[104:105], 0.5 op_sel_hi:[1,0]
	v_pk_mul_f32 v[192:193], v[102:103], 0.5 op_sel_hi:[1,0]
	v_pk_mul_f32 v[182:183], v[120:121], 0.5 op_sel_hi:[1,0]
	v_pk_mul_f32 v[180:181], v[118:119], 0.5 op_sel_hi:[1,0]
	v_pk_mul_f32 v[178:179], v[116:117], 0.5 op_sel_hi:[1,0]
	v_pk_mul_f32 v[176:177], v[114:115], 0.5 op_sel_hi:[1,0]
	v_pk_mul_f32 v[172:173], v[96:97], 0.5 op_sel_hi:[1,0]
	v_pk_mul_f32 v[170:171], v[94:95], 0.5 op_sel_hi:[1,0]
	v_pk_mul_f32 v[168:169], v[88:89], 0.5 op_sel_hi:[1,0]
	v_pk_mul_f32 v[166:167], v[86:87], 0.5 op_sel_hi:[1,0]
	v_pk_mul_f32 v[164:165], v[108:109], 0.5 op_sel_hi:[1,0]
	v_pk_mul_f32 v[162:163], v[106:107], 0.5 op_sel_hi:[1,0]
	v_pk_mul_f32 v[160:161], v[100:101], 0.5 op_sel_hi:[1,0]
	v_pk_mul_f32 v[158:159], v[98:99], 0.5 op_sel_hi:[1,0]
	v_pk_mul_f32 v[156:157], v[80:81], 0.5 op_sel_hi:[1,0]
	v_pk_mul_f32 v[154:155], v[78:79], 0.5 op_sel_hi:[1,0]
	v_pk_mul_f32 v[152:153], v[76:77], 0.5 op_sel_hi:[1,0]
	v_pk_mul_f32 v[150:151], v[74:75], 0.5 op_sel_hi:[1,0]
	v_pk_mul_f32 v[144:145], v[92:93], 0.5 op_sel_hi:[1,0]
	v_pk_mul_f32 v[142:143], v[90:91], 0.5 op_sel_hi:[1,0]
	v_pk_mul_f32 v[140:141], v[84:85], 0.5 op_sel_hi:[1,0]
	v_pk_mul_f32 v[138:139], v[82:83], 0.5 op_sel_hi:[1,0]
	v_pk_mul_f32 v[136:137], v[72:73], 0.5 op_sel_hi:[1,0]
	v_pk_mul_f32 v[134:135], v[70:71], 0.5 op_sel_hi:[1,0]
	v_pk_mul_f32 v[128:129], v[68:69], 0.5 op_sel_hi:[1,0]
	v_pk_mul_f32 v[126:127], v[66:67], 0.5 op_sel_hi:[1,0]
	v_pk_mul_f32 v[122:123], v[64:65], 0.5 op_sel_hi:[1,0]
	v_pk_mul_f32 v[120:121], v[62:63], 0.5 op_sel_hi:[1,0]
	v_pk_mul_f32 v[118:119], v[60:61], 0.5 op_sel_hi:[1,0]
	v_pk_mul_f32 v[116:117], v[58:59], 0.5 op_sel_hi:[1,0]
	v_pk_mul_f32 v[112:113], v[48:49], 0.5 op_sel_hi:[1,0]
	v_pk_mul_f32 v[110:111], v[46:47], 0.5 op_sel_hi:[1,0]
	v_pk_mul_f32 v[108:109], v[40:41], 0.5 op_sel_hi:[1,0]
	v_pk_mul_f32 v[106:107], v[38:39], 0.5 op_sel_hi:[1,0]
	v_pk_mul_f32 v[104:105], v[56:57], 0.5 op_sel_hi:[1,0]
	v_pk_mul_f32 v[102:103], v[54:55], 0.5 op_sel_hi:[1,0]
	v_pk_mul_f32 v[100:101], v[52:53], 0.5 op_sel_hi:[1,0]
	v_pk_mul_f32 v[98:99], v[50:51], 0.5 op_sel_hi:[1,0]
	v_pk_mul_f32 v[96:97], v[32:33], 0.5 op_sel_hi:[1,0]
	v_pk_mul_f32 v[94:95], v[30:31], 0.5 op_sel_hi:[1,0]
	v_pk_mul_f32 v[92:93], v[24:25], 0.5 op_sel_hi:[1,0]
	v_pk_mul_f32 v[90:91], v[22:23], 0.5 op_sel_hi:[1,0]
	v_pk_mul_f32 v[88:89], v[44:45], 0.5 op_sel_hi:[1,0]
	v_pk_mul_f32 v[86:87], v[42:43], 0.5 op_sel_hi:[1,0]
	v_pk_mul_f32 v[84:85], v[36:37], 0.5 op_sel_hi:[1,0]
	v_pk_mul_f32 v[82:83], v[34:35], 0.5 op_sel_hi:[1,0]
	v_pk_mul_f32 v[80:81], v[16:17], 0.5 op_sel_hi:[1,0]
	v_pk_mul_f32 v[78:79], v[14:15], 0.5 op_sel_hi:[1,0]
	v_pk_mul_f32 v[76:77], v[12:13], 0.5 op_sel_hi:[1,0]
	v_pk_mul_f32 v[74:75], v[10:11], 0.5 op_sel_hi:[1,0]
	v_pk_mul_f32 v[72:73], v[28:29], 0.5 op_sel_hi:[1,0]
	v_pk_mul_f32 v[70:71], v[26:27], 0.5 op_sel_hi:[1,0]
	v_pk_mul_f32 v[68:69], v[20:21], 0.5 op_sel_hi:[1,0]
	v_pk_mul_f32 v[66:67], v[18:19], 0.5 op_sel_hi:[1,0]
	v_pk_mul_f32 v[64:65], v[8:9], 0.5 op_sel_hi:[1,0]
	v_pk_mul_f32 v[62:63], v[6:7], 0.5 op_sel_hi:[1,0]
	v_pk_mul_f32 v[60:61], v[4:5], 0.5 op_sel_hi:[1,0]
	v_pk_mul_f32 v[58:59], v[2:3], 0.5 op_sel_hi:[1,0]
	s_and_b64 vcc, exec, s[38:39]
	s_cbranch_vccz .LBB0_802

.LBB0_892:
	ds_read_b128 v[130:133], v172
	ds_read_b128 v[134:137], v172 offset:1024
	ds_read_b128 v[148:151], v172 offset:2048
	ds_read_b128 v[152:155], v172 offset:3072
	ds_read_b128 v[156:159], v173
	ds_read_b128 v[160:163], v173 offset:1024
	ds_read_b128 v[164:167], v173 offset:2048
	ds_read_b128 v[180:183], v173 offset:3072
	s_add_i32 s18, s8, 0xffe80080
	s_cmp_eq_u32 s77, s52
	s_cselect_b32 s53, s6, s18
	s_cselect_b32 s58, s7, s9
	s_or_b32 s57, s53, 0x80
	s_add_i32 s18, s8, 0xfff80000
	s_mov_b32 m0, s78
	ds_read_b128 v[184:187], v174
	ds_read_b128 v[188:191], v174 offset:1024
	ds_read_b128 v[192:195], v174 offset:2048
	ds_read_b128 v[196:199], v174 offset:3072
	ds_read_b128 v[200:203], v174 offset:4096
	ds_read_b128 v[204:207], v174 offset:5120
	ds_read_b128 v[208:211], v174 offset:6144
	ds_read_b128 v[212:215], v174 offset:7168
	buffer_load_dwordx4 v170, s[12:15], s18 offen lds
	s_mov_b32 m0, s79
	s_nop 0
	buffer_load_dwordx4 v170, s[12:15], s8 offen lds
	s_waitcnt vmcnt(8)
	s_waitcnt lgkmcnt(0)
	s_setprio 1
	v_mfma_f32_16x16x32_bf16 v[126:129], v[130:133], v[184:187], v[126:129]
	s_barrier
	v_mfma_f32_16x16x32_bf16 v[126:129], v[134:137], v[188:191], v[126:129]
	v_mfma_f32_16x16x32_bf16 v[118:121], v[148:151], v[184:187], v[118:121]
	v_mfma_f32_16x16x32_bf16 v[118:121], v[152:155], v[188:191], v[118:121]
	v_mfma_f32_16x16x32_bf16 v[122:125], v[156:159], v[184:187], v[122:125]
	v_mfma_f32_16x16x32_bf16 v[122:125], v[160:163], v[188:191], v[122:125]
	v_mfma_f32_16x16x32_bf16 v[114:117], v[164:167], v[184:187], v[114:117]
	v_mfma_f32_16x16x32_bf16 v[114:117], v[180:183], v[188:191], v[114:117]
	v_mfma_f32_16x16x32_bf16 v[98:101], v[164:167], v[192:195], v[98:101]
	v_mfma_f32_16x16x32_bf16 v[98:101], v[180:183], v[196:199], v[98:101]
	v_mfma_f32_16x16x32_bf16 v[106:109], v[156:159], v[192:195], v[106:109]
	v_mfma_f32_16x16x32_bf16 v[106:109], v[160:163], v[196:199], v[106:109]
	v_mfma_f32_16x16x32_bf16 v[102:105], v[148:151], v[192:195], v[102:105]
	v_mfma_f32_16x16x32_bf16 v[102:105], v[152:155], v[196:199], v[102:105]
	v_mfma_f32_16x16x32_bf16 v[110:113], v[130:133], v[192:195], v[110:113]
	v_mfma_f32_16x16x32_bf16 v[110:113], v[134:137], v[196:199], v[110:113]
	v_mfma_f32_16x16x32_bf16 v[94:97], v[130:133], v[200:203], v[94:97]
	v_mfma_f32_16x16x32_bf16 v[94:97], v[134:137], v[204:207], v[94:97]
	v_mfma_f32_16x16x32_bf16 v[90:93], v[148:151], v[200:203], v[90:93]
	v_mfma_f32_16x16x32_bf16 v[90:93], v[152:155], v[204:207], v[90:93]
	v_mfma_f32_16x16x32_bf16 v[86:89], v[156:159], v[200:203], v[86:89]
	v_mfma_f32_16x16x32_bf16 v[86:89], v[160:163], v[204:207], v[86:89]
	v_mfma_f32_16x16x32_bf16 v[82:85], v[164:167], v[200:203], v[82:85]
	v_mfma_f32_16x16x32_bf16 v[82:85], v[180:183], v[204:207], v[82:85]
	v_mfma_f32_16x16x32_bf16 v[66:69], v[164:167], v[208:211], v[66:69]
	v_mfma_f32_16x16x32_bf16 v[66:69], v[180:183], v[212:215], v[66:69]
	v_mfma_f32_16x16x32_bf16 v[74:77], v[156:159], v[208:211], v[74:77]
	v_mfma_f32_16x16x32_bf16 v[74:77], v[160:163], v[212:215], v[74:77]
	v_mfma_f32_16x16x32_bf16 v[70:73], v[148:151], v[208:211], v[70:73]
	v_mfma_f32_16x16x32_bf16 v[70:73], v[152:155], v[212:215], v[70:73]
	v_mfma_f32_16x16x32_bf16 v[78:81], v[130:133], v[208:211], v[78:81]
	v_mfma_f32_16x16x32_bf16 v[78:81], v[134:137], v[212:215], v[78:81]
	s_setprio 0
	s_barrier
	s_mov_b32 m0, s27
	s_mov_b32 s18, s14
	s_mov_b32 s19, s15
	ds_read_b128 v[184:187], v174 offset:16384
	ds_read_b128 v[188:191], v174 offset:17408
	ds_read_b128 v[192:195], v174 offset:18432
	ds_read_b128 v[196:199], v174 offset:19456
	ds_read_b128 v[200:203], v174 offset:20480
	ds_read_b128 v[204:207], v174 offset:21504
	ds_read_b128 v[208:211], v174 offset:22528
	ds_read_b128 v[212:215], v174 offset:23552
	buffer_load_dwordx4 v171, s[16:19], s58 offen lds
	s_add_i32 s59, s58, 0x80000
	s_mov_b32 m0, s60
	s_nop 0
	buffer_load_dwordx4 v171, s[16:19], s59 offen lds
	s_add_i32 s59, s58, 0x100000
	s_mov_b32 m0, s61
	s_nop 0
	buffer_load_dwordx4 v171, s[16:19], s59 offen lds
	s_add_i32 s59, s58, 0x180000
	s_mov_b32 m0, s62
	s_nop 0
	buffer_load_dwordx4 v171, s[16:19], s59 offen lds
	s_mov_b32 m0, s25
	s_add_i32 s59, s53, 0x80000
	buffer_load_dwordx4 v170, s[12:15], s53 offen lds
	s_mov_b32 m0, s63
	s_nop 0
	buffer_load_dwordx4 v170, s[12:15], s59 offen lds
	s_waitcnt vmcnt(8)
	s_waitcnt lgkmcnt(0)
	s_setprio 1
	v_mfma_f32_16x16x32_bf16 v[62:65], v[130:133], v[184:187], v[62:65]
	s_barrier
	v_mfma_f32_16x16x32_bf16 v[62:65], v[134:137], v[188:191], v[62:65]
	v_mfma_f32_16x16x32_bf16 v[54:57], v[148:151], v[184:187], v[54:57]
	v_mfma_f32_16x16x32_bf16 v[54:57], v[152:155], v[188:191], v[54:57]
	v_mfma_f32_16x16x32_bf16 v[58:61], v[156:159], v[184:187], v[58:61]
	v_mfma_f32_16x16x32_bf16 v[58:61], v[160:163], v[188:191], v[58:61]
	v_mfma_f32_16x16x32_bf16 v[50:53], v[164:167], v[184:187], v[50:53]
	v_mfma_f32_16x16x32_bf16 v[50:53], v[180:183], v[188:191], v[50:53]
	v_mfma_f32_16x16x32_bf16 v[34:37], v[164:167], v[192:195], v[34:37]
	v_mfma_f32_16x16x32_bf16 v[34:37], v[180:183], v[196:199], v[34:37]
	v_mfma_f32_16x16x32_bf16 v[42:45], v[156:159], v[192:195], v[42:45]
	v_mfma_f32_16x16x32_bf16 v[42:45], v[160:163], v[196:199], v[42:45]
	v_mfma_f32_16x16x32_bf16 v[38:41], v[148:151], v[192:195], v[38:41]
	v_mfma_f32_16x16x32_bf16 v[38:41], v[152:155], v[196:199], v[38:41]
	v_mfma_f32_16x16x32_bf16 v[46:49], v[130:133], v[192:195], v[46:49]
	v_mfma_f32_16x16x32_bf16 v[46:49], v[134:137], v[196:199], v[46:49]
	v_mfma_f32_16x16x32_bf16 v[30:33], v[130:133], v[200:203], v[30:33]
	v_mfma_f32_16x16x32_bf16 v[30:33], v[134:137], v[204:207], v[30:33]
	v_mfma_f32_16x16x32_bf16 v[22:25], v[148:151], v[200:203], v[22:25]
	v_mfma_f32_16x16x32_bf16 v[22:25], v[152:155], v[204:207], v[22:25]
	v_mfma_f32_16x16x32_bf16 v[26:29], v[156:159], v[200:203], v[26:29]
	v_mfma_f32_16x16x32_bf16 v[26:29], v[160:163], v[204:207], v[26:29]
	v_mfma_f32_16x16x32_bf16 v[18:21], v[164:167], v[200:203], v[18:21]
	v_mfma_f32_16x16x32_bf16 v[18:21], v[180:183], v[204:207], v[18:21]
	v_mfma_f32_16x16x32_bf16 v[2:5], v[164:167], v[208:211], v[2:5]
	v_mfma_f32_16x16x32_bf16 v[2:5], v[180:183], v[212:215], v[2:5]
	v_mfma_f32_16x16x32_bf16 v[10:13], v[156:159], v[208:211], v[10:13]
	v_mfma_f32_16x16x32_bf16 v[10:13], v[160:163], v[212:215], v[10:13]
	v_mfma_f32_16x16x32_bf16 v[6:9], v[148:151], v[208:211], v[6:9]
	v_mfma_f32_16x16x32_bf16 v[6:9], v[152:155], v[212:215], v[6:9]
	v_mfma_f32_16x16x32_bf16 v[14:17], v[130:133], v[208:211], v[14:17]
	v_mfma_f32_16x16x32_bf16 v[14:17], v[134:137], v[212:215], v[14:17]
	s_setprio 0
	s_barrier
	ds_read_b128 v[130:133], v175
	ds_read_b128 v[134:137], v175 offset:1024
	ds_read_b128 v[148:151], v175 offset:2048
	ds_read_b128 v[152:155], v175 offset:3072
	ds_read_b128 v[156:159], v176
	ds_read_b128 v[160:163], v176 offset:1024
	ds_read_b128 v[164:167], v176 offset:2048
	ds_read_b128 v[180:183], v176 offset:3072
	s_mov_b32 m0, s64
	s_add_i32 s59, s53, 0x100000
	ds_read_b128 v[184:187], v174 offset:32768
	ds_read_b128 v[188:191], v174 offset:33792
	ds_read_b128 v[192:195], v174 offset:34816
	ds_read_b128 v[196:199], v174 offset:35840
	ds_read_b128 v[200:203], v174 offset:36864
	ds_read_b128 v[204:207], v174 offset:37888
	ds_read_b128 v[208:211], v174 offset:38912
	ds_read_b128 v[212:215], v174 offset:39936
	buffer_load_dwordx4 v170, s[12:15], s59 offen lds
	s_add_i32 s59, s53, 0x180000
	s_mov_b32 m0, s65
	s_nop 0
	buffer_load_dwordx4 v170, s[12:15], s59 offen lds
	s_waitcnt vmcnt(8)
	s_waitcnt lgkmcnt(0)
	s_setprio 1
	v_mfma_f32_16x16x32_bf16 v[126:129], v[130:133], v[184:187], v[126:129]
	s_barrier
	v_mfma_f32_16x16x32_bf16 v[126:129], v[134:137], v[188:191], v[126:129]
	v_mfma_f32_16x16x32_bf16 v[118:121], v[148:151], v[184:187], v[118:121]
	v_mfma_f32_16x16x32_bf16 v[118:121], v[152:155], v[188:191], v[118:121]
	v_mfma_f32_16x16x32_bf16 v[122:125], v[156:159], v[184:187], v[122:125]
	v_mfma_f32_16x16x32_bf16 v[122:125], v[160:163], v[188:191], v[122:125]
	v_mfma_f32_16x16x32_bf16 v[114:117], v[164:167], v[184:187], v[114:117]
	v_mfma_f32_16x16x32_bf16 v[114:117], v[180:183], v[188:191], v[114:117]
	v_mfma_f32_16x16x32_bf16 v[98:101], v[164:167], v[192:195], v[98:101]
	v_mfma_f32_16x16x32_bf16 v[98:101], v[180:183], v[196:199], v[98:101]
	v_mfma_f32_16x16x32_bf16 v[106:109], v[156:159], v[192:195], v[106:109]
	v_mfma_f32_16x16x32_bf16 v[106:109], v[160:163], v[196:199], v[106:109]
	v_mfma_f32_16x16x32_bf16 v[102:105], v[148:151], v[192:195], v[102:105]
	v_mfma_f32_16x16x32_bf16 v[102:105], v[152:155], v[196:199], v[102:105]
	v_mfma_f32_16x16x32_bf16 v[110:113], v[130:133], v[192:195], v[110:113]
	v_mfma_f32_16x16x32_bf16 v[110:113], v[134:137], v[196:199], v[110:113]
	v_mfma_f32_16x16x32_bf16 v[94:97], v[130:133], v[200:203], v[94:97]
	v_mfma_f32_16x16x32_bf16 v[94:97], v[134:137], v[204:207], v[94:97]
	v_mfma_f32_16x16x32_bf16 v[90:93], v[148:151], v[200:203], v[90:93]
	v_mfma_f32_16x16x32_bf16 v[90:93], v[152:155], v[204:207], v[90:93]
	v_mfma_f32_16x16x32_bf16 v[86:89], v[156:159], v[200:203], v[86:89]
	v_mfma_f32_16x16x32_bf16 v[86:89], v[160:163], v[204:207], v[86:89]
	v_mfma_f32_16x16x32_bf16 v[82:85], v[164:167], v[200:203], v[82:85]
	v_mfma_f32_16x16x32_bf16 v[82:85], v[180:183], v[204:207], v[82:85]
	v_mfma_f32_16x16x32_bf16 v[66:69], v[164:167], v[208:211], v[66:69]
	v_mfma_f32_16x16x32_bf16 v[66:69], v[180:183], v[212:215], v[66:69]
	v_mfma_f32_16x16x32_bf16 v[74:77], v[156:159], v[208:211], v[74:77]
	v_mfma_f32_16x16x32_bf16 v[74:77], v[160:163], v[212:215], v[74:77]
	v_mfma_f32_16x16x32_bf16 v[70:73], v[148:151], v[208:211], v[70:73]
	v_mfma_f32_16x16x32_bf16 v[70:73], v[152:155], v[212:215], v[70:73]
	v_mfma_f32_16x16x32_bf16 v[78:81], v[130:133], v[208:211], v[78:81]
	v_mfma_f32_16x16x32_bf16 v[78:81], v[134:137], v[212:215], v[78:81]
	s_setprio 0
	s_barrier
	s_mov_b32 m0, s70
	s_or_b32 s59, s58, 0x80
	ds_read_b128 v[184:187], v174 offset:49152
	ds_read_b128 v[188:191], v174 offset:50176
	ds_read_b128 v[192:195], v174 offset:51200
	ds_read_b128 v[196:199], v174 offset:52224
	ds_read_b128 v[200:203], v174 offset:53248
	ds_read_b128 v[204:207], v174 offset:54272
	ds_read_b128 v[208:211], v174 offset:55296
	ds_read_b128 v[212:215], v174 offset:56320
	buffer_load_dwordx4 v171, s[16:19], s59 offen lds
	s_add_i32 s59, s58, 0x80080
	s_mov_b32 m0, s71
	s_add_i32 s53, s53, 0x80080
	buffer_load_dwordx4 v171, s[16:19], s59 offen lds
	s_add_i32 s59, s58, 0x100080
	s_mov_b32 m0, s74
	s_add_i32 s58, s58, 0x180080
	buffer_load_dwordx4 v171, s[16:19], s59 offen lds
	s_mov_b32 m0, s75
	s_nop 0
	buffer_load_dwordx4 v171, s[16:19], s58 offen lds
	s_mov_b32 m0, s72
	s_nop 0
	buffer_load_dwordx4 v170, s[12:15], s57 offen lds
	s_mov_b32 m0, s73
	s_nop 0
	buffer_load_dwordx4 v170, s[12:15], s53 offen lds
	s_waitcnt vmcnt(8)
	s_waitcnt lgkmcnt(0)
	s_setprio 1
	v_mfma_f32_16x16x32_bf16 v[62:65], v[130:133], v[184:187], v[62:65]
	s_barrier
	v_mfma_f32_16x16x32_bf16 v[62:65], v[134:137], v[188:191], v[62:65]
	v_mfma_f32_16x16x32_bf16 v[54:57], v[148:151], v[184:187], v[54:57]
	v_mfma_f32_16x16x32_bf16 v[54:57], v[152:155], v[188:191], v[54:57]
	v_mfma_f32_16x16x32_bf16 v[58:61], v[156:159], v[184:187], v[58:61]
	v_mfma_f32_16x16x32_bf16 v[58:61], v[160:163], v[188:191], v[58:61]
	v_mfma_f32_16x16x32_bf16 v[50:53], v[164:167], v[184:187], v[50:53]
	v_mfma_f32_16x16x32_bf16 v[50:53], v[180:183], v[188:191], v[50:53]
	v_mfma_f32_16x16x32_bf16 v[34:37], v[164:167], v[192:195], v[34:37]
	v_mfma_f32_16x16x32_bf16 v[34:37], v[180:183], v[196:199], v[34:37]
	v_mfma_f32_16x16x32_bf16 v[42:45], v[156:159], v[192:195], v[42:45]
	v_mfma_f32_16x16x32_bf16 v[42:45], v[160:163], v[196:199], v[42:45]
	v_mfma_f32_16x16x32_bf16 v[38:41], v[148:151], v[192:195], v[38:41]
	v_mfma_f32_16x16x32_bf16 v[38:41], v[152:155], v[196:199], v[38:41]
	v_mfma_f32_16x16x32_bf16 v[46:49], v[130:133], v[192:195], v[46:49]
	v_mfma_f32_16x16x32_bf16 v[46:49], v[134:137], v[196:199], v[46:49]
	v_mfma_f32_16x16x32_bf16 v[30:33], v[130:133], v[200:203], v[30:33]
	v_mfma_f32_16x16x32_bf16 v[30:33], v[134:137], v[204:207], v[30:33]
	v_mfma_f32_16x16x32_bf16 v[22:25], v[148:151], v[200:203], v[22:25]
	v_mfma_f32_16x16x32_bf16 v[22:25], v[152:155], v[204:207], v[22:25]
	v_mfma_f32_16x16x32_bf16 v[26:29], v[156:159], v[200:203], v[26:29]
	v_mfma_f32_16x16x32_bf16 v[26:29], v[160:163], v[204:207], v[26:29]
	v_mfma_f32_16x16x32_bf16 v[18:21], v[164:167], v[200:203], v[18:21]
	v_mfma_f32_16x16x32_bf16 v[18:21], v[180:183], v[204:207], v[18:21]
	v_mfma_f32_16x16x32_bf16 v[2:5], v[164:167], v[208:211], v[2:5]
	v_mfma_f32_16x16x32_bf16 v[2:5], v[180:183], v[212:215], v[2:5]
	v_mfma_f32_16x16x32_bf16 v[10:13], v[156:159], v[208:211], v[10:13]
	v_mfma_f32_16x16x32_bf16 v[10:13], v[160:163], v[212:215], v[10:13]
	v_mfma_f32_16x16x32_bf16 v[6:9], v[148:151], v[208:211], v[6:9]
	v_mfma_f32_16x16x32_bf16 v[6:9], v[152:155], v[212:215], v[6:9]
	v_mfma_f32_16x16x32_bf16 v[14:17], v[130:133], v[208:211], v[14:17]
	v_mfma_f32_16x16x32_bf16 v[14:17], v[134:137], v[212:215], v[14:17]
	s_setprio 0
	s_barrier
	s_add_i32 s52, s52, 2
	s_addk_i32 s8, 0x100
	s_addk_i32 s9, 0x100
	s_cmp_ge_i32 s52, s21
	s_cbranch_scc0 .LBB0_892
	s_and_b64 vcc, exec, s[48:49]
	s_cbranch_vccz .LBB0_895

.LBB0_1020:
	v_add_u32_e32 v142, 0x10000, v162
	v_add_u32_e32 v150, 0x14000, v162
	ds_read_b128 v[130:133], v142
	ds_read_b128 v[134:137], v142 offset:1024
	ds_read_b128 v[138:141], v142 offset:2048
	ds_read_b128 v[142:145], v142 offset:3072
	ds_read_b128 v[154:157], v150
	ds_read_b128 v[164:167], v150 offset:1024
	ds_read_b128 v[168:171], v150 offset:2048
	ds_read_b128 v[172:175], v150 offset:3072
	s_add_i32 s90, s6, 0x100
	s_add_i32 s7, s88, s6
	s_cmp_eq_u32 s81, s89
	s_cselect_b32 s91, 0, s90
	s_cselect_b32 s93, s87, s7
	s_add_i32 s91, s91, s70
	s_or_b32 s92, s91, 0x80
	s_add_i32 s6, s3, s6
	s_mov_b32 m0, s82
	s_add_i32 s7, s6, 0x20080
	ds_read_b128 v[176:179], v163
	ds_read_b128 v[180:183], v163 offset:1024
	ds_read_b128 v[184:187], v163 offset:2048
	ds_read_b128 v[188:191], v163 offset:3072
	ds_read_b128 v[192:195], v163 offset:4096
	ds_read_b128 v[196:199], v163 offset:5120
	ds_read_b128 v[200:203], v163 offset:6144
	ds_read_b128 v[204:207], v163 offset:7168
	buffer_load_dwordx4 v161, s[12:15], s7 offen lds
	s_add_i32 s6, s6, 0x30080
	s_mov_b32 m0, s83
	s_nop 0
	buffer_load_dwordx4 v161, s[12:15], s6 offen lds
	s_waitcnt vmcnt(8)
	s_waitcnt lgkmcnt(0)
	s_setprio 1
	v_mfma_f32_16x16x32_bf16 v[126:129], v[130:133], v[176:179], v[126:129]
	s_barrier
	v_mfma_f32_16x16x32_bf16 v[126:129], v[134:137], v[180:183], v[126:129]
	v_mfma_f32_16x16x32_bf16 v[122:125], v[138:141], v[176:179], v[122:125]
	v_mfma_f32_16x16x32_bf16 v[122:125], v[142:145], v[180:183], v[122:125]
	v_mfma_f32_16x16x32_bf16 v[118:121], v[154:157], v[176:179], v[118:121]
	v_mfma_f32_16x16x32_bf16 v[118:121], v[164:167], v[180:183], v[118:121]
	v_mfma_f32_16x16x32_bf16 v[114:117], v[168:171], v[176:179], v[114:117]
	v_mfma_f32_16x16x32_bf16 v[114:117], v[172:175], v[180:183], v[114:117]
	v_mfma_f32_16x16x32_bf16 v[98:101], v[168:171], v[184:187], v[98:101]
	v_mfma_f32_16x16x32_bf16 v[98:101], v[172:175], v[188:191], v[98:101]
	v_mfma_f32_16x16x32_bf16 v[102:105], v[154:157], v[184:187], v[102:105]
	v_mfma_f32_16x16x32_bf16 v[102:105], v[164:167], v[188:191], v[102:105]
	v_mfma_f32_16x16x32_bf16 v[106:109], v[138:141], v[184:187], v[106:109]
	v_mfma_f32_16x16x32_bf16 v[106:109], v[142:145], v[188:191], v[106:109]
	v_mfma_f32_16x16x32_bf16 v[110:113], v[130:133], v[184:187], v[110:113]
	v_mfma_f32_16x16x32_bf16 v[110:113], v[134:137], v[188:191], v[110:113]
	v_mfma_f32_16x16x32_bf16 v[94:97], v[130:133], v[192:195], v[94:97]
	v_mfma_f32_16x16x32_bf16 v[94:97], v[134:137], v[196:199], v[94:97]
	v_mfma_f32_16x16x32_bf16 v[90:93], v[138:141], v[192:195], v[90:93]
	v_mfma_f32_16x16x32_bf16 v[90:93], v[142:145], v[196:199], v[90:93]
	v_mfma_f32_16x16x32_bf16 v[86:89], v[154:157], v[192:195], v[86:89]
	v_mfma_f32_16x16x32_bf16 v[86:89], v[164:167], v[196:199], v[86:89]
	v_mfma_f32_16x16x32_bf16 v[82:85], v[168:171], v[192:195], v[82:85]
	v_mfma_f32_16x16x32_bf16 v[82:85], v[172:175], v[196:199], v[82:85]
	v_mfma_f32_16x16x32_bf16 v[66:69], v[168:171], v[200:203], v[66:69]
	v_mfma_f32_16x16x32_bf16 v[66:69], v[172:175], v[204:207], v[66:69]
	v_mfma_f32_16x16x32_bf16 v[70:73], v[154:157], v[200:203], v[70:73]
	v_mfma_f32_16x16x32_bf16 v[70:73], v[164:167], v[204:207], v[70:73]
	v_mfma_f32_16x16x32_bf16 v[74:77], v[138:141], v[200:203], v[74:77]
	v_mfma_f32_16x16x32_bf16 v[74:77], v[142:145], v[204:207], v[74:77]
	v_mfma_f32_16x16x32_bf16 v[78:81], v[130:133], v[200:203], v[78:81]
	v_mfma_f32_16x16x32_bf16 v[78:81], v[134:137], v[204:207], v[78:81]
	s_setprio 0
	s_barrier
	s_mov_b32 m0, s66
	s_mov_b32 s6, s14
	s_mov_b32 s7, s15
	ds_read_b128 v[176:179], v163 offset:16384
	ds_read_b128 v[180:183], v163 offset:17408
	ds_read_b128 v[184:187], v163 offset:18432
	ds_read_b128 v[188:191], v163 offset:19456
	ds_read_b128 v[192:195], v163 offset:20480
	ds_read_b128 v[196:199], v163 offset:21504
	ds_read_b128 v[200:203], v163 offset:22528
	ds_read_b128 v[204:207], v163 offset:23552
	buffer_load_dwordx4 v160, s[4:7], s93 offen lds
	s_add_i32 s94, s93, 0x10000
	s_mov_b32 m0, s67
	s_nop 0
	buffer_load_dwordx4 v160, s[4:7], s94 offen lds
	s_add_i32 s94, s93, 0x20000
	s_mov_b32 m0, s68
	s_nop 0
	buffer_load_dwordx4 v160, s[4:7], s94 offen lds
	s_add_i32 s94, s93, 0x30000
	s_mov_b32 m0, s69
	s_nop 0
	buffer_load_dwordx4 v160, s[4:7], s94 offen lds
	s_mov_b32 m0, s65
	s_add_i32 s94, s91, 0x10000
	buffer_load_dwordx4 v161, s[12:15], s91 offen lds
	s_mov_b32 m0, s71
	s_nop 0
	buffer_load_dwordx4 v161, s[12:15], s94 offen lds
	s_waitcnt vmcnt(8)
	s_waitcnt lgkmcnt(0)
	s_setprio 1
	v_mfma_f32_16x16x32_bf16 v[62:65], v[130:133], v[176:179], v[62:65]
	s_barrier
	v_mfma_f32_16x16x32_bf16 v[62:65], v[134:137], v[180:183], v[62:65]
	v_mfma_f32_16x16x32_bf16 v[58:61], v[138:141], v[176:179], v[58:61]
	v_mfma_f32_16x16x32_bf16 v[58:61], v[142:145], v[180:183], v[58:61]
	v_mfma_f32_16x16x32_bf16 v[54:57], v[154:157], v[176:179], v[54:57]
	v_mfma_f32_16x16x32_bf16 v[54:57], v[164:167], v[180:183], v[54:57]
	v_mfma_f32_16x16x32_bf16 v[50:53], v[168:171], v[176:179], v[50:53]
	v_mfma_f32_16x16x32_bf16 v[50:53], v[172:175], v[180:183], v[50:53]
	v_mfma_f32_16x16x32_bf16 v[34:37], v[168:171], v[184:187], v[34:37]
	v_mfma_f32_16x16x32_bf16 v[34:37], v[172:175], v[188:191], v[34:37]
	v_mfma_f32_16x16x32_bf16 v[38:41], v[154:157], v[184:187], v[38:41]
	v_mfma_f32_16x16x32_bf16 v[38:41], v[164:167], v[188:191], v[38:41]
	v_mfma_f32_16x16x32_bf16 v[42:45], v[138:141], v[184:187], v[42:45]
	v_mfma_f32_16x16x32_bf16 v[42:45], v[142:145], v[188:191], v[42:45]
	v_mfma_f32_16x16x32_bf16 v[46:49], v[130:133], v[184:187], v[46:49]
	v_mfma_f32_16x16x32_bf16 v[46:49], v[134:137], v[188:191], v[46:49]
	v_mfma_f32_16x16x32_bf16 v[30:33], v[130:133], v[192:195], v[30:33]
	v_mfma_f32_16x16x32_bf16 v[30:33], v[134:137], v[196:199], v[30:33]
	v_mfma_f32_16x16x32_bf16 v[26:29], v[138:141], v[192:195], v[26:29]
	v_mfma_f32_16x16x32_bf16 v[26:29], v[142:145], v[196:199], v[26:29]
	v_mfma_f32_16x16x32_bf16 v[22:25], v[154:157], v[192:195], v[22:25]
	v_mfma_f32_16x16x32_bf16 v[22:25], v[164:167], v[196:199], v[22:25]
	v_mfma_f32_16x16x32_bf16 v[18:21], v[168:171], v[192:195], v[18:21]
	v_mfma_f32_16x16x32_bf16 v[18:21], v[172:175], v[196:199], v[18:21]
	v_mfma_f32_16x16x32_bf16 v[2:5], v[168:171], v[200:203], v[2:5]
	v_mfma_f32_16x16x32_bf16 v[2:5], v[172:175], v[204:207], v[2:5]
	v_mfma_f32_16x16x32_bf16 v[6:9], v[154:157], v[200:203], v[6:9]
	v_mfma_f32_16x16x32_bf16 v[6:9], v[164:167], v[204:207], v[6:9]
	v_mfma_f32_16x16x32_bf16 v[10:13], v[138:141], v[200:203], v[10:13]
	v_mfma_f32_16x16x32_bf16 v[10:13], v[142:145], v[204:207], v[10:13]
	v_mfma_f32_16x16x32_bf16 v[14:17], v[130:133], v[200:203], v[14:17]
	v_mfma_f32_16x16x32_bf16 v[14:17], v[134:137], v[204:207], v[14:17]
	s_setprio 0
	s_barrier
	v_add_u32_e32 v142, 0x18000, v162
	v_add_u32_e32 v150, 0x1c000, v162
	ds_read_b128 v[130:133], v142
	ds_read_b128 v[134:137], v142 offset:1024
	ds_read_b128 v[138:141], v142 offset:2048
	ds_read_b128 v[142:145], v142 offset:3072
	ds_read_b128 v[154:157], v150
	ds_read_b128 v[164:167], v150 offset:1024
	ds_read_b128 v[168:171], v150 offset:2048
	ds_read_b128 v[172:175], v150 offset:3072
	s_mov_b32 m0, s72
	s_add_i32 s94, s91, 0x20000
	ds_read_b128 v[176:179], v163 offset:32768
	ds_read_b128 v[180:183], v163 offset:33792
	ds_read_b128 v[184:187], v163 offset:34816
	ds_read_b128 v[188:191], v163 offset:35840
	ds_read_b128 v[192:195], v163 offset:36864
	ds_read_b128 v[196:199], v163 offset:37888
	ds_read_b128 v[200:203], v163 offset:38912
	ds_read_b128 v[204:207], v163 offset:39936
	buffer_load_dwordx4 v161, s[12:15], s94 offen lds
	s_add_i32 s94, s91, 0x30000
	s_mov_b32 m0, s73
	s_nop 0
	buffer_load_dwordx4 v161, s[12:15], s94 offen lds
	s_waitcnt vmcnt(8)
	s_waitcnt lgkmcnt(0)
	s_setprio 1
	v_mfma_f32_16x16x32_bf16 v[126:129], v[130:133], v[176:179], v[126:129]
	s_barrier
	v_mfma_f32_16x16x32_bf16 v[126:129], v[134:137], v[180:183], v[126:129]
	v_mfma_f32_16x16x32_bf16 v[122:125], v[138:141], v[176:179], v[122:125]
	v_mfma_f32_16x16x32_bf16 v[122:125], v[142:145], v[180:183], v[122:125]
	v_mfma_f32_16x16x32_bf16 v[118:121], v[154:157], v[176:179], v[118:121]
	v_mfma_f32_16x16x32_bf16 v[118:121], v[164:167], v[180:183], v[118:121]
	v_mfma_f32_16x16x32_bf16 v[114:117], v[168:171], v[176:179], v[114:117]
	v_mfma_f32_16x16x32_bf16 v[114:117], v[172:175], v[180:183], v[114:117]
	v_mfma_f32_16x16x32_bf16 v[98:101], v[168:171], v[184:187], v[98:101]
	v_mfma_f32_16x16x32_bf16 v[98:101], v[172:175], v[188:191], v[98:101]
	v_mfma_f32_16x16x32_bf16 v[102:105], v[154:157], v[184:187], v[102:105]
	v_mfma_f32_16x16x32_bf16 v[102:105], v[164:167], v[188:191], v[102:105]
	v_mfma_f32_16x16x32_bf16 v[106:109], v[138:141], v[184:187], v[106:109]
	v_mfma_f32_16x16x32_bf16 v[106:109], v[142:145], v[188:191], v[106:109]
	v_mfma_f32_16x16x32_bf16 v[110:113], v[130:133], v[184:187], v[110:113]
	v_mfma_f32_16x16x32_bf16 v[110:113], v[134:137], v[188:191], v[110:113]
	v_mfma_f32_16x16x32_bf16 v[94:97], v[130:133], v[192:195], v[94:97]
	v_mfma_f32_16x16x32_bf16 v[94:97], v[134:137], v[196:199], v[94:97]
	v_mfma_f32_16x16x32_bf16 v[90:93], v[138:141], v[192:195], v[90:93]
	v_mfma_f32_16x16x32_bf16 v[90:93], v[142:145], v[196:199], v[90:93]
	v_mfma_f32_16x16x32_bf16 v[86:89], v[154:157], v[192:195], v[86:89]
	v_mfma_f32_16x16x32_bf16 v[86:89], v[164:167], v[196:199], v[86:89]
	v_mfma_f32_16x16x32_bf16 v[82:85], v[168:171], v[192:195], v[82:85]
	v_mfma_f32_16x16x32_bf16 v[82:85], v[172:175], v[196:199], v[82:85]
	v_mfma_f32_16x16x32_bf16 v[66:69], v[168:171], v[200:203], v[66:69]
	v_mfma_f32_16x16x32_bf16 v[66:69], v[172:175], v[204:207], v[66:69]
	v_mfma_f32_16x16x32_bf16 v[70:73], v[154:157], v[200:203], v[70:73]
	v_mfma_f32_16x16x32_bf16 v[70:73], v[164:167], v[204:207], v[70:73]
	v_mfma_f32_16x16x32_bf16 v[74:77], v[138:141], v[200:203], v[74:77]
	v_mfma_f32_16x16x32_bf16 v[74:77], v[142:145], v[204:207], v[74:77]
	v_mfma_f32_16x16x32_bf16 v[78:81], v[130:133], v[200:203], v[78:81]
	v_mfma_f32_16x16x32_bf16 v[78:81], v[134:137], v[204:207], v[78:81]
	s_setprio 0
	s_barrier
	s_mov_b32 m0, s74
	s_or_b32 s94, s93, 0x80
	ds_read_b128 v[176:179], v163 offset:49152
	ds_read_b128 v[180:183], v163 offset:50176
	ds_read_b128 v[184:187], v163 offset:51200
	ds_read_b128 v[188:191], v163 offset:52224
	ds_read_b128 v[192:195], v163 offset:53248
	ds_read_b128 v[196:199], v163 offset:54272
	ds_read_b128 v[200:203], v163 offset:55296
	ds_read_b128 v[204:207], v163 offset:56320
	buffer_load_dwordx4 v160, s[4:7], s94 offen lds
	s_add_i32 s94, s93, 0x10080
	s_mov_b32 m0, s75
	s_add_i32 s91, s91, 0x10080
	buffer_load_dwordx4 v160, s[4:7], s94 offen lds
	s_add_i32 s94, s93, 0x20080
	s_mov_b32 m0, s78
	s_add_i32 s93, s93, 0x30080
	buffer_load_dwordx4 v160, s[4:7], s94 offen lds
	s_mov_b32 m0, s79
	s_nop 0
	buffer_load_dwordx4 v160, s[4:7], s93 offen lds
	s_mov_b32 m0, s76
	s_nop 0
	buffer_load_dwordx4 v161, s[12:15], s92 offen lds
	s_mov_b32 m0, s77
	s_nop 0
	buffer_load_dwordx4 v161, s[12:15], s91 offen lds
	s_waitcnt vmcnt(8)
	s_waitcnt lgkmcnt(0)
	s_setprio 1
	v_mfma_f32_16x16x32_bf16 v[62:65], v[130:133], v[176:179], v[62:65]
	s_barrier
	v_mfma_f32_16x16x32_bf16 v[62:65], v[134:137], v[180:183], v[62:65]
	v_mfma_f32_16x16x32_bf16 v[58:61], v[138:141], v[176:179], v[58:61]
	v_mfma_f32_16x16x32_bf16 v[58:61], v[142:145], v[180:183], v[58:61]
	v_mfma_f32_16x16x32_bf16 v[54:57], v[154:157], v[176:179], v[54:57]
	v_mfma_f32_16x16x32_bf16 v[54:57], v[164:167], v[180:183], v[54:57]
	v_mfma_f32_16x16x32_bf16 v[50:53], v[168:171], v[176:179], v[50:53]
	v_mfma_f32_16x16x32_bf16 v[50:53], v[172:175], v[180:183], v[50:53]
	v_mfma_f32_16x16x32_bf16 v[34:37], v[168:171], v[184:187], v[34:37]
	v_mfma_f32_16x16x32_bf16 v[34:37], v[172:175], v[188:191], v[34:37]
	v_mfma_f32_16x16x32_bf16 v[38:41], v[154:157], v[184:187], v[38:41]
	v_mfma_f32_16x16x32_bf16 v[38:41], v[164:167], v[188:191], v[38:41]
	v_mfma_f32_16x16x32_bf16 v[42:45], v[138:141], v[184:187], v[42:45]
	v_mfma_f32_16x16x32_bf16 v[42:45], v[142:145], v[188:191], v[42:45]
	v_mfma_f32_16x16x32_bf16 v[46:49], v[130:133], v[184:187], v[46:49]
	v_mfma_f32_16x16x32_bf16 v[46:49], v[134:137], v[188:191], v[46:49]
	v_mfma_f32_16x16x32_bf16 v[30:33], v[130:133], v[192:195], v[30:33]
	v_mfma_f32_16x16x32_bf16 v[30:33], v[134:137], v[196:199], v[30:33]
	v_mfma_f32_16x16x32_bf16 v[26:29], v[138:141], v[192:195], v[26:29]
	v_mfma_f32_16x16x32_bf16 v[26:29], v[142:145], v[196:199], v[26:29]
	v_mfma_f32_16x16x32_bf16 v[22:25], v[154:157], v[192:195], v[22:25]
	v_mfma_f32_16x16x32_bf16 v[22:25], v[164:167], v[196:199], v[22:25]
	v_mfma_f32_16x16x32_bf16 v[18:21], v[168:171], v[192:195], v[18:21]
	v_mfma_f32_16x16x32_bf16 v[18:21], v[172:175], v[196:199], v[18:21]
	v_mfma_f32_16x16x32_bf16 v[2:5], v[168:171], v[200:203], v[2:5]
	v_mfma_f32_16x16x32_bf16 v[2:5], v[172:175], v[204:207], v[2:5]
	v_mfma_f32_16x16x32_bf16 v[6:9], v[154:157], v[200:203], v[6:9]
	v_mfma_f32_16x16x32_bf16 v[6:9], v[164:167], v[204:207], v[6:9]
	v_mfma_f32_16x16x32_bf16 v[10:13], v[138:141], v[200:203], v[10:13]
	v_mfma_f32_16x16x32_bf16 v[10:13], v[142:145], v[204:207], v[10:13]
	v_mfma_f32_16x16x32_bf16 v[14:17], v[130:133], v[200:203], v[14:17]
	v_mfma_f32_16x16x32_bf16 v[14:17], v[134:137], v[204:207], v[14:17]
	s_setprio 0
	s_barrier
	s_add_i32 s89, s89, 2
	s_cmp_ge_i32 s89, s63
	s_mov_b32 s6, s90
	s_cbranch_scc0 .LBB0_1020
	s_and_b64 vcc, exec, s[54:55]
	s_cbranch_vccz .LBB0_1023

.LBB0_1035:
	ds_read_b128 v[140:143], v134
	ds_read_b128 v[148:151], v134 offset:1024
	ds_read_b128 v[152:155], v134 offset:2048
	ds_read_b128 v[156:159], v134 offset:3072
	ds_read_b128 v[160:163], v135
	ds_read_b128 v[164:167], v135 offset:1024
	ds_read_b128 v[168:171], v135 offset:2048
	ds_read_b128 v[172:175], v135 offset:3072
	s_add_i32 s73, s70, 0xfffb8080
	s_cmp_eq_u32 s53, s72
	s_cselect_b32 s73, s68, s73
	s_cselect_b32 s75, s69, s71
	s_add_i32 s74, s73, 0x80
	s_add_i32 s76, s70, 0xfffe8000
	s_mov_b32 m0, s54
	ds_read_b128 v[176:179], v136
	ds_read_b128 v[180:183], v136 offset:1024
	ds_read_b128 v[184:187], v136 offset:2048
	ds_read_b128 v[188:191], v136 offset:3072
	ds_read_b128 v[192:195], v136 offset:4096
	ds_read_b128 v[196:199], v136 offset:5120
	ds_read_b128 v[200:203], v136 offset:6144
	ds_read_b128 v[204:207], v136 offset:7168
	buffer_load_dwordx4 v132, s[12:15], s76 offen lds
	s_mov_b32 m0, s55
	s_nop 0
	buffer_load_dwordx4 v132, s[12:15], s70 offen lds
	s_waitcnt vmcnt(8)
	s_waitcnt lgkmcnt(0)
	s_setprio 1
	v_mfma_f32_16x16x32_bf16 v[126:129], v[140:143], v[176:179], v[126:129]
	s_barrier
	v_mfma_f32_16x16x32_bf16 v[126:129], v[148:151], v[180:183], v[126:129]
	v_mfma_f32_16x16x32_bf16 v[122:125], v[152:155], v[176:179], v[122:125]
	v_mfma_f32_16x16x32_bf16 v[122:125], v[156:159], v[180:183], v[122:125]
	v_mfma_f32_16x16x32_bf16 v[118:121], v[160:163], v[176:179], v[118:121]
	v_mfma_f32_16x16x32_bf16 v[118:121], v[164:167], v[180:183], v[118:121]
	v_mfma_f32_16x16x32_bf16 v[114:117], v[168:171], v[176:179], v[114:117]
	v_mfma_f32_16x16x32_bf16 v[114:117], v[172:175], v[180:183], v[114:117]
	v_mfma_f32_16x16x32_bf16 v[98:101], v[168:171], v[184:187], v[98:101]
	v_mfma_f32_16x16x32_bf16 v[98:101], v[172:175], v[188:191], v[98:101]
	v_mfma_f32_16x16x32_bf16 v[102:105], v[160:163], v[184:187], v[102:105]
	v_mfma_f32_16x16x32_bf16 v[102:105], v[164:167], v[188:191], v[102:105]
	v_mfma_f32_16x16x32_bf16 v[106:109], v[152:155], v[184:187], v[106:109]
	v_mfma_f32_16x16x32_bf16 v[106:109], v[156:159], v[188:191], v[106:109]
	v_mfma_f32_16x16x32_bf16 v[110:113], v[140:143], v[184:187], v[110:113]
	v_mfma_f32_16x16x32_bf16 v[110:113], v[148:151], v[188:191], v[110:113]
	v_mfma_f32_16x16x32_bf16 v[94:97], v[140:143], v[192:195], v[94:97]
	v_mfma_f32_16x16x32_bf16 v[94:97], v[148:151], v[196:199], v[94:97]
	v_mfma_f32_16x16x32_bf16 v[90:93], v[152:155], v[192:195], v[90:93]
	v_mfma_f32_16x16x32_bf16 v[90:93], v[156:159], v[196:199], v[90:93]
	v_mfma_f32_16x16x32_bf16 v[86:89], v[160:163], v[192:195], v[86:89]
	v_mfma_f32_16x16x32_bf16 v[86:89], v[164:167], v[196:199], v[86:89]
	v_mfma_f32_16x16x32_bf16 v[82:85], v[168:171], v[192:195], v[82:85]
	v_mfma_f32_16x16x32_bf16 v[82:85], v[172:175], v[196:199], v[82:85]
	v_mfma_f32_16x16x32_bf16 v[66:69], v[168:171], v[200:203], v[66:69]
	v_mfma_f32_16x16x32_bf16 v[66:69], v[172:175], v[204:207], v[66:69]
	v_mfma_f32_16x16x32_bf16 v[70:73], v[160:163], v[200:203], v[70:73]
	v_mfma_f32_16x16x32_bf16 v[70:73], v[164:167], v[204:207], v[70:73]
	v_mfma_f32_16x16x32_bf16 v[74:77], v[152:155], v[200:203], v[74:77]
	v_mfma_f32_16x16x32_bf16 v[74:77], v[156:159], v[204:207], v[74:77]
	v_mfma_f32_16x16x32_bf16 v[78:81], v[140:143], v[200:203], v[78:81]
	v_mfma_f32_16x16x32_bf16 v[78:81], v[148:151], v[204:207], v[78:81]
	s_setprio 0
	s_barrier
	s_mov_b32 m0, s30
	ds_read_b128 v[176:179], v136 offset:16384
	ds_read_b128 v[180:183], v136 offset:17408
	ds_read_b128 v[184:187], v136 offset:18432
	ds_read_b128 v[188:191], v136 offset:19456
	ds_read_b128 v[192:195], v136 offset:20480
	ds_read_b128 v[196:199], v136 offset:21504
	ds_read_b128 v[200:203], v136 offset:22528
	ds_read_b128 v[204:207], v136 offset:23552
	buffer_load_dwordx4 v133, s[16:19], s75 offen lds
	s_add_i32 s76, s75, 0x200000
	s_mov_b32 m0, s31
	s_nop 0
	buffer_load_dwordx4 v133, s[16:19], s76 offen lds
	s_add_i32 s76, s75, 0x400000
	s_mov_b32 m0, s35
	s_nop 0
	buffer_load_dwordx4 v133, s[16:19], s76 offen lds
	s_add_i32 s76, s75, 0x600000
	s_mov_b32 m0, s42
	s_nop 0
	buffer_load_dwordx4 v133, s[16:19], s76 offen lds
	s_mov_b32 m0, s27
	s_add_i32 s76, s73, 0x18000
	buffer_load_dwordx4 v132, s[12:15], s73 offen lds
	s_mov_b32 m0, s43
	s_nop 0
	buffer_load_dwordx4 v132, s[12:15], s76 offen lds
	s_waitcnt vmcnt(8)
	s_waitcnt lgkmcnt(0)
	s_setprio 1
	v_mfma_f32_16x16x32_bf16 v[62:65], v[140:143], v[176:179], v[62:65]
	s_barrier
	v_mfma_f32_16x16x32_bf16 v[62:65], v[148:151], v[180:183], v[62:65]
	v_mfma_f32_16x16x32_bf16 v[58:61], v[152:155], v[176:179], v[58:61]
	v_mfma_f32_16x16x32_bf16 v[58:61], v[156:159], v[180:183], v[58:61]
	v_mfma_f32_16x16x32_bf16 v[54:57], v[160:163], v[176:179], v[54:57]
	v_mfma_f32_16x16x32_bf16 v[54:57], v[164:167], v[180:183], v[54:57]
	v_mfma_f32_16x16x32_bf16 v[50:53], v[168:171], v[176:179], v[50:53]
	v_mfma_f32_16x16x32_bf16 v[50:53], v[172:175], v[180:183], v[50:53]
	v_mfma_f32_16x16x32_bf16 v[34:37], v[168:171], v[184:187], v[34:37]
	v_mfma_f32_16x16x32_bf16 v[34:37], v[172:175], v[188:191], v[34:37]
	v_mfma_f32_16x16x32_bf16 v[38:41], v[160:163], v[184:187], v[38:41]
	v_mfma_f32_16x16x32_bf16 v[38:41], v[164:167], v[188:191], v[38:41]
	v_mfma_f32_16x16x32_bf16 v[42:45], v[152:155], v[184:187], v[42:45]
	v_mfma_f32_16x16x32_bf16 v[42:45], v[156:159], v[188:191], v[42:45]
	v_mfma_f32_16x16x32_bf16 v[46:49], v[140:143], v[184:187], v[46:49]
	v_mfma_f32_16x16x32_bf16 v[46:49], v[148:151], v[188:191], v[46:49]
	v_mfma_f32_16x16x32_bf16 v[30:33], v[140:143], v[192:195], v[30:33]
	v_mfma_f32_16x16x32_bf16 v[30:33], v[148:151], v[196:199], v[30:33]
	v_mfma_f32_16x16x32_bf16 v[26:29], v[152:155], v[192:195], v[26:29]
	v_mfma_f32_16x16x32_bf16 v[26:29], v[156:159], v[196:199], v[26:29]
	v_mfma_f32_16x16x32_bf16 v[22:25], v[160:163], v[192:195], v[22:25]
	v_mfma_f32_16x16x32_bf16 v[22:25], v[164:167], v[196:199], v[22:25]
	v_mfma_f32_16x16x32_bf16 v[18:21], v[168:171], v[192:195], v[18:21]
	v_mfma_f32_16x16x32_bf16 v[18:21], v[172:175], v[196:199], v[18:21]
	v_mfma_f32_16x16x32_bf16 v[2:5], v[168:171], v[200:203], v[2:5]
	v_mfma_f32_16x16x32_bf16 v[2:5], v[172:175], v[204:207], v[2:5]
	v_mfma_f32_16x16x32_bf16 v[6:9], v[160:163], v[200:203], v[6:9]
	v_mfma_f32_16x16x32_bf16 v[6:9], v[164:167], v[204:207], v[6:9]
	v_mfma_f32_16x16x32_bf16 v[10:13], v[152:155], v[200:203], v[10:13]
	v_mfma_f32_16x16x32_bf16 v[10:13], v[156:159], v[204:207], v[10:13]
	v_mfma_f32_16x16x32_bf16 v[14:17], v[140:143], v[200:203], v[14:17]
	v_mfma_f32_16x16x32_bf16 v[14:17], v[148:151], v[204:207], v[14:17]
	s_setprio 0
	s_barrier
	ds_read_b128 v[140:143], v137
	ds_read_b128 v[148:151], v137 offset:1024
	ds_read_b128 v[152:155], v137 offset:2048
	ds_read_b128 v[156:159], v137 offset:3072
	ds_read_b128 v[160:163], v138
	ds_read_b128 v[164:167], v138 offset:1024
	ds_read_b128 v[168:171], v138 offset:2048
	ds_read_b128 v[172:175], v138 offset:3072
	s_mov_b32 m0, s44
	s_add_i32 s76, s73, 0x30000
	ds_read_b128 v[176:179], v136 offset:32768
	ds_read_b128 v[180:183], v136 offset:33792
	ds_read_b128 v[184:187], v136 offset:34816
	ds_read_b128 v[188:191], v136 offset:35840
	ds_read_b128 v[192:195], v136 offset:36864
	ds_read_b128 v[196:199], v136 offset:37888
	ds_read_b128 v[200:203], v136 offset:38912
	ds_read_b128 v[204:207], v136 offset:39936
	buffer_load_dwordx4 v132, s[12:15], s76 offen lds
	s_add_i32 s76, s73, 0x48000
	s_mov_b32 m0, s45
	s_nop 0
	buffer_load_dwordx4 v132, s[12:15], s76 offen lds
	s_waitcnt vmcnt(8)
	s_waitcnt lgkmcnt(0)
	s_setprio 1
	v_mfma_f32_16x16x32_bf16 v[126:129], v[140:143], v[176:179], v[126:129]
	s_barrier
	v_mfma_f32_16x16x32_bf16 v[126:129], v[148:151], v[180:183], v[126:129]
	v_mfma_f32_16x16x32_bf16 v[122:125], v[152:155], v[176:179], v[122:125]
	v_mfma_f32_16x16x32_bf16 v[122:125], v[156:159], v[180:183], v[122:125]
	v_mfma_f32_16x16x32_bf16 v[118:121], v[160:163], v[176:179], v[118:121]
	v_mfma_f32_16x16x32_bf16 v[118:121], v[164:167], v[180:183], v[118:121]
	v_mfma_f32_16x16x32_bf16 v[114:117], v[168:171], v[176:179], v[114:117]
	v_mfma_f32_16x16x32_bf16 v[114:117], v[172:175], v[180:183], v[114:117]
	v_mfma_f32_16x16x32_bf16 v[98:101], v[168:171], v[184:187], v[98:101]
	v_mfma_f32_16x16x32_bf16 v[98:101], v[172:175], v[188:191], v[98:101]
	v_mfma_f32_16x16x32_bf16 v[102:105], v[160:163], v[184:187], v[102:105]
	v_mfma_f32_16x16x32_bf16 v[102:105], v[164:167], v[188:191], v[102:105]
	v_mfma_f32_16x16x32_bf16 v[106:109], v[152:155], v[184:187], v[106:109]
	v_mfma_f32_16x16x32_bf16 v[106:109], v[156:159], v[188:191], v[106:109]
	v_mfma_f32_16x16x32_bf16 v[110:113], v[140:143], v[184:187], v[110:113]
	v_mfma_f32_16x16x32_bf16 v[110:113], v[148:151], v[188:191], v[110:113]
	v_mfma_f32_16x16x32_bf16 v[94:97], v[140:143], v[192:195], v[94:97]
	v_mfma_f32_16x16x32_bf16 v[94:97], v[148:151], v[196:199], v[94:97]
	v_mfma_f32_16x16x32_bf16 v[90:93], v[152:155], v[192:195], v[90:93]
	v_mfma_f32_16x16x32_bf16 v[90:93], v[156:159], v[196:199], v[90:93]
	v_mfma_f32_16x16x32_bf16 v[86:89], v[160:163], v[192:195], v[86:89]
	v_mfma_f32_16x16x32_bf16 v[86:89], v[164:167], v[196:199], v[86:89]
	v_mfma_f32_16x16x32_bf16 v[82:85], v[168:171], v[192:195], v[82:85]
	v_mfma_f32_16x16x32_bf16 v[82:85], v[172:175], v[196:199], v[82:85]
	v_mfma_f32_16x16x32_bf16 v[66:69], v[168:171], v[200:203], v[66:69]
	v_mfma_f32_16x16x32_bf16 v[66:69], v[172:175], v[204:207], v[66:69]
	v_mfma_f32_16x16x32_bf16 v[70:73], v[160:163], v[200:203], v[70:73]
	v_mfma_f32_16x16x32_bf16 v[70:73], v[164:167], v[204:207], v[70:73]
	v_mfma_f32_16x16x32_bf16 v[74:77], v[152:155], v[200:203], v[74:77]
	v_mfma_f32_16x16x32_bf16 v[74:77], v[156:159], v[204:207], v[74:77]
	v_mfma_f32_16x16x32_bf16 v[78:81], v[140:143], v[200:203], v[78:81]
	v_mfma_f32_16x16x32_bf16 v[78:81], v[148:151], v[204:207], v[78:81]
	s_setprio 0
	s_barrier
	s_mov_b32 m0, s46
	s_add_i32 s76, s75, 0x80
	ds_read_b128 v[176:179], v136 offset:49152
	ds_read_b128 v[180:183], v136 offset:50176
	ds_read_b128 v[184:187], v136 offset:51200
	ds_read_b128 v[188:191], v136 offset:52224
	ds_read_b128 v[192:195], v136 offset:53248
	ds_read_b128 v[196:199], v136 offset:54272
	ds_read_b128 v[200:203], v136 offset:55296
	ds_read_b128 v[204:207], v136 offset:56320
	buffer_load_dwordx4 v133, s[16:19], s76 offen lds
	s_add_i32 s76, s75, 0x200080
	s_mov_b32 m0, s47
	s_add_i32 s73, s73, 0x18080
	buffer_load_dwordx4 v133, s[16:19], s76 offen lds
	s_add_i32 s76, s75, 0x400080
	s_mov_b32 m0, s50
	s_add_i32 s75, s75, 0x600080
	buffer_load_dwordx4 v133, s[16:19], s76 offen lds
	s_mov_b32 m0, s51
	s_nop 0
	buffer_load_dwordx4 v133, s[16:19], s75 offen lds
	s_mov_b32 m0, s48
	s_nop 0
	buffer_load_dwordx4 v132, s[12:15], s74 offen lds
	s_mov_b32 m0, s49
	s_nop 0
	buffer_load_dwordx4 v132, s[12:15], s73 offen lds
	s_waitcnt vmcnt(8)
	s_waitcnt lgkmcnt(0)
	s_setprio 1
	v_mfma_f32_16x16x32_bf16 v[62:65], v[140:143], v[176:179], v[62:65]
	s_barrier
	v_mfma_f32_16x16x32_bf16 v[62:65], v[148:151], v[180:183], v[62:65]
	v_mfma_f32_16x16x32_bf16 v[58:61], v[152:155], v[176:179], v[58:61]
	v_mfma_f32_16x16x32_bf16 v[58:61], v[156:159], v[180:183], v[58:61]
	v_mfma_f32_16x16x32_bf16 v[54:57], v[160:163], v[176:179], v[54:57]
	v_mfma_f32_16x16x32_bf16 v[54:57], v[164:167], v[180:183], v[54:57]
	v_mfma_f32_16x16x32_bf16 v[50:53], v[168:171], v[176:179], v[50:53]
	v_mfma_f32_16x16x32_bf16 v[50:53], v[172:175], v[180:183], v[50:53]
	v_mfma_f32_16x16x32_bf16 v[34:37], v[168:171], v[184:187], v[34:37]
	v_mfma_f32_16x16x32_bf16 v[34:37], v[172:175], v[188:191], v[34:37]
	v_mfma_f32_16x16x32_bf16 v[38:41], v[160:163], v[184:187], v[38:41]
	v_mfma_f32_16x16x32_bf16 v[38:41], v[164:167], v[188:191], v[38:41]
	v_mfma_f32_16x16x32_bf16 v[42:45], v[152:155], v[184:187], v[42:45]
	v_mfma_f32_16x16x32_bf16 v[42:45], v[156:159], v[188:191], v[42:45]
	v_mfma_f32_16x16x32_bf16 v[46:49], v[140:143], v[184:187], v[46:49]
	v_mfma_f32_16x16x32_bf16 v[46:49], v[148:151], v[188:191], v[46:49]
	v_mfma_f32_16x16x32_bf16 v[30:33], v[140:143], v[192:195], v[30:33]
	v_mfma_f32_16x16x32_bf16 v[30:33], v[148:151], v[196:199], v[30:33]
	v_mfma_f32_16x16x32_bf16 v[26:29], v[152:155], v[192:195], v[26:29]
	v_mfma_f32_16x16x32_bf16 v[26:29], v[156:159], v[196:199], v[26:29]
	v_mfma_f32_16x16x32_bf16 v[22:25], v[160:163], v[192:195], v[22:25]
	v_mfma_f32_16x16x32_bf16 v[22:25], v[164:167], v[196:199], v[22:25]
	v_mfma_f32_16x16x32_bf16 v[18:21], v[168:171], v[192:195], v[18:21]
	v_mfma_f32_16x16x32_bf16 v[18:21], v[172:175], v[196:199], v[18:21]
	v_mfma_f32_16x16x32_bf16 v[2:5], v[168:171], v[200:203], v[2:5]
	v_mfma_f32_16x16x32_bf16 v[2:5], v[172:175], v[204:207], v[2:5]
	v_mfma_f32_16x16x32_bf16 v[6:9], v[160:163], v[200:203], v[6:9]
	v_mfma_f32_16x16x32_bf16 v[6:9], v[164:167], v[204:207], v[6:9]
	v_mfma_f32_16x16x32_bf16 v[10:13], v[152:155], v[200:203], v[10:13]
	v_mfma_f32_16x16x32_bf16 v[10:13], v[156:159], v[204:207], v[10:13]
	v_mfma_f32_16x16x32_bf16 v[14:17], v[140:143], v[200:203], v[14:17]
	v_mfma_f32_16x16x32_bf16 v[14:17], v[148:151], v[204:207], v[14:17]
	s_setprio 0
	s_barrier
	s_add_i32 s72, s72, 2
	s_addk_i32 s70, 0x100
	s_addk_i32 s71, 0x100
	s_cmp_ge_i32 s72, s21
	s_cbranch_scc0 .LBB0_1035

.LBB0_1050:
	ds_read_b128 v[132:135], v142
	ds_read_b128 v[136:139], v142 offset:1024
	ds_read_b128 v[148:151], v142 offset:2048
	ds_read_b128 v[152:155], v142 offset:3072
	ds_read_b128 v[156:159], v143
	ds_read_b128 v[160:163], v143 offset:1024
	ds_read_b128 v[164:167], v143 offset:2048
	ds_read_b128 v[168:171], v143 offset:3072
	s_add_i32 s18, s61, 0xfff40080
	s_cmp_eq_u32 s54, s62
	s_cselect_b32 s64, s35, s18
	s_add_i32 s63, s64, 0x80
	s_add_i32 s18, s61, 0xfffc0000
	s_mov_b32 m0, s55
	ds_read_b128 v[172:175], v144
	ds_read_b128 v[176:179], v144 offset:1024
	ds_read_b128 v[180:183], v144 offset:2048
	ds_read_b128 v[184:187], v144 offset:3072
	ds_read_b128 v[188:191], v144 offset:4096
	ds_read_b128 v[192:195], v144 offset:5120
	ds_read_b128 v[196:199], v144 offset:6144
	ds_read_b128 v[200:203], v144 offset:7168
	buffer_load_dwordx4 v140, s[12:15], s18 offen lds
	s_mov_b32 m0, s56
	s_nop 0
	buffer_load_dwordx4 v140, s[12:15], s61 offen lds
	s_waitcnt vmcnt(8)
	s_waitcnt lgkmcnt(0)
	s_setprio 1
	v_mfma_f32_16x16x32_bf16 v[126:129], v[132:135], v[172:175], v[126:129]
	s_barrier
	v_mfma_f32_16x16x32_bf16 v[126:129], v[136:139], v[176:179], v[126:129]
	v_mfma_f32_16x16x32_bf16 v[122:125], v[148:151], v[172:175], v[122:125]
	v_mfma_f32_16x16x32_bf16 v[122:125], v[152:155], v[176:179], v[122:125]
	v_mfma_f32_16x16x32_bf16 v[118:121], v[156:159], v[172:175], v[118:121]
	v_mfma_f32_16x16x32_bf16 v[118:121], v[160:163], v[176:179], v[118:121]
	v_mfma_f32_16x16x32_bf16 v[114:117], v[164:167], v[172:175], v[114:117]
	v_mfma_f32_16x16x32_bf16 v[114:117], v[168:171], v[176:179], v[114:117]
	v_mfma_f32_16x16x32_bf16 v[98:101], v[164:167], v[180:183], v[98:101]
	v_mfma_f32_16x16x32_bf16 v[98:101], v[168:171], v[184:187], v[98:101]
	v_mfma_f32_16x16x32_bf16 v[102:105], v[156:159], v[180:183], v[102:105]
	v_mfma_f32_16x16x32_bf16 v[102:105], v[160:163], v[184:187], v[102:105]
	v_mfma_f32_16x16x32_bf16 v[106:109], v[148:151], v[180:183], v[106:109]
	v_mfma_f32_16x16x32_bf16 v[106:109], v[152:155], v[184:187], v[106:109]
	v_mfma_f32_16x16x32_bf16 v[110:113], v[132:135], v[180:183], v[110:113]
	v_mfma_f32_16x16x32_bf16 v[110:113], v[136:139], v[184:187], v[110:113]
	v_mfma_f32_16x16x32_bf16 v[94:97], v[132:135], v[188:191], v[94:97]
	v_mfma_f32_16x16x32_bf16 v[94:97], v[136:139], v[192:195], v[94:97]
	v_mfma_f32_16x16x32_bf16 v[90:93], v[148:151], v[188:191], v[90:93]
	v_mfma_f32_16x16x32_bf16 v[90:93], v[152:155], v[192:195], v[90:93]
	v_mfma_f32_16x16x32_bf16 v[86:89], v[156:159], v[188:191], v[86:89]
	v_mfma_f32_16x16x32_bf16 v[86:89], v[160:163], v[192:195], v[86:89]
	v_mfma_f32_16x16x32_bf16 v[82:85], v[164:167], v[188:191], v[82:85]
	v_mfma_f32_16x16x32_bf16 v[82:85], v[168:171], v[192:195], v[82:85]
	v_mfma_f32_16x16x32_bf16 v[66:69], v[164:167], v[196:199], v[66:69]
	v_mfma_f32_16x16x32_bf16 v[66:69], v[168:171], v[200:203], v[66:69]
	v_mfma_f32_16x16x32_bf16 v[70:73], v[156:159], v[196:199], v[70:73]
	v_mfma_f32_16x16x32_bf16 v[70:73], v[160:163], v[200:203], v[70:73]
	v_mfma_f32_16x16x32_bf16 v[74:77], v[148:151], v[196:199], v[74:77]
	v_mfma_f32_16x16x32_bf16 v[74:77], v[152:155], v[200:203], v[74:77]
	v_mfma_f32_16x16x32_bf16 v[78:81], v[132:135], v[196:199], v[78:81]
	v_mfma_f32_16x16x32_bf16 v[78:81], v[136:139], v[200:203], v[78:81]
	s_setprio 0
	s_barrier
	s_mov_b32 m0, s25
	s_mov_b32 s18, s14
	s_mov_b32 s19, s15
	ds_read_b128 v[172:175], v144 offset:16384
	ds_read_b128 v[176:179], v144 offset:17408
	ds_read_b128 v[180:183], v144 offset:18432
	ds_read_b128 v[184:187], v144 offset:19456
	ds_read_b128 v[188:191], v144 offset:20480
	ds_read_b128 v[192:195], v144 offset:21504
	ds_read_b128 v[196:199], v144 offset:22528
	ds_read_b128 v[200:203], v144 offset:23552
	buffer_load_dwordx4 v141, s[16:19], s64 offen lds
	s_add_i32 s65, s64, 0x40000
	s_mov_b32 m0, s27
	s_add_i32 s66, s64, 0x80000
	buffer_load_dwordx4 v141, s[16:19], s65 offen lds
	s_mov_b32 m0, s30
	s_add_i32 s67, s64, 0xc0000
	buffer_load_dwordx4 v141, s[16:19], s66 offen lds
	s_mov_b32 m0, s31
	s_nop 0
	buffer_load_dwordx4 v141, s[16:19], s67 offen lds
	s_mov_b32 m0, s21
	s_nop 0
	buffer_load_dwordx4 v140, s[12:15], s64 offen lds
	s_mov_b32 m0, s38
	s_nop 0
	buffer_load_dwordx4 v140, s[12:15], s65 offen lds
	s_waitcnt vmcnt(8)
	s_waitcnt lgkmcnt(0)
	s_setprio 1
	v_mfma_f32_16x16x32_bf16 v[62:65], v[132:135], v[172:175], v[62:65]
	s_barrier
	v_mfma_f32_16x16x32_bf16 v[62:65], v[136:139], v[176:179], v[62:65]
	v_mfma_f32_16x16x32_bf16 v[58:61], v[148:151], v[172:175], v[58:61]
	v_mfma_f32_16x16x32_bf16 v[58:61], v[152:155], v[176:179], v[58:61]
	v_mfma_f32_16x16x32_bf16 v[54:57], v[156:159], v[172:175], v[54:57]
	v_mfma_f32_16x16x32_bf16 v[54:57], v[160:163], v[176:179], v[54:57]
	v_mfma_f32_16x16x32_bf16 v[50:53], v[164:167], v[172:175], v[50:53]
	v_mfma_f32_16x16x32_bf16 v[50:53], v[168:171], v[176:179], v[50:53]
	v_mfma_f32_16x16x32_bf16 v[34:37], v[164:167], v[180:183], v[34:37]
	v_mfma_f32_16x16x32_bf16 v[34:37], v[168:171], v[184:187], v[34:37]
	v_mfma_f32_16x16x32_bf16 v[38:41], v[156:159], v[180:183], v[38:41]
	v_mfma_f32_16x16x32_bf16 v[38:41], v[160:163], v[184:187], v[38:41]
	v_mfma_f32_16x16x32_bf16 v[42:45], v[148:151], v[180:183], v[42:45]
	v_mfma_f32_16x16x32_bf16 v[42:45], v[152:155], v[184:187], v[42:45]
	v_mfma_f32_16x16x32_bf16 v[46:49], v[132:135], v[180:183], v[46:49]
	v_mfma_f32_16x16x32_bf16 v[46:49], v[136:139], v[184:187], v[46:49]
	v_mfma_f32_16x16x32_bf16 v[30:33], v[132:135], v[188:191], v[30:33]
	v_mfma_f32_16x16x32_bf16 v[30:33], v[136:139], v[192:195], v[30:33]
	v_mfma_f32_16x16x32_bf16 v[26:29], v[148:151], v[188:191], v[26:29]
	v_mfma_f32_16x16x32_bf16 v[26:29], v[152:155], v[192:195], v[26:29]
	v_mfma_f32_16x16x32_bf16 v[22:25], v[156:159], v[188:191], v[22:25]
	v_mfma_f32_16x16x32_bf16 v[22:25], v[160:163], v[192:195], v[22:25]
	v_mfma_f32_16x16x32_bf16 v[18:21], v[164:167], v[188:191], v[18:21]
	v_mfma_f32_16x16x32_bf16 v[18:21], v[168:171], v[192:195], v[18:21]
	v_mfma_f32_16x16x32_bf16 v[2:5], v[164:167], v[196:199], v[2:5]
	v_mfma_f32_16x16x32_bf16 v[2:5], v[168:171], v[200:203], v[2:5]
	v_mfma_f32_16x16x32_bf16 v[6:9], v[156:159], v[196:199], v[6:9]
	v_mfma_f32_16x16x32_bf16 v[6:9], v[160:163], v[200:203], v[6:9]
	v_mfma_f32_16x16x32_bf16 v[10:13], v[148:151], v[196:199], v[10:13]
	v_mfma_f32_16x16x32_bf16 v[10:13], v[152:155], v[200:203], v[10:13]
	v_mfma_f32_16x16x32_bf16 v[14:17], v[132:135], v[196:199], v[14:17]
	v_mfma_f32_16x16x32_bf16 v[14:17], v[136:139], v[200:203], v[14:17]
	s_setprio 0
	s_barrier
	ds_read_b128 v[132:135], v145
	ds_read_b128 v[136:139], v145 offset:1024
	ds_read_b128 v[148:151], v145 offset:2048
	ds_read_b128 v[152:155], v145 offset:3072
	ds_read_b128 v[156:159], v147
	ds_read_b128 v[160:163], v147 offset:1024
	ds_read_b128 v[164:167], v147 offset:2048
	ds_read_b128 v[168:171], v147 offset:3072
	s_mov_b32 m0, s39
	ds_read_b128 v[172:175], v144 offset:32768
	ds_read_b128 v[176:179], v144 offset:33792
	ds_read_b128 v[180:183], v144 offset:34816
	ds_read_b128 v[184:187], v144 offset:35840
	ds_read_b128 v[188:191], v144 offset:36864
	ds_read_b128 v[192:195], v144 offset:37888
	ds_read_b128 v[196:199], v144 offset:38912
	ds_read_b128 v[200:203], v144 offset:39936
	buffer_load_dwordx4 v140, s[12:15], s66 offen lds
	s_mov_b32 m0, s40
	s_nop 0
	buffer_load_dwordx4 v140, s[12:15], s67 offen lds
	s_waitcnt vmcnt(8)
	s_waitcnt lgkmcnt(0)
	s_setprio 1
	v_mfma_f32_16x16x32_bf16 v[126:129], v[132:135], v[172:175], v[126:129]
	s_barrier
	v_mfma_f32_16x16x32_bf16 v[126:129], v[136:139], v[176:179], v[126:129]
	v_mfma_f32_16x16x32_bf16 v[122:125], v[148:151], v[172:175], v[122:125]
	v_mfma_f32_16x16x32_bf16 v[122:125], v[152:155], v[176:179], v[122:125]
	v_mfma_f32_16x16x32_bf16 v[118:121], v[156:159], v[172:175], v[118:121]
	v_mfma_f32_16x16x32_bf16 v[118:121], v[160:163], v[176:179], v[118:121]
	v_mfma_f32_16x16x32_bf16 v[114:117], v[164:167], v[172:175], v[114:117]
	v_mfma_f32_16x16x32_bf16 v[114:117], v[168:171], v[176:179], v[114:117]
	v_mfma_f32_16x16x32_bf16 v[98:101], v[164:167], v[180:183], v[98:101]
	v_mfma_f32_16x16x32_bf16 v[98:101], v[168:171], v[184:187], v[98:101]
	v_mfma_f32_16x16x32_bf16 v[102:105], v[156:159], v[180:183], v[102:105]
	v_mfma_f32_16x16x32_bf16 v[102:105], v[160:163], v[184:187], v[102:105]
	v_mfma_f32_16x16x32_bf16 v[106:109], v[148:151], v[180:183], v[106:109]
	v_mfma_f32_16x16x32_bf16 v[106:109], v[152:155], v[184:187], v[106:109]
	v_mfma_f32_16x16x32_bf16 v[110:113], v[132:135], v[180:183], v[110:113]
	v_mfma_f32_16x16x32_bf16 v[110:113], v[136:139], v[184:187], v[110:113]
	v_mfma_f32_16x16x32_bf16 v[94:97], v[132:135], v[188:191], v[94:97]
	v_mfma_f32_16x16x32_bf16 v[94:97], v[136:139], v[192:195], v[94:97]
	v_mfma_f32_16x16x32_bf16 v[90:93], v[148:151], v[188:191], v[90:93]
	v_mfma_f32_16x16x32_bf16 v[90:93], v[152:155], v[192:195], v[90:93]
	v_mfma_f32_16x16x32_bf16 v[86:89], v[156:159], v[188:191], v[86:89]
	v_mfma_f32_16x16x32_bf16 v[86:89], v[160:163], v[192:195], v[86:89]
	v_mfma_f32_16x16x32_bf16 v[82:85], v[164:167], v[188:191], v[82:85]
	v_mfma_f32_16x16x32_bf16 v[82:85], v[168:171], v[192:195], v[82:85]
	v_mfma_f32_16x16x32_bf16 v[66:69], v[164:167], v[196:199], v[66:69]
	v_mfma_f32_16x16x32_bf16 v[66:69], v[168:171], v[200:203], v[66:69]
	v_mfma_f32_16x16x32_bf16 v[70:73], v[156:159], v[196:199], v[70:73]
	v_mfma_f32_16x16x32_bf16 v[70:73], v[160:163], v[200:203], v[70:73]
	v_mfma_f32_16x16x32_bf16 v[74:77], v[148:151], v[196:199], v[74:77]
	v_mfma_f32_16x16x32_bf16 v[74:77], v[152:155], v[200:203], v[74:77]
	v_mfma_f32_16x16x32_bf16 v[78:81], v[132:135], v[196:199], v[78:81]
	v_mfma_f32_16x16x32_bf16 v[78:81], v[136:139], v[200:203], v[78:81]
	s_setprio 0
	s_barrier
	s_mov_b32 m0, s48
	ds_read_b128 v[172:175], v144 offset:49152
	ds_read_b128 v[176:179], v144 offset:50176
	ds_read_b128 v[180:183], v144 offset:51200
	ds_read_b128 v[184:187], v144 offset:52224
	ds_read_b128 v[188:191], v144 offset:53248
	ds_read_b128 v[192:195], v144 offset:54272
	ds_read_b128 v[196:199], v144 offset:55296
	ds_read_b128 v[200:203], v144 offset:56320
	buffer_load_dwordx4 v141, s[16:19], s63 offen lds
	s_add_i32 s65, s64, 0x40080
	s_mov_b32 m0, s49
	s_add_i32 s66, s64, 0x80080
	buffer_load_dwordx4 v141, s[16:19], s65 offen lds
	s_mov_b32 m0, s52
	s_add_i32 s64, s64, 0xc0080
	buffer_load_dwordx4 v141, s[16:19], s66 offen lds
	s_mov_b32 m0, s53
	s_nop 0
	buffer_load_dwordx4 v141, s[16:19], s64 offen lds
	s_mov_b32 m0, s50
	s_nop 0
	buffer_load_dwordx4 v140, s[12:15], s63 offen lds
	s_mov_b32 m0, s51
	s_nop 0
	buffer_load_dwordx4 v140, s[12:15], s65 offen lds
	s_waitcnt vmcnt(8)
	s_waitcnt lgkmcnt(0)
	s_setprio 1
	v_mfma_f32_16x16x32_bf16 v[62:65], v[132:135], v[172:175], v[62:65]
	s_barrier
	v_mfma_f32_16x16x32_bf16 v[62:65], v[136:139], v[176:179], v[62:65]
	v_mfma_f32_16x16x32_bf16 v[58:61], v[148:151], v[172:175], v[58:61]
	v_mfma_f32_16x16x32_bf16 v[58:61], v[152:155], v[176:179], v[58:61]
	v_mfma_f32_16x16x32_bf16 v[54:57], v[156:159], v[172:175], v[54:57]
	v_mfma_f32_16x16x32_bf16 v[54:57], v[160:163], v[176:179], v[54:57]
	v_mfma_f32_16x16x32_bf16 v[50:53], v[164:167], v[172:175], v[50:53]
	v_mfma_f32_16x16x32_bf16 v[50:53], v[168:171], v[176:179], v[50:53]
	v_mfma_f32_16x16x32_bf16 v[34:37], v[164:167], v[180:183], v[34:37]
	v_mfma_f32_16x16x32_bf16 v[34:37], v[168:171], v[184:187], v[34:37]
	v_mfma_f32_16x16x32_bf16 v[38:41], v[156:159], v[180:183], v[38:41]
	v_mfma_f32_16x16x32_bf16 v[38:41], v[160:163], v[184:187], v[38:41]
	v_mfma_f32_16x16x32_bf16 v[42:45], v[148:151], v[180:183], v[42:45]
	v_mfma_f32_16x16x32_bf16 v[42:45], v[152:155], v[184:187], v[42:45]
	v_mfma_f32_16x16x32_bf16 v[46:49], v[132:135], v[180:183], v[46:49]
	v_mfma_f32_16x16x32_bf16 v[46:49], v[136:139], v[184:187], v[46:49]
	v_mfma_f32_16x16x32_bf16 v[30:33], v[132:135], v[188:191], v[30:33]
	v_mfma_f32_16x16x32_bf16 v[30:33], v[136:139], v[192:195], v[30:33]
	v_mfma_f32_16x16x32_bf16 v[26:29], v[148:151], v[188:191], v[26:29]
	v_mfma_f32_16x16x32_bf16 v[26:29], v[152:155], v[192:195], v[26:29]
	v_mfma_f32_16x16x32_bf16 v[22:25], v[156:159], v[188:191], v[22:25]
	v_mfma_f32_16x16x32_bf16 v[22:25], v[160:163], v[192:195], v[22:25]
	v_mfma_f32_16x16x32_bf16 v[18:21], v[164:167], v[188:191], v[18:21]
	v_mfma_f32_16x16x32_bf16 v[18:21], v[168:171], v[192:195], v[18:21]
	v_mfma_f32_16x16x32_bf16 v[2:5], v[164:167], v[196:199], v[2:5]
	v_mfma_f32_16x16x32_bf16 v[2:5], v[168:171], v[200:203], v[2:5]
	v_mfma_f32_16x16x32_bf16 v[6:9], v[156:159], v[196:199], v[6:9]
	v_mfma_f32_16x16x32_bf16 v[6:9], v[160:163], v[200:203], v[6:9]
	v_mfma_f32_16x16x32_bf16 v[10:13], v[148:151], v[196:199], v[10:13]
	v_mfma_f32_16x16x32_bf16 v[10:13], v[152:155], v[200:203], v[10:13]
	v_mfma_f32_16x16x32_bf16 v[14:17], v[132:135], v[196:199], v[14:17]
	v_mfma_f32_16x16x32_bf16 v[14:17], v[136:139], v[200:203], v[14:17]
	s_setprio 0
	s_barrier
	s_add_i32 s62, s62, 2
	s_addk_i32 s61, 0x100
	s_cmp_ge_i32 s62, s3
	s_cbranch_scc0 .LBB0_1050

.LBB0_1181:
	v_add_u32_e32 v2, 0x10000, v232
	ds_read_b128 v[134:137], v2
	ds_read_b128 v[138:141], v2 offset:1024
	ds_read_b128 v[142:145], v2 offset:2048
	ds_read_b128 v[146:149], v2 offset:3072
	v_add_u32_e32 v2, 0x14000, v232
	ds_read_b128 v[150:153], v2
	ds_read_b128 v[154:157], v2 offset:1024
	ds_read_b128 v[158:161], v2 offset:2048
	ds_read_b128 v[162:165], v2 offset:3072
	s_add_i32 s50, s47, s90
	s_and_b64 s[18:19], exec, s[18:19]
	s_cselect_b32 s51, s88, s50
	s_add_i32 s50, s92, 0x80
	s_or_b32 s52, s51, 0x80
	s_add_i32 s18, s89, s93
	s_add_i32 s94, s94, 0x1bfffc80
	s_cmp_lt_u32 s91, 8
	s_cselect_b32 s18, s18, s94
	s_mov_b32 m0, s74
	s_add_i32 s19, s18, 0x80000
	ds_read_b128 v[166:169], v233
	ds_read_b128 v[170:173], v233 offset:1024
	ds_read_b128 v[174:177], v233 offset:2048
	ds_read_b128 v[178:181], v233 offset:3072
	ds_read_b128 v[182:185], v233 offset:4096
	ds_read_b128 v[186:189], v233 offset:5120
	ds_read_b128 v[190:193], v233 offset:6144
	ds_read_b128 v[194:197], v233 offset:7168
	buffer_load_dwordx4 v230, s[12:15], s19 offen lds
	s_add_i32 s18, s18, 0xc0000
	s_mov_b32 m0, s75
	s_nop 0
	buffer_load_dwordx4 v230, s[12:15], s18 offen lds
	s_waitcnt vmcnt(8)
	s_waitcnt lgkmcnt(0)
	s_setprio 1
	v_mfma_f32_16x16x32_bf16 v[130:133], v[134:137], v[166:169], v[130:133]
	s_barrier
	v_mfma_f32_16x16x32_bf16 v[130:133], v[138:141], v[170:173], v[130:133]
	v_mfma_f32_16x16x32_bf16 v[126:129], v[142:145], v[166:169], v[126:129]
	v_mfma_f32_16x16x32_bf16 v[126:129], v[146:149], v[170:173], v[126:129]
	v_mfma_f32_16x16x32_bf16 v[122:125], v[150:153], v[166:169], v[122:125]
	v_mfma_f32_16x16x32_bf16 v[122:125], v[154:157], v[170:173], v[122:125]
	v_mfma_f32_16x16x32_bf16 v[118:121], v[158:161], v[166:169], v[118:121]
	v_mfma_f32_16x16x32_bf16 v[118:121], v[162:165], v[170:173], v[118:121]
	v_mfma_f32_16x16x32_bf16 v[102:105], v[158:161], v[174:177], v[102:105]
	v_mfma_f32_16x16x32_bf16 v[102:105], v[162:165], v[178:181], v[102:105]
	v_mfma_f32_16x16x32_bf16 v[106:109], v[150:153], v[174:177], v[106:109]
	v_mfma_f32_16x16x32_bf16 v[106:109], v[154:157], v[178:181], v[106:109]
	v_mfma_f32_16x16x32_bf16 v[110:113], v[142:145], v[174:177], v[110:113]
	v_mfma_f32_16x16x32_bf16 v[110:113], v[146:149], v[178:181], v[110:113]
	v_mfma_f32_16x16x32_bf16 v[114:117], v[134:137], v[174:177], v[114:117]
	v_mfma_f32_16x16x32_bf16 v[114:117], v[138:141], v[178:181], v[114:117]
	v_mfma_f32_16x16x32_bf16 v[98:101], v[134:137], v[182:185], v[98:101]
	v_mfma_f32_16x16x32_bf16 v[98:101], v[138:141], v[186:189], v[98:101]
	v_mfma_f32_16x16x32_bf16 v[94:97], v[142:145], v[182:185], v[94:97]
	v_mfma_f32_16x16x32_bf16 v[94:97], v[146:149], v[186:189], v[94:97]
	v_mfma_f32_16x16x32_bf16 v[90:93], v[150:153], v[182:185], v[90:93]
	v_mfma_f32_16x16x32_bf16 v[90:93], v[154:157], v[186:189], v[90:93]
	v_mfma_f32_16x16x32_bf16 v[86:89], v[158:161], v[182:185], v[86:89]
	v_mfma_f32_16x16x32_bf16 v[86:89], v[162:165], v[186:189], v[86:89]
	v_mfma_f32_16x16x32_bf16 v[70:73], v[158:161], v[190:193], v[70:73]
	v_mfma_f32_16x16x32_bf16 v[70:73], v[162:165], v[194:197], v[70:73]
	v_mfma_f32_16x16x32_bf16 v[74:77], v[150:153], v[190:193], v[74:77]
	v_mfma_f32_16x16x32_bf16 v[74:77], v[154:157], v[194:197], v[74:77]
	v_mfma_f32_16x16x32_bf16 v[78:81], v[142:145], v[190:193], v[78:81]
	v_mfma_f32_16x16x32_bf16 v[78:81], v[146:149], v[194:197], v[78:81]
	v_mfma_f32_16x16x32_bf16 v[82:85], v[134:137], v[190:193], v[82:85]
	v_mfma_f32_16x16x32_bf16 v[82:85], v[138:141], v[194:197], v[82:85]
	s_setprio 0
	s_barrier
	s_mov_b32 m0, s27
	s_mov_b32 s18, s14
	s_mov_b32 s19, s15
	ds_read_b128 v[166:169], v233 offset:16384
	ds_read_b128 v[170:173], v233 offset:17408
	ds_read_b128 v[174:177], v233 offset:18432
	ds_read_b128 v[178:181], v233 offset:19456
	ds_read_b128 v[182:185], v233 offset:20480
	ds_read_b128 v[186:189], v233 offset:21504
	ds_read_b128 v[190:193], v233 offset:22528
	ds_read_b128 v[194:197], v233 offset:23552
	buffer_load_dwordx4 v231, s[16:19], s51 offen lds
	s_add_i32 s53, s51, 0x18000
	s_mov_b32 m0, s30
	s_nop 0
	buffer_load_dwordx4 v231, s[16:19], s53 offen lds
	s_add_i32 s53, s51, 0x30000
	s_mov_b32 m0, s31
	s_nop 0
	buffer_load_dwordx4 v231, s[16:19], s53 offen lds
	s_add_i32 s53, s51, 0x48000
	s_mov_b32 m0, s54
	s_nop 0
	buffer_load_dwordx4 v231, s[16:19], s53 offen lds
	s_mov_b32 m0, s25
	s_add_i32 s53, s92, 0x40000
	buffer_load_dwordx4 v230, s[12:15], s92 offen lds
	s_mov_b32 m0, s55
	s_nop 0
	buffer_load_dwordx4 v230, s[12:15], s53 offen lds
	s_waitcnt vmcnt(8)
	s_waitcnt lgkmcnt(0)
	s_setprio 1
	v_mfma_f32_16x16x32_bf16 v[66:69], v[134:137], v[166:169], v[66:69]
	s_barrier
	v_mfma_f32_16x16x32_bf16 v[62:65], v[142:145], v[166:169], v[62:65]
	v_mfma_f32_16x16x32_bf16 v[50:53], v[134:137], v[174:177], v[50:53]
	v_mfma_f32_16x16x32_bf16 v[46:49], v[142:145], v[174:177], v[46:49]
	v_mfma_f32_16x16x32_bf16 v[34:37], v[134:137], v[182:185], v[34:37]
	v_mfma_f32_16x16x32_bf16 v[30:33], v[142:145], v[182:185], v[30:33]
	v_mfma_f32_16x16x32_bf16 v[18:21], v[134:137], v[190:193], v[18:21]
	v_mfma_f32_16x16x32_bf16 v[14:17], v[142:145], v[190:193], v[14:17]
	v_mfma_f32_16x16x32_bf16 v[58:61], v[150:153], v[166:169], v[58:61]
	v_mfma_f32_16x16x32_bf16 v[54:57], v[158:161], v[166:169], v[54:57]
	v_mfma_f32_16x16x32_bf16 v[42:45], v[150:153], v[174:177], v[42:45]
	v_mfma_f32_16x16x32_bf16 v[38:41], v[158:161], v[174:177], v[38:41]
	v_mfma_f32_16x16x32_bf16 v[26:29], v[150:153], v[182:185], v[26:29]
	v_mfma_f32_16x16x32_bf16 v[22:25], v[158:161], v[182:185], v[22:25]
	v_mfma_f32_16x16x32_bf16 v[10:13], v[150:153], v[190:193], v[10:13]
	v_mfma_f32_16x16x32_bf16 v[4:7], v[158:161], v[190:193], v[6:9]
	v_mfma_f32_16x16x32_bf16 v[66:69], v[138:141], v[170:173], v[66:69]
	v_mfma_f32_16x16x32_bf16 v[62:65], v[146:149], v[170:173], v[62:65]
	v_mfma_f32_16x16x32_bf16 v[50:53], v[138:141], v[178:181], v[50:53]
	v_mfma_f32_16x16x32_bf16 v[46:49], v[146:149], v[178:181], v[46:49]
	v_mfma_f32_16x16x32_bf16 v[34:37], v[138:141], v[186:189], v[34:37]
	v_mfma_f32_16x16x32_bf16 v[30:33], v[146:149], v[186:189], v[30:33]
	v_mfma_f32_16x16x32_bf16 v[18:21], v[138:141], v[194:197], v[18:21]
	v_mfma_f32_16x16x32_bf16 v[14:17], v[146:149], v[194:197], v[14:17]
	v_mfma_f32_16x16x32_bf16 v[58:61], v[154:157], v[170:173], v[58:61]
	v_mfma_f32_16x16x32_bf16 v[54:57], v[162:165], v[170:173], v[54:57]
	v_mfma_f32_16x16x32_bf16 v[42:45], v[154:157], v[178:181], v[42:45]
	v_mfma_f32_16x16x32_bf16 v[38:41], v[162:165], v[178:181], v[38:41]
	v_mfma_f32_16x16x32_bf16 v[26:29], v[154:157], v[186:189], v[26:29]
	v_mfma_f32_16x16x32_bf16 v[22:25], v[162:165], v[186:189], v[22:25]
	v_mfma_f32_16x16x32_bf16 v[10:13], v[154:157], v[194:197], v[10:13]
	v_mfma_f32_16x16x32_bf16 v[4:7], v[162:165], v[194:197], v[4:7]
	s_setprio 0
	s_barrier
	v_add_u32_e32 v2, 0x18000, v232
	ds_read_b128 v[134:137], v2
	ds_read_b128 v[138:141], v2 offset:1024
	ds_read_b128 v[142:145], v2 offset:2048
	ds_read_b128 v[146:149], v2 offset:3072
	v_add_u32_e32 v2, 0x1c000, v232
	ds_read_b128 v[150:153], v2
	ds_read_b128 v[154:157], v2 offset:1024
	ds_read_b128 v[158:161], v2 offset:2048
	ds_read_b128 v[162:165], v2 offset:3072
	s_mov_b32 m0, s56
	s_add_i32 s53, s92, 0x80000
	ds_read_b128 v[166:169], v233 offset:32768
	ds_read_b128 v[170:173], v233 offset:33792
	ds_read_b128 v[174:177], v233 offset:34816
	ds_read_b128 v[178:181], v233 offset:35840
	ds_read_b128 v[182:185], v233 offset:36864
	ds_read_b128 v[186:189], v233 offset:37888
	ds_read_b128 v[190:193], v233 offset:38912
	ds_read_b128 v[194:197], v233 offset:39936
	buffer_load_dwordx4 v230, s[12:15], s53 offen lds
	s_add_i32 s53, s92, 0xc0000
	s_mov_b32 m0, s57
	s_nop 0
	buffer_load_dwordx4 v230, s[12:15], s53 offen lds
	s_waitcnt vmcnt(8)
	s_waitcnt lgkmcnt(0)
	s_setprio 1
	v_mfma_f32_16x16x32_bf16 v[130:133], v[134:137], v[166:169], v[130:133]
	s_barrier
	v_mfma_f32_16x16x32_bf16 v[130:133], v[138:141], v[170:173], v[130:133]
	v_mfma_f32_16x16x32_bf16 v[126:129], v[142:145], v[166:169], v[126:129]
	v_mfma_f32_16x16x32_bf16 v[126:129], v[146:149], v[170:173], v[126:129]
	v_mfma_f32_16x16x32_bf16 v[122:125], v[150:153], v[166:169], v[122:125]
	v_mfma_f32_16x16x32_bf16 v[122:125], v[154:157], v[170:173], v[122:125]
	v_mfma_f32_16x16x32_bf16 v[118:121], v[158:161], v[166:169], v[118:121]
	v_mfma_f32_16x16x32_bf16 v[118:121], v[162:165], v[170:173], v[118:121]
	v_mfma_f32_16x16x32_bf16 v[102:105], v[158:161], v[174:177], v[102:105]
	v_mfma_f32_16x16x32_bf16 v[102:105], v[162:165], v[178:181], v[102:105]
	v_mfma_f32_16x16x32_bf16 v[106:109], v[150:153], v[174:177], v[106:109]
	v_mfma_f32_16x16x32_bf16 v[106:109], v[154:157], v[178:181], v[106:109]
	v_mfma_f32_16x16x32_bf16 v[110:113], v[142:145], v[174:177], v[110:113]
	v_mfma_f32_16x16x32_bf16 v[110:113], v[146:149], v[178:181], v[110:113]
	v_mfma_f32_16x16x32_bf16 v[114:117], v[134:137], v[174:177], v[114:117]
	v_mfma_f32_16x16x32_bf16 v[114:117], v[138:141], v[178:181], v[114:117]
	v_mfma_f32_16x16x32_bf16 v[98:101], v[134:137], v[182:185], v[98:101]
	v_mfma_f32_16x16x32_bf16 v[98:101], v[138:141], v[186:189], v[98:101]
	v_mfma_f32_16x16x32_bf16 v[94:97], v[142:145], v[182:185], v[94:97]
	v_mfma_f32_16x16x32_bf16 v[94:97], v[146:149], v[186:189], v[94:97]
	v_mfma_f32_16x16x32_bf16 v[90:93], v[150:153], v[182:185], v[90:93]
	v_mfma_f32_16x16x32_bf16 v[90:93], v[154:157], v[186:189], v[90:93]
	v_mfma_f32_16x16x32_bf16 v[86:89], v[158:161], v[182:185], v[86:89]
	v_mfma_f32_16x16x32_bf16 v[86:89], v[162:165], v[186:189], v[86:89]
	v_mfma_f32_16x16x32_bf16 v[70:73], v[158:161], v[190:193], v[70:73]
	v_mfma_f32_16x16x32_bf16 v[70:73], v[162:165], v[194:197], v[70:73]
	v_mfma_f32_16x16x32_bf16 v[74:77], v[150:153], v[190:193], v[74:77]
	v_mfma_f32_16x16x32_bf16 v[74:77], v[154:157], v[194:197], v[74:77]
	v_mfma_f32_16x16x32_bf16 v[78:81], v[142:145], v[190:193], v[78:81]
	v_mfma_f32_16x16x32_bf16 v[78:81], v[146:149], v[194:197], v[78:81]
	v_mfma_f32_16x16x32_bf16 v[82:85], v[134:137], v[190:193], v[82:85]
	v_mfma_f32_16x16x32_bf16 v[82:85], v[138:141], v[194:197], v[82:85]
	s_setprio 0
	s_barrier
	s_mov_b32 m0, s64
	ds_read_b128 v[166:169], v233 offset:49152
	ds_read_b128 v[170:173], v233 offset:50176
	ds_read_b128 v[174:177], v233 offset:51200
	ds_read_b128 v[178:181], v233 offset:52224
	ds_read_b128 v[182:185], v233 offset:53248
	ds_read_b128 v[186:189], v233 offset:54272
	ds_read_b128 v[190:193], v233 offset:55296
	ds_read_b128 v[194:197], v233 offset:56320
	buffer_load_dwordx4 v231, s[16:19], s52 offen lds
	s_add_i32 s52, s51, 0x18080
	s_mov_b32 m0, s65
	s_nop 0
	buffer_load_dwordx4 v231, s[16:19], s52 offen lds
	s_add_i32 s52, s51, 0x30080
	s_mov_b32 m0, s68
	s_add_i32 s51, s51, 0x48080
	buffer_load_dwordx4 v231, s[16:19], s52 offen lds
	s_mov_b32 m0, s69
	s_nop 0
	buffer_load_dwordx4 v231, s[16:19], s51 offen lds
	s_mov_b32 m0, s66
	s_add_i32 s18, s92, 0x40080
	buffer_load_dwordx4 v230, s[12:15], s50 offen lds
	s_mov_b32 m0, s67
	s_nop 0
	buffer_load_dwordx4 v230, s[12:15], s18 offen lds
	s_waitcnt vmcnt(8)
	s_waitcnt lgkmcnt(0)
	s_setprio 1
	v_mfma_f32_16x16x32_bf16 v[66:69], v[134:137], v[166:169], v[66:69]
	s_barrier
	v_mfma_f32_16x16x32_bf16 v[62:65], v[142:145], v[166:169], v[62:65]
	v_mfma_f32_16x16x32_bf16 v[50:53], v[134:137], v[174:177], v[50:53]
	v_mfma_f32_16x16x32_bf16 v[46:49], v[142:145], v[174:177], v[46:49]
	v_mfma_f32_16x16x32_bf16 v[34:37], v[134:137], v[182:185], v[34:37]
	v_mfma_f32_16x16x32_bf16 v[30:33], v[142:145], v[182:185], v[30:33]
	v_mfma_f32_16x16x32_bf16 v[18:21], v[134:137], v[190:193], v[18:21]
	v_mfma_f32_16x16x32_bf16 v[14:17], v[142:145], v[190:193], v[14:17]
	v_mfma_f32_16x16x32_bf16 v[58:61], v[150:153], v[166:169], v[58:61]
	v_mfma_f32_16x16x32_bf16 v[54:57], v[158:161], v[166:169], v[54:57]
	v_mfma_f32_16x16x32_bf16 v[42:45], v[150:153], v[174:177], v[42:45]
	v_mfma_f32_16x16x32_bf16 v[38:41], v[158:161], v[174:177], v[38:41]
	v_mfma_f32_16x16x32_bf16 v[26:29], v[150:153], v[182:185], v[26:29]
	v_mfma_f32_16x16x32_bf16 v[22:25], v[158:161], v[182:185], v[22:25]
	v_mfma_f32_16x16x32_bf16 v[8:11], v[150:153], v[190:193], v[10:13]
	v_mfma_f32_16x16x32_bf16 v[4:7], v[158:161], v[190:193], v[4:7]
	v_mfma_f32_16x16x32_bf16 v[66:69], v[138:141], v[170:173], v[66:69]
	v_mfma_f32_16x16x32_bf16 v[62:65], v[146:149], v[170:173], v[62:65]
	v_mfma_f32_16x16x32_bf16 v[50:53], v[138:141], v[178:181], v[50:53]
	v_mfma_f32_16x16x32_bf16 v[46:49], v[146:149], v[178:181], v[46:49]
	v_mfma_f32_16x16x32_bf16 v[34:37], v[138:141], v[186:189], v[34:37]
	v_mfma_f32_16x16x32_bf16 v[30:33], v[146:149], v[186:189], v[30:33]
	v_mfma_f32_16x16x32_bf16 v[18:21], v[138:141], v[194:197], v[18:21]
	v_mfma_f32_16x16x32_bf16 v[14:17], v[146:149], v[194:197], v[14:17]
	v_mfma_f32_16x16x32_bf16 v[58:61], v[154:157], v[170:173], v[58:61]
	v_mfma_f32_16x16x32_bf16 v[54:57], v[162:165], v[170:173], v[54:57]
	v_mfma_f32_16x16x32_bf16 v[42:45], v[154:157], v[178:181], v[42:45]
	v_mfma_f32_16x16x32_bf16 v[38:41], v[162:165], v[178:181], v[38:41]
	v_mfma_f32_16x16x32_bf16 v[26:29], v[154:157], v[186:189], v[26:29]
	v_mfma_f32_16x16x32_bf16 v[22:25], v[162:165], v[186:189], v[22:25]
	v_mfma_f32_16x16x32_bf16 v[10:13], v[154:157], v[194:197], v[8:11]
	v_mfma_f32_16x16x32_bf16 v[6:9], v[162:165], v[194:197], v[4:7]
	s_setprio 0
	s_barrier
	s_add_i32 s91, s91, 2
	s_addk_i32 s90, 0x100
	s_cmp_ge_i32 s91, s3
	s_cbranch_scc1 .LBB0_1193

.LBB0_1290:
	ds_read_b128 v[106:109], v224
	ds_read_b128 v[118:121], v224 offset:1024
	ds_read_b128 v[130:133], v224 offset:2048
	ds_read_b128 v[138:141], v224 offset:3072
	ds_read_b128 v[146:149], v225
	ds_read_b128 v[150:153], v225 offset:1024
	ds_read_b128 v[154:157], v225 offset:2048
	ds_read_b128 v[158:161], v225 offset:3072
	s_add_i32 s18, s72, 0xffe80080
	s_cmp_eq_u32 s56, s74
	s_cselect_b32 s75, s6, s18
	s_cselect_b32 s77, s7, s73
	s_or_b32 s76, s75, 0x80
	s_add_i32 s18, s72, 0xfff80000
	s_mov_b32 m0, s57
	ds_read_b128 v[162:165], v226
	ds_read_b128 v[166:169], v226 offset:1024
	ds_read_b128 v[170:173], v226 offset:2048
	ds_read_b128 v[174:177], v226 offset:3072
	ds_read_b128 v[178:181], v226 offset:4096
	ds_read_b128 v[182:185], v226 offset:5120
	ds_read_b128 v[190:193], v226 offset:6144
	ds_read_b128 v[194:197], v226 offset:7168
	buffer_load_dwordx4 v222, s[12:15], s18 offen lds
	s_mov_b32 m0, s60
	s_nop 0
	buffer_load_dwordx4 v222, s[12:15], s72 offen lds
	s_waitcnt vmcnt(8)
	s_waitcnt lgkmcnt(0)
	s_setprio 1
	v_mfma_f32_16x16x32_bf16 v[142:145], v[106:109], v[162:165], v[142:145]
	s_barrier
	v_mfma_f32_16x16x32_bf16 v[142:145], v[118:121], v[166:169], v[142:145]
	v_mfma_f32_16x16x32_bf16 v[134:137], v[130:133], v[162:165], v[134:137]
	v_mfma_f32_16x16x32_bf16 v[134:137], v[138:141], v[166:169], v[134:137]
	v_mfma_f32_16x16x32_bf16 v[126:129], v[146:149], v[162:165], v[126:129]
	v_mfma_f32_16x16x32_bf16 v[126:129], v[150:153], v[166:169], v[126:129]
	v_mfma_f32_16x16x32_bf16 v[122:125], v[154:157], v[162:165], v[122:125]
	v_mfma_f32_16x16x32_bf16 v[122:125], v[158:161], v[166:169], v[122:125]
	v_mfma_f32_16x16x32_bf16 v[98:101], v[154:157], v[170:173], v[98:101]
	v_mfma_f32_16x16x32_bf16 v[98:101], v[158:161], v[174:177], v[98:101]
	v_mfma_f32_16x16x32_bf16 v[102:105], v[146:149], v[170:173], v[102:105]
	v_mfma_f32_16x16x32_bf16 v[102:105], v[150:153], v[174:177], v[102:105]
	v_mfma_f32_16x16x32_bf16 v[110:113], v[130:133], v[170:173], v[110:113]
	v_mfma_f32_16x16x32_bf16 v[110:113], v[138:141], v[174:177], v[110:113]
	v_mfma_f32_16x16x32_bf16 v[114:117], v[106:109], v[170:173], v[114:117]
	v_mfma_f32_16x16x32_bf16 v[114:117], v[118:121], v[174:177], v[114:117]
	v_mfma_f32_16x16x32_bf16 v[94:97], v[106:109], v[178:181], v[94:97]
	v_mfma_f32_16x16x32_bf16 v[94:97], v[118:121], v[182:185], v[94:97]
	v_mfma_f32_16x16x32_bf16 v[90:93], v[130:133], v[178:181], v[90:93]
	v_mfma_f32_16x16x32_bf16 v[90:93], v[138:141], v[182:185], v[90:93]
	v_mfma_f32_16x16x32_bf16 v[86:89], v[146:149], v[178:181], v[86:89]
	v_mfma_f32_16x16x32_bf16 v[86:89], v[150:153], v[182:185], v[86:89]
	v_mfma_f32_16x16x32_bf16 v[82:85], v[154:157], v[178:181], v[82:85]
	v_mfma_f32_16x16x32_bf16 v[82:85], v[158:161], v[182:185], v[82:85]
	v_mfma_f32_16x16x32_bf16 v[66:69], v[154:157], v[190:193], v[66:69]
	v_mfma_f32_16x16x32_bf16 v[66:69], v[158:161], v[194:197], v[66:69]
	v_mfma_f32_16x16x32_bf16 v[70:73], v[146:149], v[190:193], v[70:73]
	v_mfma_f32_16x16x32_bf16 v[70:73], v[150:153], v[194:197], v[70:73]
	v_mfma_f32_16x16x32_bf16 v[74:77], v[130:133], v[190:193], v[74:77]
	v_mfma_f32_16x16x32_bf16 v[74:77], v[138:141], v[194:197], v[74:77]
	v_mfma_f32_16x16x32_bf16 v[78:81], v[106:109], v[190:193], v[78:81]
	v_mfma_f32_16x16x32_bf16 v[78:81], v[118:121], v[194:197], v[78:81]
	s_setprio 0
	s_barrier
	s_mov_b32 m0, s27
	s_mov_b32 s18, s14
	s_mov_b32 s19, s15
	ds_read_b128 v[162:165], v226 offset:16384
	ds_read_b128 v[166:169], v226 offset:17408
	ds_read_b128 v[170:173], v226 offset:18432
	ds_read_b128 v[174:177], v226 offset:19456
	ds_read_b128 v[178:181], v226 offset:20480
	ds_read_b128 v[182:185], v226 offset:21504
	ds_read_b128 v[190:193], v226 offset:22528
	ds_read_b128 v[194:197], v226 offset:23552
	buffer_load_dwordx4 v223, s[16:19], s77 offen lds
	s_add_i32 s78, s77, 0x80000
	s_mov_b32 m0, s30
	s_nop 0
	buffer_load_dwordx4 v223, s[16:19], s78 offen lds
	s_add_i32 s78, s77, 0x100000
	s_mov_b32 m0, s31
	s_nop 0
	buffer_load_dwordx4 v223, s[16:19], s78 offen lds
	s_add_i32 s78, s77, 0x180000
	s_mov_b32 m0, s41
	s_nop 0
	buffer_load_dwordx4 v223, s[16:19], s78 offen lds
	s_mov_b32 m0, s25
	s_add_i32 s78, s75, 0x80000
	buffer_load_dwordx4 v222, s[12:15], s75 offen lds
	s_mov_b32 m0, s42
	s_nop 0
	buffer_load_dwordx4 v222, s[12:15], s78 offen lds
	s_waitcnt vmcnt(8)
	s_waitcnt lgkmcnt(0)
	s_setprio 1
	v_mfma_f32_16x16x32_bf16 v[62:65], v[106:109], v[162:165], v[62:65]
	s_barrier
	v_mfma_f32_16x16x32_bf16 v[62:65], v[118:121], v[166:169], v[62:65]
	v_mfma_f32_16x16x32_bf16 v[58:61], v[130:133], v[162:165], v[58:61]
	v_mfma_f32_16x16x32_bf16 v[58:61], v[138:141], v[166:169], v[58:61]
	v_mfma_f32_16x16x32_bf16 v[54:57], v[146:149], v[162:165], v[54:57]
	v_mfma_f32_16x16x32_bf16 v[54:57], v[150:153], v[166:169], v[54:57]
	v_mfma_f32_16x16x32_bf16 v[50:53], v[154:157], v[162:165], v[50:53]
	v_mfma_f32_16x16x32_bf16 v[50:53], v[158:161], v[166:169], v[50:53]
	v_mfma_f32_16x16x32_bf16 v[34:37], v[154:157], v[170:173], v[34:37]
	v_mfma_f32_16x16x32_bf16 v[34:37], v[158:161], v[174:177], v[34:37]
	v_mfma_f32_16x16x32_bf16 v[38:41], v[146:149], v[170:173], v[38:41]
	v_mfma_f32_16x16x32_bf16 v[38:41], v[150:153], v[174:177], v[38:41]
	v_mfma_f32_16x16x32_bf16 v[42:45], v[130:133], v[170:173], v[42:45]
	v_mfma_f32_16x16x32_bf16 v[42:45], v[138:141], v[174:177], v[42:45]
	v_mfma_f32_16x16x32_bf16 v[46:49], v[106:109], v[170:173], v[46:49]
	v_mfma_f32_16x16x32_bf16 v[46:49], v[118:121], v[174:177], v[46:49]
	v_mfma_f32_16x16x32_bf16 v[30:33], v[106:109], v[178:181], v[30:33]
	v_mfma_f32_16x16x32_bf16 v[30:33], v[118:121], v[182:185], v[30:33]
	v_mfma_f32_16x16x32_bf16 v[26:29], v[130:133], v[178:181], v[26:29]
	v_mfma_f32_16x16x32_bf16 v[26:29], v[138:141], v[182:185], v[26:29]
	v_mfma_f32_16x16x32_bf16 v[22:25], v[146:149], v[178:181], v[22:25]
	v_mfma_f32_16x16x32_bf16 v[22:25], v[150:153], v[182:185], v[22:25]
	v_mfma_f32_16x16x32_bf16 v[18:21], v[154:157], v[178:181], v[18:21]
	v_mfma_f32_16x16x32_bf16 v[18:21], v[158:161], v[182:185], v[18:21]
	v_mfma_f32_16x16x32_bf16 v[2:5], v[154:157], v[190:193], v[2:5]
	v_mfma_f32_16x16x32_bf16 v[2:5], v[158:161], v[194:197], v[2:5]
	v_mfma_f32_16x16x32_bf16 v[6:9], v[146:149], v[190:193], v[6:9]
	v_mfma_f32_16x16x32_bf16 v[6:9], v[150:153], v[194:197], v[6:9]
	v_mfma_f32_16x16x32_bf16 v[10:13], v[130:133], v[190:193], v[10:13]
	v_mfma_f32_16x16x32_bf16 v[10:13], v[138:141], v[194:197], v[10:13]
	v_mfma_f32_16x16x32_bf16 v[14:17], v[106:109], v[190:193], v[14:17]
	v_mfma_f32_16x16x32_bf16 v[14:17], v[118:121], v[194:197], v[14:17]
	s_setprio 0
	s_barrier
	ds_read_b128 v[106:109], v227
	ds_read_b128 v[118:121], v227 offset:1024
	ds_read_b128 v[130:133], v227 offset:2048
	ds_read_b128 v[138:141], v227 offset:3072
	ds_read_b128 v[146:149], v228
	ds_read_b128 v[150:153], v228 offset:1024
	ds_read_b128 v[154:157], v228 offset:2048
	ds_read_b128 v[158:161], v228 offset:3072
	s_mov_b32 m0, s43
	s_add_i32 s78, s75, 0x100000
	ds_read_b128 v[162:165], v226 offset:32768
	ds_read_b128 v[166:169], v226 offset:33792
	ds_read_b128 v[170:173], v226 offset:34816
	ds_read_b128 v[174:177], v226 offset:35840
	ds_read_b128 v[178:181], v226 offset:36864
	ds_read_b128 v[182:185], v226 offset:37888
	ds_read_b128 v[190:193], v226 offset:38912
	ds_read_b128 v[194:197], v226 offset:39936
	buffer_load_dwordx4 v222, s[12:15], s78 offen lds
	s_add_i32 s78, s75, 0x180000
	s_mov_b32 m0, s44
	s_nop 0
	buffer_load_dwordx4 v222, s[12:15], s78 offen lds
	s_waitcnt vmcnt(8)
	s_waitcnt lgkmcnt(0)
	s_setprio 1
	v_mfma_f32_16x16x32_bf16 v[142:145], v[106:109], v[162:165], v[142:145]
	s_barrier
	v_mfma_f32_16x16x32_bf16 v[142:145], v[118:121], v[166:169], v[142:145]
	v_mfma_f32_16x16x32_bf16 v[134:137], v[130:133], v[162:165], v[134:137]
	v_mfma_f32_16x16x32_bf16 v[134:137], v[138:141], v[166:169], v[134:137]
	v_mfma_f32_16x16x32_bf16 v[126:129], v[146:149], v[162:165], v[126:129]
	v_mfma_f32_16x16x32_bf16 v[126:129], v[150:153], v[166:169], v[126:129]
	v_mfma_f32_16x16x32_bf16 v[122:125], v[154:157], v[162:165], v[122:125]
	v_mfma_f32_16x16x32_bf16 v[122:125], v[158:161], v[166:169], v[122:125]
	v_mfma_f32_16x16x32_bf16 v[98:101], v[154:157], v[170:173], v[98:101]
	v_mfma_f32_16x16x32_bf16 v[98:101], v[158:161], v[174:177], v[98:101]
	v_mfma_f32_16x16x32_bf16 v[102:105], v[146:149], v[170:173], v[102:105]
	v_mfma_f32_16x16x32_bf16 v[102:105], v[150:153], v[174:177], v[102:105]
	v_mfma_f32_16x16x32_bf16 v[110:113], v[130:133], v[170:173], v[110:113]
	v_mfma_f32_16x16x32_bf16 v[110:113], v[138:141], v[174:177], v[110:113]
	v_mfma_f32_16x16x32_bf16 v[114:117], v[106:109], v[170:173], v[114:117]
	v_mfma_f32_16x16x32_bf16 v[114:117], v[118:121], v[174:177], v[114:117]
	v_mfma_f32_16x16x32_bf16 v[94:97], v[106:109], v[178:181], v[94:97]
	v_mfma_f32_16x16x32_bf16 v[94:97], v[118:121], v[182:185], v[94:97]
	v_mfma_f32_16x16x32_bf16 v[90:93], v[130:133], v[178:181], v[90:93]
	v_mfma_f32_16x16x32_bf16 v[90:93], v[138:141], v[182:185], v[90:93]
	v_mfma_f32_16x16x32_bf16 v[86:89], v[146:149], v[178:181], v[86:89]
	v_mfma_f32_16x16x32_bf16 v[86:89], v[150:153], v[182:185], v[86:89]
	v_mfma_f32_16x16x32_bf16 v[82:85], v[154:157], v[178:181], v[82:85]
	v_mfma_f32_16x16x32_bf16 v[82:85], v[158:161], v[182:185], v[82:85]
	v_mfma_f32_16x16x32_bf16 v[66:69], v[154:157], v[190:193], v[66:69]
	v_mfma_f32_16x16x32_bf16 v[66:69], v[158:161], v[194:197], v[66:69]
	v_mfma_f32_16x16x32_bf16 v[70:73], v[146:149], v[190:193], v[70:73]
	v_mfma_f32_16x16x32_bf16 v[70:73], v[150:153], v[194:197], v[70:73]
	v_mfma_f32_16x16x32_bf16 v[74:77], v[130:133], v[190:193], v[74:77]
	v_mfma_f32_16x16x32_bf16 v[74:77], v[138:141], v[194:197], v[74:77]
	v_mfma_f32_16x16x32_bf16 v[78:81], v[106:109], v[190:193], v[78:81]
	v_mfma_f32_16x16x32_bf16 v[78:81], v[118:121], v[194:197], v[78:81]
	s_setprio 0
	s_barrier
	s_mov_b32 m0, s48
	s_or_b32 s78, s77, 0x80
	ds_read_b128 v[162:165], v226 offset:49152
	ds_read_b128 v[166:169], v226 offset:50176
	ds_read_b128 v[170:173], v226 offset:51200
	ds_read_b128 v[174:177], v226 offset:52224
	ds_read_b128 v[178:181], v226 offset:53248
	ds_read_b128 v[182:185], v226 offset:54272
	ds_read_b128 v[190:193], v226 offset:55296
	ds_read_b128 v[194:197], v226 offset:56320
	buffer_load_dwordx4 v223, s[16:19], s78 offen lds
	s_add_i32 s78, s77, 0x80080
	s_mov_b32 m0, s49
	s_add_i32 s75, s75, 0x80080
	buffer_load_dwordx4 v223, s[16:19], s78 offen lds
	s_add_i32 s78, s77, 0x100080
	s_mov_b32 m0, s52
	s_add_i32 s77, s77, 0x180080
	buffer_load_dwordx4 v223, s[16:19], s78 offen lds
	s_mov_b32 m0, s53
	s_nop 0
	buffer_load_dwordx4 v223, s[16:19], s77 offen lds
	s_mov_b32 m0, s50
	s_nop 0
	buffer_load_dwordx4 v222, s[12:15], s76 offen lds
	s_mov_b32 m0, s51
	s_nop 0
	buffer_load_dwordx4 v222, s[12:15], s75 offen lds
	s_waitcnt vmcnt(8)
	s_waitcnt lgkmcnt(0)
	s_setprio 1
	v_mfma_f32_16x16x32_bf16 v[62:65], v[106:109], v[162:165], v[62:65]
	s_barrier
	v_mfma_f32_16x16x32_bf16 v[62:65], v[118:121], v[166:169], v[62:65]
	v_mfma_f32_16x16x32_bf16 v[58:61], v[130:133], v[162:165], v[58:61]
	v_mfma_f32_16x16x32_bf16 v[58:61], v[138:141], v[166:169], v[58:61]
	v_mfma_f32_16x16x32_bf16 v[54:57], v[146:149], v[162:165], v[54:57]
	v_mfma_f32_16x16x32_bf16 v[54:57], v[150:153], v[166:169], v[54:57]
	v_mfma_f32_16x16x32_bf16 v[50:53], v[154:157], v[162:165], v[50:53]
	v_mfma_f32_16x16x32_bf16 v[50:53], v[158:161], v[166:169], v[50:53]
	v_mfma_f32_16x16x32_bf16 v[34:37], v[154:157], v[170:173], v[34:37]
	v_mfma_f32_16x16x32_bf16 v[34:37], v[158:161], v[174:177], v[34:37]
	v_mfma_f32_16x16x32_bf16 v[38:41], v[146:149], v[170:173], v[38:41]
	v_mfma_f32_16x16x32_bf16 v[38:41], v[150:153], v[174:177], v[38:41]
	v_mfma_f32_16x16x32_bf16 v[42:45], v[130:133], v[170:173], v[42:45]
	v_mfma_f32_16x16x32_bf16 v[42:45], v[138:141], v[174:177], v[42:45]
	v_mfma_f32_16x16x32_bf16 v[46:49], v[106:109], v[170:173], v[46:49]
	v_mfma_f32_16x16x32_bf16 v[46:49], v[118:121], v[174:177], v[46:49]
	v_mfma_f32_16x16x32_bf16 v[30:33], v[106:109], v[178:181], v[30:33]
	v_mfma_f32_16x16x32_bf16 v[30:33], v[118:121], v[182:185], v[30:33]
	v_mfma_f32_16x16x32_bf16 v[26:29], v[130:133], v[178:181], v[26:29]
	v_mfma_f32_16x16x32_bf16 v[26:29], v[138:141], v[182:185], v[26:29]
	v_mfma_f32_16x16x32_bf16 v[22:25], v[146:149], v[178:181], v[22:25]
	v_mfma_f32_16x16x32_bf16 v[22:25], v[150:153], v[182:185], v[22:25]
	v_mfma_f32_16x16x32_bf16 v[18:21], v[154:157], v[178:181], v[18:21]
	v_mfma_f32_16x16x32_bf16 v[18:21], v[158:161], v[182:185], v[18:21]
	v_mfma_f32_16x16x32_bf16 v[2:5], v[154:157], v[190:193], v[2:5]
	v_mfma_f32_16x16x32_bf16 v[2:5], v[158:161], v[194:197], v[2:5]
	v_mfma_f32_16x16x32_bf16 v[6:9], v[146:149], v[190:193], v[6:9]
	v_mfma_f32_16x16x32_bf16 v[6:9], v[150:153], v[194:197], v[6:9]
	v_mfma_f32_16x16x32_bf16 v[10:13], v[130:133], v[190:193], v[10:13]
	v_mfma_f32_16x16x32_bf16 v[10:13], v[138:141], v[194:197], v[10:13]
	v_mfma_f32_16x16x32_bf16 v[14:17], v[106:109], v[190:193], v[14:17]
	v_mfma_f32_16x16x32_bf16 v[14:17], v[118:121], v[194:197], v[14:17]
	s_setprio 0
	s_barrier
	s_add_i32 s74, s74, 2
	s_addk_i32 s72, 0x100
	s_addk_i32 s73, 0x100
	s_cmp_ge_i32 s74, s3
	s_cbranch_scc0 .LBB0_1290
	s_and_b64 vcc, exec, s[38:39]
	s_cbranch_vccz .LBB0_1293

.LBB0_1382:
	ds_read_b128 v[144:147], v138
	ds_read_b128 v[148:151], v138 offset:1024
	ds_read_b128 v[152:155], v138 offset:2048
	ds_read_b128 v[156:159], v138 offset:3072
	ds_read_b128 v[160:163], v139
	ds_read_b128 v[164:167], v139 offset:1024
	ds_read_b128 v[168:171], v139 offset:2048
	ds_read_b128 v[172:175], v139 offset:3072
	s_add_i32 s14, s74, 0xffe80080
	s_cmp_eq_u32 s61, s76
	s_cselect_b32 s77, s72, s14
	s_cselect_b32 s79, s73, s75
	s_or_b32 s78, s77, 0x80
	s_add_i32 s14, s74, 0xfff80000
	s_mov_b32 m0, s62
	ds_read_b128 v[176:179], v140
	ds_read_b128 v[180:183], v140 offset:1024
	ds_read_b128 v[184:187], v140 offset:2048
	ds_read_b128 v[188:191], v140 offset:3072
	ds_read_b128 v[192:195], v140 offset:4096
	ds_read_b128 v[196:199], v140 offset:5120
	ds_read_b128 v[200:203], v140 offset:6144
	ds_read_b128 v[204:207], v140 offset:7168
	buffer_load_dwordx4 v136, s[16:19], s14 offen lds
	s_mov_b32 m0, s63
	s_nop 0
	buffer_load_dwordx4 v136, s[16:19], s74 offen lds
	s_waitcnt vmcnt(8)
	s_waitcnt lgkmcnt(0)
	s_setprio 1
	v_mfma_f32_16x16x32_bf16 v[118:121], v[144:147], v[176:179], v[118:121]
	s_barrier
	v_mfma_f32_16x16x32_bf16 v[118:121], v[148:151], v[180:183], v[118:121]
	v_mfma_f32_16x16x32_bf16 v[114:117], v[152:155], v[176:179], v[114:117]
	v_mfma_f32_16x16x32_bf16 v[114:117], v[156:159], v[180:183], v[114:117]
	v_mfma_f32_16x16x32_bf16 v[126:129], v[160:163], v[176:179], v[126:129]
	v_mfma_f32_16x16x32_bf16 v[126:129], v[164:167], v[180:183], v[126:129]
	v_mfma_f32_16x16x32_bf16 v[122:125], v[168:171], v[176:179], v[122:125]
	v_mfma_f32_16x16x32_bf16 v[122:125], v[172:175], v[180:183], v[122:125]
	v_mfma_f32_16x16x32_bf16 v[98:101], v[168:171], v[184:187], v[98:101]
	v_mfma_f32_16x16x32_bf16 v[98:101], v[172:175], v[188:191], v[98:101]
	v_mfma_f32_16x16x32_bf16 v[106:109], v[160:163], v[184:187], v[106:109]
	v_mfma_f32_16x16x32_bf16 v[106:109], v[164:167], v[188:191], v[106:109]
	v_mfma_f32_16x16x32_bf16 v[102:105], v[152:155], v[184:187], v[102:105]
	v_mfma_f32_16x16x32_bf16 v[102:105], v[156:159], v[188:191], v[102:105]
	v_mfma_f32_16x16x32_bf16 v[110:113], v[144:147], v[184:187], v[110:113]
	v_mfma_f32_16x16x32_bf16 v[110:113], v[148:151], v[188:191], v[110:113]
	v_mfma_f32_16x16x32_bf16 v[94:97], v[144:147], v[192:195], v[94:97]
	v_mfma_f32_16x16x32_bf16 v[94:97], v[148:151], v[196:199], v[94:97]
	v_mfma_f32_16x16x32_bf16 v[86:89], v[152:155], v[192:195], v[86:89]
	v_mfma_f32_16x16x32_bf16 v[86:89], v[156:159], v[196:199], v[86:89]
	v_mfma_f32_16x16x32_bf16 v[90:93], v[160:163], v[192:195], v[90:93]
	v_mfma_f32_16x16x32_bf16 v[90:93], v[164:167], v[196:199], v[90:93]
	v_mfma_f32_16x16x32_bf16 v[82:85], v[168:171], v[192:195], v[82:85]
	v_mfma_f32_16x16x32_bf16 v[82:85], v[172:175], v[196:199], v[82:85]
	v_mfma_f32_16x16x32_bf16 v[70:73], v[168:171], v[200:203], v[70:73]
	v_mfma_f32_16x16x32_bf16 v[70:73], v[172:175], v[204:207], v[70:73]
	v_mfma_f32_16x16x32_bf16 v[74:77], v[160:163], v[200:203], v[74:77]
	v_mfma_f32_16x16x32_bf16 v[74:77], v[164:167], v[204:207], v[74:77]
	v_mfma_f32_16x16x32_bf16 v[66:69], v[152:155], v[200:203], v[66:69]
	v_mfma_f32_16x16x32_bf16 v[66:69], v[156:159], v[204:207], v[66:69]
	v_mfma_f32_16x16x32_bf16 v[78:81], v[144:147], v[200:203], v[78:81]
	v_mfma_f32_16x16x32_bf16 v[78:81], v[148:151], v[204:207], v[78:81]
	s_setprio 0
	s_barrier
	s_mov_b32 m0, s45
	s_mov_b32 s14, s18
	s_mov_b32 s15, s19
	ds_read_b128 v[176:179], v140 offset:16384
	ds_read_b128 v[180:183], v140 offset:17408
	ds_read_b128 v[184:187], v140 offset:18432
	ds_read_b128 v[188:191], v140 offset:19456
	ds_read_b128 v[192:195], v140 offset:20480
	ds_read_b128 v[196:199], v140 offset:21504
	ds_read_b128 v[200:203], v140 offset:22528
	ds_read_b128 v[204:207], v140 offset:23552
	buffer_load_dwordx4 v137, s[12:15], s79 offen lds
	s_add_i32 s80, s79, 0x80000
	s_mov_b32 m0, s46
	s_nop 0
	buffer_load_dwordx4 v137, s[12:15], s80 offen lds
	s_add_i32 s80, s79, 0x100000
	s_mov_b32 m0, s47
	s_nop 0
	buffer_load_dwordx4 v137, s[12:15], s80 offen lds
	s_add_i32 s80, s79, 0x180000
	s_mov_b32 m0, s48
	s_nop 0
	buffer_load_dwordx4 v137, s[12:15], s80 offen lds
	s_mov_b32 m0, s44
	s_add_i32 s80, s77, 0x80000
	buffer_load_dwordx4 v136, s[16:19], s77 offen lds
	s_mov_b32 m0, s49
	s_nop 0
	buffer_load_dwordx4 v136, s[16:19], s80 offen lds
	s_waitcnt vmcnt(8)
	s_waitcnt lgkmcnt(0)
	s_setprio 1
	v_mfma_f32_16x16x32_bf16 v[62:65], v[144:147], v[176:179], v[62:65]
	s_barrier
	v_mfma_f32_16x16x32_bf16 v[62:65], v[148:151], v[180:183], v[62:65]
	v_mfma_f32_16x16x32_bf16 v[54:57], v[152:155], v[176:179], v[54:57]
	v_mfma_f32_16x16x32_bf16 v[54:57], v[156:159], v[180:183], v[54:57]
	v_mfma_f32_16x16x32_bf16 v[58:61], v[160:163], v[176:179], v[58:61]
	v_mfma_f32_16x16x32_bf16 v[58:61], v[164:167], v[180:183], v[58:61]
	v_mfma_f32_16x16x32_bf16 v[50:53], v[168:171], v[176:179], v[50:53]
	v_mfma_f32_16x16x32_bf16 v[50:53], v[172:175], v[180:183], v[50:53]
	v_mfma_f32_16x16x32_bf16 v[34:37], v[168:171], v[184:187], v[34:37]
	v_mfma_f32_16x16x32_bf16 v[34:37], v[172:175], v[188:191], v[34:37]
	v_mfma_f32_16x16x32_bf16 v[42:45], v[160:163], v[184:187], v[42:45]
	v_mfma_f32_16x16x32_bf16 v[42:45], v[164:167], v[188:191], v[42:45]
	v_mfma_f32_16x16x32_bf16 v[38:41], v[152:155], v[184:187], v[38:41]
	v_mfma_f32_16x16x32_bf16 v[38:41], v[156:159], v[188:191], v[38:41]
	v_mfma_f32_16x16x32_bf16 v[46:49], v[144:147], v[184:187], v[46:49]
	v_mfma_f32_16x16x32_bf16 v[46:49], v[148:151], v[188:191], v[46:49]
	v_mfma_f32_16x16x32_bf16 v[30:33], v[144:147], v[192:195], v[30:33]
	v_mfma_f32_16x16x32_bf16 v[30:33], v[148:151], v[196:199], v[30:33]
	v_mfma_f32_16x16x32_bf16 v[22:25], v[152:155], v[192:195], v[22:25]
	v_mfma_f32_16x16x32_bf16 v[22:25], v[156:159], v[196:199], v[22:25]
	v_mfma_f32_16x16x32_bf16 v[26:29], v[160:163], v[192:195], v[26:29]
	v_mfma_f32_16x16x32_bf16 v[26:29], v[164:167], v[196:199], v[26:29]
	v_mfma_f32_16x16x32_bf16 v[18:21], v[168:171], v[192:195], v[18:21]
	v_mfma_f32_16x16x32_bf16 v[18:21], v[172:175], v[196:199], v[18:21]
	v_mfma_f32_16x16x32_bf16 v[2:5], v[168:171], v[200:203], v[2:5]
	v_mfma_f32_16x16x32_bf16 v[2:5], v[172:175], v[204:207], v[2:5]
	v_mfma_f32_16x16x32_bf16 v[10:13], v[160:163], v[200:203], v[10:13]
	v_mfma_f32_16x16x32_bf16 v[10:13], v[164:167], v[204:207], v[10:13]
	v_mfma_f32_16x16x32_bf16 v[6:9], v[152:155], v[200:203], v[6:9]
	v_mfma_f32_16x16x32_bf16 v[6:9], v[156:159], v[204:207], v[6:9]
	v_mfma_f32_16x16x32_bf16 v[14:17], v[144:147], v[200:203], v[14:17]
	v_mfma_f32_16x16x32_bf16 v[14:17], v[148:151], v[204:207], v[14:17]
	s_setprio 0
	s_barrier
	ds_read_b128 v[144:147], v141
	ds_read_b128 v[148:151], v141 offset:1024
	ds_read_b128 v[152:155], v141 offset:2048
	ds_read_b128 v[156:159], v141 offset:3072
	ds_read_b128 v[160:163], v142
	ds_read_b128 v[164:167], v142 offset:1024
	ds_read_b128 v[168:171], v142 offset:2048
	ds_read_b128 v[172:175], v142 offset:3072
	s_mov_b32 m0, s50
	s_add_i32 s80, s77, 0x100000
	ds_read_b128 v[176:179], v140 offset:32768
	ds_read_b128 v[180:183], v140 offset:33792
	ds_read_b128 v[184:187], v140 offset:34816
	ds_read_b128 v[188:191], v140 offset:35840
	ds_read_b128 v[192:195], v140 offset:36864
	ds_read_b128 v[196:199], v140 offset:37888
	ds_read_b128 v[200:203], v140 offset:38912
	ds_read_b128 v[204:207], v140 offset:39936
	buffer_load_dwordx4 v136, s[16:19], s80 offen lds
	s_add_i32 s80, s77, 0x180000
	s_mov_b32 m0, s51
	s_nop 0
	buffer_load_dwordx4 v136, s[16:19], s80 offen lds
	s_waitcnt vmcnt(8)
	s_waitcnt lgkmcnt(0)
	s_setprio 1
	v_mfma_f32_16x16x32_bf16 v[118:121], v[144:147], v[176:179], v[118:121]
	s_barrier
	v_mfma_f32_16x16x32_bf16 v[118:121], v[148:151], v[180:183], v[118:121]
	v_mfma_f32_16x16x32_bf16 v[114:117], v[152:155], v[176:179], v[114:117]
	v_mfma_f32_16x16x32_bf16 v[114:117], v[156:159], v[180:183], v[114:117]
	v_mfma_f32_16x16x32_bf16 v[126:129], v[160:163], v[176:179], v[126:129]
	v_mfma_f32_16x16x32_bf16 v[126:129], v[164:167], v[180:183], v[126:129]
	v_mfma_f32_16x16x32_bf16 v[122:125], v[168:171], v[176:179], v[122:125]
	v_mfma_f32_16x16x32_bf16 v[122:125], v[172:175], v[180:183], v[122:125]
	v_mfma_f32_16x16x32_bf16 v[98:101], v[168:171], v[184:187], v[98:101]
	v_mfma_f32_16x16x32_bf16 v[98:101], v[172:175], v[188:191], v[98:101]
	v_mfma_f32_16x16x32_bf16 v[106:109], v[160:163], v[184:187], v[106:109]
	v_mfma_f32_16x16x32_bf16 v[106:109], v[164:167], v[188:191], v[106:109]
	v_mfma_f32_16x16x32_bf16 v[102:105], v[152:155], v[184:187], v[102:105]
	v_mfma_f32_16x16x32_bf16 v[102:105], v[156:159], v[188:191], v[102:105]
	v_mfma_f32_16x16x32_bf16 v[110:113], v[144:147], v[184:187], v[110:113]
	v_mfma_f32_16x16x32_bf16 v[110:113], v[148:151], v[188:191], v[110:113]
	v_mfma_f32_16x16x32_bf16 v[94:97], v[144:147], v[192:195], v[94:97]
	v_mfma_f32_16x16x32_bf16 v[94:97], v[148:151], v[196:199], v[94:97]
	v_mfma_f32_16x16x32_bf16 v[86:89], v[152:155], v[192:195], v[86:89]
	v_mfma_f32_16x16x32_bf16 v[86:89], v[156:159], v[196:199], v[86:89]
	v_mfma_f32_16x16x32_bf16 v[90:93], v[160:163], v[192:195], v[90:93]
	v_mfma_f32_16x16x32_bf16 v[90:93], v[164:167], v[196:199], v[90:93]
	v_mfma_f32_16x16x32_bf16 v[82:85], v[168:171], v[192:195], v[82:85]
	v_mfma_f32_16x16x32_bf16 v[82:85], v[172:175], v[196:199], v[82:85]
	v_mfma_f32_16x16x32_bf16 v[70:73], v[168:171], v[200:203], v[70:73]
	v_mfma_f32_16x16x32_bf16 v[70:73], v[172:175], v[204:207], v[70:73]
	v_mfma_f32_16x16x32_bf16 v[74:77], v[160:163], v[200:203], v[74:77]
	v_mfma_f32_16x16x32_bf16 v[74:77], v[164:167], v[204:207], v[74:77]
	v_mfma_f32_16x16x32_bf16 v[66:69], v[152:155], v[200:203], v[66:69]
	v_mfma_f32_16x16x32_bf16 v[66:69], v[156:159], v[204:207], v[66:69]
	v_mfma_f32_16x16x32_bf16 v[78:81], v[144:147], v[200:203], v[78:81]
	v_mfma_f32_16x16x32_bf16 v[78:81], v[148:151], v[204:207], v[78:81]
	s_setprio 0
	s_barrier
	s_mov_b32 m0, s53
	s_or_b32 s80, s79, 0x80
	ds_read_b128 v[176:179], v140 offset:49152
	ds_read_b128 v[180:183], v140 offset:50176
	ds_read_b128 v[184:187], v140 offset:51200
	ds_read_b128 v[188:191], v140 offset:52224
	ds_read_b128 v[192:195], v140 offset:53248
	ds_read_b128 v[196:199], v140 offset:54272
	ds_read_b128 v[200:203], v140 offset:55296
	ds_read_b128 v[204:207], v140 offset:56320
	buffer_load_dwordx4 v137, s[12:15], s80 offen lds
	s_add_i32 s80, s79, 0x80080
	s_mov_b32 m0, s54
	s_add_i32 s77, s77, 0x80080
	buffer_load_dwordx4 v137, s[12:15], s80 offen lds
	s_add_i32 s80, s79, 0x100080
	s_mov_b32 m0, s57
	s_add_i32 s79, s79, 0x180080
	buffer_load_dwordx4 v137, s[12:15], s80 offen lds
	s_mov_b32 m0, s58
	s_nop 0
	buffer_load_dwordx4 v137, s[12:15], s79 offen lds
	s_mov_b32 m0, s55
	s_nop 0
	buffer_load_dwordx4 v136, s[16:19], s78 offen lds
	s_mov_b32 m0, s56
	s_nop 0
	buffer_load_dwordx4 v136, s[16:19], s77 offen lds
	s_waitcnt vmcnt(8)
	s_waitcnt lgkmcnt(0)
	s_setprio 1
	v_mfma_f32_16x16x32_bf16 v[62:65], v[144:147], v[176:179], v[62:65]
	s_barrier
	v_mfma_f32_16x16x32_bf16 v[62:65], v[148:151], v[180:183], v[62:65]
	v_mfma_f32_16x16x32_bf16 v[54:57], v[152:155], v[176:179], v[54:57]
	v_mfma_f32_16x16x32_bf16 v[54:57], v[156:159], v[180:183], v[54:57]
	v_mfma_f32_16x16x32_bf16 v[58:61], v[160:163], v[176:179], v[58:61]
	v_mfma_f32_16x16x32_bf16 v[58:61], v[164:167], v[180:183], v[58:61]
	v_mfma_f32_16x16x32_bf16 v[50:53], v[168:171], v[176:179], v[50:53]
	v_mfma_f32_16x16x32_bf16 v[50:53], v[172:175], v[180:183], v[50:53]
	v_mfma_f32_16x16x32_bf16 v[34:37], v[168:171], v[184:187], v[34:37]
	v_mfma_f32_16x16x32_bf16 v[34:37], v[172:175], v[188:191], v[34:37]
	v_mfma_f32_16x16x32_bf16 v[42:45], v[160:163], v[184:187], v[42:45]
	v_mfma_f32_16x16x32_bf16 v[42:45], v[164:167], v[188:191], v[42:45]
	v_mfma_f32_16x16x32_bf16 v[38:41], v[152:155], v[184:187], v[38:41]
	v_mfma_f32_16x16x32_bf16 v[38:41], v[156:159], v[188:191], v[38:41]
	v_mfma_f32_16x16x32_bf16 v[46:49], v[144:147], v[184:187], v[46:49]
	v_mfma_f32_16x16x32_bf16 v[46:49], v[148:151], v[188:191], v[46:49]
	v_mfma_f32_16x16x32_bf16 v[30:33], v[144:147], v[192:195], v[30:33]
	v_mfma_f32_16x16x32_bf16 v[30:33], v[148:151], v[196:199], v[30:33]
	v_mfma_f32_16x16x32_bf16 v[22:25], v[152:155], v[192:195], v[22:25]
	v_mfma_f32_16x16x32_bf16 v[22:25], v[156:159], v[196:199], v[22:25]
	v_mfma_f32_16x16x32_bf16 v[26:29], v[160:163], v[192:195], v[26:29]
	v_mfma_f32_16x16x32_bf16 v[26:29], v[164:167], v[196:199], v[26:29]
	v_mfma_f32_16x16x32_bf16 v[18:21], v[168:171], v[192:195], v[18:21]
	v_mfma_f32_16x16x32_bf16 v[18:21], v[172:175], v[196:199], v[18:21]
	v_mfma_f32_16x16x32_bf16 v[2:5], v[168:171], v[200:203], v[2:5]
	v_mfma_f32_16x16x32_bf16 v[2:5], v[172:175], v[204:207], v[2:5]
	v_mfma_f32_16x16x32_bf16 v[10:13], v[160:163], v[200:203], v[10:13]
	v_mfma_f32_16x16x32_bf16 v[10:13], v[164:167], v[204:207], v[10:13]
	v_mfma_f32_16x16x32_bf16 v[6:9], v[152:155], v[200:203], v[6:9]
	v_mfma_f32_16x16x32_bf16 v[6:9], v[156:159], v[204:207], v[6:9]
	v_mfma_f32_16x16x32_bf16 v[14:17], v[144:147], v[200:203], v[14:17]
	v_mfma_f32_16x16x32_bf16 v[14:17], v[148:151], v[204:207], v[14:17]
	s_setprio 0
	s_barrier
	s_add_i32 s76, s76, 2
	s_addk_i32 s74, 0x100
	s_addk_i32 s75, 0x100
	s_cmp_ge_i32 s76, s27
	s_cbranch_scc0 .LBB0_1382
	s_and_b64 vcc, exec, s[42:43]
	s_cbranch_vccz .LBB0_1385

.LBB0_1402:
	ds_read_b128 v[146:149], v138
	ds_read_b128 v[150:153], v138 offset:1024
	ds_read_b128 v[154:157], v138 offset:2048
	ds_read_b128 v[158:161], v138 offset:3072
	ds_read_b128 v[162:165], v139
	ds_read_b128 v[166:169], v139 offset:1024
	ds_read_b128 v[170:173], v139 offset:2048
	ds_read_b128 v[174:177], v139 offset:3072
	s_add_i32 s22, s75, 0xffe80080
	s_cmp_eq_u32 s62, s77
	s_cselect_b32 s78, s73, s22
	s_cselect_b32 s80, s74, s76
	s_or_b32 s79, s78, 0x80
	s_add_i32 s22, s75, 0xfff80000
	s_mov_b32 m0, s63
	ds_read_b128 v[178:181], v140
	ds_read_b128 v[182:185], v140 offset:1024
	ds_read_b128 v[186:189], v140 offset:2048
	ds_read_b128 v[190:193], v140 offset:3072
	ds_read_b128 v[194:197], v140 offset:4096
	ds_read_b128 v[198:201], v140 offset:5120
	ds_read_b128 v[202:205], v140 offset:6144
	ds_read_b128 v[206:209], v140 offset:7168
	buffer_load_dwordx4 v136, s[16:19], s22 offen lds
	s_mov_b32 m0, s64
	s_nop 0
	buffer_load_dwordx4 v136, s[16:19], s75 offen lds
	s_waitcnt vmcnt(8)
	s_waitcnt lgkmcnt(0)
	s_setprio 1
	v_mfma_f32_16x16x32_bf16 v[118:121], v[146:149], v[178:181], v[118:121]
	s_barrier
	v_mfma_f32_16x16x32_bf16 v[118:121], v[150:153], v[182:185], v[118:121]
	v_mfma_f32_16x16x32_bf16 v[114:117], v[154:157], v[178:181], v[114:117]
	v_mfma_f32_16x16x32_bf16 v[114:117], v[158:161], v[182:185], v[114:117]
	v_mfma_f32_16x16x32_bf16 v[126:129], v[162:165], v[178:181], v[126:129]
	v_mfma_f32_16x16x32_bf16 v[126:129], v[166:169], v[182:185], v[126:129]
	v_mfma_f32_16x16x32_bf16 v[122:125], v[170:173], v[178:181], v[122:125]
	v_mfma_f32_16x16x32_bf16 v[122:125], v[174:177], v[182:185], v[122:125]
	v_mfma_f32_16x16x32_bf16 v[98:101], v[170:173], v[186:189], v[98:101]
	v_mfma_f32_16x16x32_bf16 v[98:101], v[174:177], v[190:193], v[98:101]
	v_mfma_f32_16x16x32_bf16 v[106:109], v[162:165], v[186:189], v[106:109]
	v_mfma_f32_16x16x32_bf16 v[106:109], v[166:169], v[190:193], v[106:109]
	v_mfma_f32_16x16x32_bf16 v[102:105], v[154:157], v[186:189], v[102:105]
	v_mfma_f32_16x16x32_bf16 v[102:105], v[158:161], v[190:193], v[102:105]
	v_mfma_f32_16x16x32_bf16 v[110:113], v[146:149], v[186:189], v[110:113]
	v_mfma_f32_16x16x32_bf16 v[110:113], v[150:153], v[190:193], v[110:113]
	v_mfma_f32_16x16x32_bf16 v[94:97], v[146:149], v[194:197], v[94:97]
	v_mfma_f32_16x16x32_bf16 v[94:97], v[150:153], v[198:201], v[94:97]
	v_mfma_f32_16x16x32_bf16 v[86:89], v[154:157], v[194:197], v[86:89]
	v_mfma_f32_16x16x32_bf16 v[86:89], v[158:161], v[198:201], v[86:89]
	v_mfma_f32_16x16x32_bf16 v[90:93], v[162:165], v[194:197], v[90:93]
	v_mfma_f32_16x16x32_bf16 v[90:93], v[166:169], v[198:201], v[90:93]
	v_mfma_f32_16x16x32_bf16 v[82:85], v[170:173], v[194:197], v[82:85]
	v_mfma_f32_16x16x32_bf16 v[82:85], v[174:177], v[198:201], v[82:85]
	v_mfma_f32_16x16x32_bf16 v[70:73], v[170:173], v[202:205], v[70:73]
	v_mfma_f32_16x16x32_bf16 v[70:73], v[174:177], v[206:209], v[70:73]
	v_mfma_f32_16x16x32_bf16 v[74:77], v[162:165], v[202:205], v[74:77]
	v_mfma_f32_16x16x32_bf16 v[74:77], v[166:169], v[206:209], v[74:77]
	v_mfma_f32_16x16x32_bf16 v[66:69], v[154:157], v[202:205], v[66:69]
	v_mfma_f32_16x16x32_bf16 v[66:69], v[158:161], v[206:209], v[66:69]
	v_mfma_f32_16x16x32_bf16 v[78:81], v[146:149], v[202:205], v[78:81]
	v_mfma_f32_16x16x32_bf16 v[78:81], v[150:153], v[206:209], v[78:81]
	s_setprio 0
	s_barrier
	s_mov_b32 m0, s31
	s_mov_b32 s22, s18
	s_mov_b32 s23, s19
	ds_read_b128 v[178:181], v140 offset:16384
	ds_read_b128 v[182:185], v140 offset:17408
	ds_read_b128 v[186:189], v140 offset:18432
	ds_read_b128 v[190:193], v140 offset:19456
	ds_read_b128 v[194:197], v140 offset:20480
	ds_read_b128 v[198:201], v140 offset:21504
	ds_read_b128 v[202:205], v140 offset:22528
	ds_read_b128 v[206:209], v140 offset:23552
	buffer_load_dwordx4 v137, s[20:23], s80 offen lds
	s_add_i32 s81, s80, 0x80000
	s_mov_b32 m0, s48
	s_nop 0
	buffer_load_dwordx4 v137, s[20:23], s81 offen lds
	s_add_i32 s81, s80, 0x100000
	s_mov_b32 m0, s49
	s_nop 0
	buffer_load_dwordx4 v137, s[20:23], s81 offen lds
	s_add_i32 s81, s80, 0x180000
	s_mov_b32 m0, s50
	s_nop 0
	buffer_load_dwordx4 v137, s[20:23], s81 offen lds
	s_mov_b32 m0, s30
	s_add_i32 s81, s78, 0x80000
	buffer_load_dwordx4 v136, s[16:19], s78 offen lds
	s_mov_b32 m0, s51
	s_nop 0
	buffer_load_dwordx4 v136, s[16:19], s81 offen lds
	s_waitcnt vmcnt(8)
	s_waitcnt lgkmcnt(0)
	s_setprio 1
	v_mfma_f32_16x16x32_bf16 v[62:65], v[146:149], v[178:181], v[62:65]
	s_barrier
	v_mfma_f32_16x16x32_bf16 v[62:65], v[150:153], v[182:185], v[62:65]
	v_mfma_f32_16x16x32_bf16 v[54:57], v[154:157], v[178:181], v[54:57]
	v_mfma_f32_16x16x32_bf16 v[54:57], v[158:161], v[182:185], v[54:57]
	v_mfma_f32_16x16x32_bf16 v[58:61], v[162:165], v[178:181], v[58:61]
	v_mfma_f32_16x16x32_bf16 v[58:61], v[166:169], v[182:185], v[58:61]
	v_mfma_f32_16x16x32_bf16 v[50:53], v[170:173], v[178:181], v[50:53]
	v_mfma_f32_16x16x32_bf16 v[50:53], v[174:177], v[182:185], v[50:53]
	v_mfma_f32_16x16x32_bf16 v[34:37], v[170:173], v[186:189], v[34:37]
	v_mfma_f32_16x16x32_bf16 v[34:37], v[174:177], v[190:193], v[34:37]
	v_mfma_f32_16x16x32_bf16 v[42:45], v[162:165], v[186:189], v[42:45]
	v_mfma_f32_16x16x32_bf16 v[42:45], v[166:169], v[190:193], v[42:45]
	v_mfma_f32_16x16x32_bf16 v[38:41], v[154:157], v[186:189], v[38:41]
	v_mfma_f32_16x16x32_bf16 v[38:41], v[158:161], v[190:193], v[38:41]
	v_mfma_f32_16x16x32_bf16 v[46:49], v[146:149], v[186:189], v[46:49]
	v_mfma_f32_16x16x32_bf16 v[46:49], v[150:153], v[190:193], v[46:49]
	v_mfma_f32_16x16x32_bf16 v[30:33], v[146:149], v[194:197], v[30:33]
	v_mfma_f32_16x16x32_bf16 v[30:33], v[150:153], v[198:201], v[30:33]
	v_mfma_f32_16x16x32_bf16 v[22:25], v[154:157], v[194:197], v[22:25]
	v_mfma_f32_16x16x32_bf16 v[22:25], v[158:161], v[198:201], v[22:25]
	v_mfma_f32_16x16x32_bf16 v[26:29], v[162:165], v[194:197], v[26:29]
	v_mfma_f32_16x16x32_bf16 v[26:29], v[166:169], v[198:201], v[26:29]
	v_mfma_f32_16x16x32_bf16 v[18:21], v[170:173], v[194:197], v[18:21]
	v_mfma_f32_16x16x32_bf16 v[18:21], v[174:177], v[198:201], v[18:21]
	v_mfma_f32_16x16x32_bf16 v[2:5], v[170:173], v[202:205], v[2:5]
	v_mfma_f32_16x16x32_bf16 v[2:5], v[174:177], v[206:209], v[2:5]
	v_mfma_f32_16x16x32_bf16 v[10:13], v[162:165], v[202:205], v[10:13]
	v_mfma_f32_16x16x32_bf16 v[10:13], v[166:169], v[206:209], v[10:13]
	v_mfma_f32_16x16x32_bf16 v[6:9], v[154:157], v[202:205], v[6:9]
	v_mfma_f32_16x16x32_bf16 v[6:9], v[158:161], v[206:209], v[6:9]
	v_mfma_f32_16x16x32_bf16 v[14:17], v[146:149], v[202:205], v[14:17]
	v_mfma_f32_16x16x32_bf16 v[14:17], v[150:153], v[206:209], v[14:17]
	s_setprio 0
	s_barrier
	ds_read_b128 v[146:149], v141
	ds_read_b128 v[150:153], v141 offset:1024
	ds_read_b128 v[154:157], v141 offset:2048
	ds_read_b128 v[158:161], v141 offset:3072
	ds_read_b128 v[162:165], v142
	ds_read_b128 v[166:169], v142 offset:1024
	ds_read_b128 v[170:173], v142 offset:2048
	ds_read_b128 v[174:177], v142 offset:3072
	s_mov_b32 m0, s52
	s_add_i32 s81, s78, 0x100000
	ds_read_b128 v[178:181], v140 offset:32768
	ds_read_b128 v[182:185], v140 offset:33792
	ds_read_b128 v[186:189], v140 offset:34816
	ds_read_b128 v[190:193], v140 offset:35840
	ds_read_b128 v[194:197], v140 offset:36864
	ds_read_b128 v[198:201], v140 offset:37888
	ds_read_b128 v[202:205], v140 offset:38912
	ds_read_b128 v[206:209], v140 offset:39936
	buffer_load_dwordx4 v136, s[16:19], s81 offen lds
	s_add_i32 s81, s78, 0x180000
	s_mov_b32 m0, s53
	s_nop 0
	buffer_load_dwordx4 v136, s[16:19], s81 offen lds
	s_waitcnt vmcnt(8)
	s_waitcnt lgkmcnt(0)
	s_setprio 1
	v_mfma_f32_16x16x32_bf16 v[118:121], v[146:149], v[178:181], v[118:121]
	s_barrier
	v_mfma_f32_16x16x32_bf16 v[118:121], v[150:153], v[182:185], v[118:121]
	v_mfma_f32_16x16x32_bf16 v[114:117], v[154:157], v[178:181], v[114:117]
	v_mfma_f32_16x16x32_bf16 v[114:117], v[158:161], v[182:185], v[114:117]
	v_mfma_f32_16x16x32_bf16 v[126:129], v[162:165], v[178:181], v[126:129]
	v_mfma_f32_16x16x32_bf16 v[126:129], v[166:169], v[182:185], v[126:129]
	v_mfma_f32_16x16x32_bf16 v[122:125], v[170:173], v[178:181], v[122:125]
	v_mfma_f32_16x16x32_bf16 v[122:125], v[174:177], v[182:185], v[122:125]
	v_mfma_f32_16x16x32_bf16 v[98:101], v[170:173], v[186:189], v[98:101]
	v_mfma_f32_16x16x32_bf16 v[98:101], v[174:177], v[190:193], v[98:101]
	v_mfma_f32_16x16x32_bf16 v[106:109], v[162:165], v[186:189], v[106:109]
	v_mfma_f32_16x16x32_bf16 v[106:109], v[166:169], v[190:193], v[106:109]
	v_mfma_f32_16x16x32_bf16 v[102:105], v[154:157], v[186:189], v[102:105]
	v_mfma_f32_16x16x32_bf16 v[102:105], v[158:161], v[190:193], v[102:105]
	v_mfma_f32_16x16x32_bf16 v[110:113], v[146:149], v[186:189], v[110:113]
	v_mfma_f32_16x16x32_bf16 v[110:113], v[150:153], v[190:193], v[110:113]
	v_mfma_f32_16x16x32_bf16 v[94:97], v[146:149], v[194:197], v[94:97]
	v_mfma_f32_16x16x32_bf16 v[94:97], v[150:153], v[198:201], v[94:97]
	v_mfma_f32_16x16x32_bf16 v[86:89], v[154:157], v[194:197], v[86:89]
	v_mfma_f32_16x16x32_bf16 v[86:89], v[158:161], v[198:201], v[86:89]
	v_mfma_f32_16x16x32_bf16 v[90:93], v[162:165], v[194:197], v[90:93]
	v_mfma_f32_16x16x32_bf16 v[90:93], v[166:169], v[198:201], v[90:93]
	v_mfma_f32_16x16x32_bf16 v[82:85], v[170:173], v[194:197], v[82:85]
	v_mfma_f32_16x16x32_bf16 v[82:85], v[174:177], v[198:201], v[82:85]
	v_mfma_f32_16x16x32_bf16 v[70:73], v[170:173], v[202:205], v[70:73]
	v_mfma_f32_16x16x32_bf16 v[70:73], v[174:177], v[206:209], v[70:73]
	v_mfma_f32_16x16x32_bf16 v[74:77], v[162:165], v[202:205], v[74:77]
	v_mfma_f32_16x16x32_bf16 v[74:77], v[166:169], v[206:209], v[74:77]
	v_mfma_f32_16x16x32_bf16 v[66:69], v[154:157], v[202:205], v[66:69]
	v_mfma_f32_16x16x32_bf16 v[66:69], v[158:161], v[206:209], v[66:69]
	v_mfma_f32_16x16x32_bf16 v[78:81], v[146:149], v[202:205], v[78:81]
	v_mfma_f32_16x16x32_bf16 v[78:81], v[150:153], v[206:209], v[78:81]
	s_setprio 0
	s_barrier
	s_mov_b32 m0, s54
	s_or_b32 s81, s80, 0x80
	ds_read_b128 v[178:181], v140 offset:49152
	ds_read_b128 v[182:185], v140 offset:50176
	ds_read_b128 v[186:189], v140 offset:51200
	ds_read_b128 v[190:193], v140 offset:52224
	ds_read_b128 v[194:197], v140 offset:53248
	ds_read_b128 v[198:201], v140 offset:54272
	ds_read_b128 v[202:205], v140 offset:55296
	ds_read_b128 v[206:209], v140 offset:56320
	buffer_load_dwordx4 v137, s[20:23], s81 offen lds
	s_add_i32 s81, s80, 0x80080
	s_mov_b32 m0, s55
	s_add_i32 s78, s78, 0x80080
	buffer_load_dwordx4 v137, s[20:23], s81 offen lds
	s_add_i32 s81, s80, 0x100080
	s_mov_b32 m0, s58
	s_add_i32 s80, s80, 0x180080
	buffer_load_dwordx4 v137, s[20:23], s81 offen lds
	s_mov_b32 m0, s59
	s_nop 0
	buffer_load_dwordx4 v137, s[20:23], s80 offen lds
	s_mov_b32 m0, s56
	s_nop 0
	buffer_load_dwordx4 v136, s[16:19], s79 offen lds
	s_mov_b32 m0, s57
	s_nop 0
	buffer_load_dwordx4 v136, s[16:19], s78 offen lds
	s_waitcnt vmcnt(8)
	s_waitcnt lgkmcnt(0)
	s_setprio 1
	v_mfma_f32_16x16x32_bf16 v[62:65], v[146:149], v[178:181], v[62:65]
	s_barrier
	v_mfma_f32_16x16x32_bf16 v[62:65], v[150:153], v[182:185], v[62:65]
	v_mfma_f32_16x16x32_bf16 v[54:57], v[154:157], v[178:181], v[54:57]
	v_mfma_f32_16x16x32_bf16 v[54:57], v[158:161], v[182:185], v[54:57]
	v_mfma_f32_16x16x32_bf16 v[58:61], v[162:165], v[178:181], v[58:61]
	v_mfma_f32_16x16x32_bf16 v[58:61], v[166:169], v[182:185], v[58:61]
	v_mfma_f32_16x16x32_bf16 v[50:53], v[170:173], v[178:181], v[50:53]
	v_mfma_f32_16x16x32_bf16 v[50:53], v[174:177], v[182:185], v[50:53]
	v_mfma_f32_16x16x32_bf16 v[34:37], v[170:173], v[186:189], v[34:37]
	v_mfma_f32_16x16x32_bf16 v[34:37], v[174:177], v[190:193], v[34:37]
	v_mfma_f32_16x16x32_bf16 v[42:45], v[162:165], v[186:189], v[42:45]
	v_mfma_f32_16x16x32_bf16 v[42:45], v[166:169], v[190:193], v[42:45]
	v_mfma_f32_16x16x32_bf16 v[38:41], v[154:157], v[186:189], v[38:41]
	v_mfma_f32_16x16x32_bf16 v[38:41], v[158:161], v[190:193], v[38:41]
	v_mfma_f32_16x16x32_bf16 v[46:49], v[146:149], v[186:189], v[46:49]
	v_mfma_f32_16x16x32_bf16 v[46:49], v[150:153], v[190:193], v[46:49]
	v_mfma_f32_16x16x32_bf16 v[30:33], v[146:149], v[194:197], v[30:33]
	v_mfma_f32_16x16x32_bf16 v[30:33], v[150:153], v[198:201], v[30:33]
	v_mfma_f32_16x16x32_bf16 v[22:25], v[154:157], v[194:197], v[22:25]
	v_mfma_f32_16x16x32_bf16 v[22:25], v[158:161], v[198:201], v[22:25]
	v_mfma_f32_16x16x32_bf16 v[26:29], v[162:165], v[194:197], v[26:29]
	v_mfma_f32_16x16x32_bf16 v[26:29], v[166:169], v[198:201], v[26:29]
	v_mfma_f32_16x16x32_bf16 v[18:21], v[170:173], v[194:197], v[18:21]
	v_mfma_f32_16x16x32_bf16 v[18:21], v[174:177], v[198:201], v[18:21]
	v_mfma_f32_16x16x32_bf16 v[2:5], v[170:173], v[202:205], v[2:5]
	v_mfma_f32_16x16x32_bf16 v[2:5], v[174:177], v[206:209], v[2:5]
	v_mfma_f32_16x16x32_bf16 v[10:13], v[162:165], v[202:205], v[10:13]
	v_mfma_f32_16x16x32_bf16 v[10:13], v[166:169], v[206:209], v[10:13]
	v_mfma_f32_16x16x32_bf16 v[6:9], v[154:157], v[202:205], v[6:9]
	v_mfma_f32_16x16x32_bf16 v[6:9], v[158:161], v[206:209], v[6:9]
	v_mfma_f32_16x16x32_bf16 v[14:17], v[146:149], v[202:205], v[14:17]
	v_mfma_f32_16x16x32_bf16 v[14:17], v[150:153], v[206:209], v[14:17]
	s_setprio 0
	s_barrier
	s_add_i32 s77, s77, 2
	s_addk_i32 s75, 0x100
	s_addk_i32 s76, 0x100
	s_cmp_ge_i32 s77, s13
	s_cbranch_scc0 .LBB0_1402
	s_and_b64 vcc, exec, s[46:47]
	s_cbranch_vccz .LBB0_1405

.LBB0_1519:
	ds_read_b128 v[134:137], v208
	ds_read_b128 v[138:141], v208 offset:1024
	ds_read_b128 v[142:145], v208 offset:2048
	ds_read_b128 v[146:149], v208 offset:3072
	ds_read_b128 v[150:153], v209
	ds_read_b128 v[154:157], v209 offset:1024
	ds_read_b128 v[158:161], v209 offset:2048
	ds_read_b128 v[162:165], v209 offset:3072
	s_add_i32 s18, s80, 0xffbf8080
	s_cmp_eq_u32 s65, s82
	s_cselect_b32 s83, s6, s18
	s_cselect_b32 s85, s7, s81
	s_or_b32 s84, s83, 0x80
	s_add_i32 s18, s80, 0xffea8000
	s_mov_b32 m0, s66
	ds_read_b128 v[166:169], v210
	ds_read_b128 v[170:173], v210 offset:1024
	ds_read_b128 v[174:177], v210 offset:2048
	ds_read_b128 v[178:181], v210 offset:3072
	ds_read_b128 v[182:185], v210 offset:4096
	ds_read_b128 v[186:189], v210 offset:5120
	ds_read_b128 v[190:193], v210 offset:6144
	ds_read_b128 v[194:197], v210 offset:7168
	buffer_load_dwordx4 v206, s[12:15], s18 offen lds
	s_mov_b32 m0, s69
	s_nop 0
	buffer_load_dwordx4 v206, s[12:15], s80 offen lds
	s_waitcnt vmcnt(8)
	s_waitcnt lgkmcnt(0)
	s_setprio 1
	v_mfma_f32_16x16x32_bf16 v[126:129], v[134:137], v[166:169], v[126:129]
	s_barrier
	v_mfma_f32_16x16x32_bf16 v[126:129], v[138:141], v[170:173], v[126:129]
	v_mfma_f32_16x16x32_bf16 v[122:125], v[142:145], v[166:169], v[122:125]
	v_mfma_f32_16x16x32_bf16 v[122:125], v[146:149], v[170:173], v[122:125]
	v_mfma_f32_16x16x32_bf16 v[110:113], v[150:153], v[166:169], v[110:113]
	v_mfma_f32_16x16x32_bf16 v[110:113], v[154:157], v[170:173], v[110:113]
	v_mfma_f32_16x16x32_bf16 v[102:105], v[158:161], v[166:169], v[102:105]
	v_mfma_f32_16x16x32_bf16 v[102:105], v[162:165], v[170:173], v[102:105]
	v_mfma_f32_16x16x32_bf16 v[86:89], v[158:161], v[174:177], v[86:89]
	v_mfma_f32_16x16x32_bf16 v[86:89], v[162:165], v[178:181], v[86:89]
	v_mfma_f32_16x16x32_bf16 v[94:97], v[150:153], v[174:177], v[94:97]
	v_mfma_f32_16x16x32_bf16 v[94:97], v[154:157], v[178:181], v[94:97]
	v_mfma_f32_16x16x32_bf16 v[114:117], v[142:145], v[174:177], v[114:117]
	v_mfma_f32_16x16x32_bf16 v[114:117], v[146:149], v[178:181], v[114:117]
	v_mfma_f32_16x16x32_bf16 v[118:121], v[134:137], v[174:177], v[118:121]
	v_mfma_f32_16x16x32_bf16 v[118:121], v[138:141], v[178:181], v[118:121]
	v_mfma_f32_16x16x32_bf16 v[106:109], v[134:137], v[182:185], v[106:109]
	v_mfma_f32_16x16x32_bf16 v[106:109], v[138:141], v[186:189], v[106:109]
	v_mfma_f32_16x16x32_bf16 v[98:101], v[142:145], v[182:185], v[98:101]
	v_mfma_f32_16x16x32_bf16 v[98:101], v[146:149], v[186:189], v[98:101]
	v_mfma_f32_16x16x32_bf16 v[78:81], v[150:153], v[182:185], v[78:81]
	v_mfma_f32_16x16x32_bf16 v[78:81], v[154:157], v[186:189], v[78:81]
	v_mfma_f32_16x16x32_bf16 v[74:77], v[158:161], v[182:185], v[74:77]
	v_mfma_f32_16x16x32_bf16 v[74:77], v[162:165], v[186:189], v[74:77]
	v_mfma_f32_16x16x32_bf16 v[66:69], v[158:161], v[190:193], v[66:69]
	v_mfma_f32_16x16x32_bf16 v[66:69], v[162:165], v[194:197], v[66:69]
	v_mfma_f32_16x16x32_bf16 v[70:73], v[150:153], v[190:193], v[70:73]
	v_mfma_f32_16x16x32_bf16 v[70:73], v[154:157], v[194:197], v[70:73]
	v_mfma_f32_16x16x32_bf16 v[82:85], v[142:145], v[190:193], v[82:85]
	v_mfma_f32_16x16x32_bf16 v[82:85], v[146:149], v[194:197], v[82:85]
	v_mfma_f32_16x16x32_bf16 v[90:93], v[134:137], v[190:193], v[90:93]
	v_mfma_f32_16x16x32_bf16 v[90:93], v[138:141], v[194:197], v[90:93]
	s_setprio 0
	s_barrier
	s_mov_b32 m0, s27
	s_mov_b32 s18, s14
	s_mov_b32 s19, s15
	ds_read_b128 v[166:169], v210 offset:16384
	ds_read_b128 v[170:173], v210 offset:17408
	ds_read_b128 v[174:177], v210 offset:18432
	ds_read_b128 v[178:181], v210 offset:19456
	ds_read_b128 v[182:185], v210 offset:20480
	ds_read_b128 v[186:189], v210 offset:21504
	ds_read_b128 v[190:193], v210 offset:22528
	ds_read_b128 v[194:197], v210 offset:23552
	buffer_load_dwordx4 v207, s[16:19], s85 offen lds
	s_add_i32 s86, s85, 0x158000
	s_mov_b32 m0, s30
	s_nop 0
	buffer_load_dwordx4 v207, s[16:19], s86 offen lds
	s_add_i32 s86, s85, 0x2b0000
	s_mov_b32 m0, s31
	s_nop 0
	buffer_load_dwordx4 v207, s[16:19], s86 offen lds
	s_add_i32 s86, s85, 0x408000
	s_mov_b32 m0, s50
	s_nop 0
	buffer_load_dwordx4 v207, s[16:19], s86 offen lds
	s_mov_b32 m0, s25
	s_add_i32 s86, s83, 0x158000
	buffer_load_dwordx4 v206, s[12:15], s83 offen lds
	s_mov_b32 m0, s51
	s_nop 0
	buffer_load_dwordx4 v206, s[12:15], s86 offen lds
	s_waitcnt vmcnt(8)
	s_waitcnt lgkmcnt(0)
	s_setprio 1
	v_mfma_f32_16x16x32_bf16 v[62:65], v[134:137], v[166:169], v[62:65]
	s_barrier
	v_mfma_f32_16x16x32_bf16 v[62:65], v[138:141], v[170:173], v[62:65]
	v_mfma_f32_16x16x32_bf16 v[58:61], v[142:145], v[166:169], v[58:61]
	v_mfma_f32_16x16x32_bf16 v[58:61], v[146:149], v[170:173], v[58:61]
	v_mfma_f32_16x16x32_bf16 v[46:49], v[150:153], v[166:169], v[46:49]
	v_mfma_f32_16x16x32_bf16 v[46:49], v[154:157], v[170:173], v[46:49]
	v_mfma_f32_16x16x32_bf16 v[38:41], v[158:161], v[166:169], v[38:41]
	v_mfma_f32_16x16x32_bf16 v[38:41], v[162:165], v[170:173], v[38:41]
	v_mfma_f32_16x16x32_bf16 v[22:25], v[158:161], v[174:177], v[22:25]
	v_mfma_f32_16x16x32_bf16 v[22:25], v[162:165], v[178:181], v[22:25]
	v_mfma_f32_16x16x32_bf16 v[30:33], v[150:153], v[174:177], v[30:33]
	v_mfma_f32_16x16x32_bf16 v[30:33], v[154:157], v[178:181], v[30:33]
	v_mfma_f32_16x16x32_bf16 v[50:53], v[142:145], v[174:177], v[50:53]
	v_mfma_f32_16x16x32_bf16 v[50:53], v[146:149], v[178:181], v[50:53]
	v_mfma_f32_16x16x32_bf16 v[54:57], v[134:137], v[174:177], v[54:57]
	v_mfma_f32_16x16x32_bf16 v[54:57], v[138:141], v[178:181], v[54:57]
	v_mfma_f32_16x16x32_bf16 v[42:45], v[134:137], v[182:185], v[42:45]
	v_mfma_f32_16x16x32_bf16 v[42:45], v[138:141], v[186:189], v[42:45]
	v_mfma_f32_16x16x32_bf16 v[34:37], v[142:145], v[182:185], v[34:37]
	v_mfma_f32_16x16x32_bf16 v[34:37], v[146:149], v[186:189], v[34:37]
	v_mfma_f32_16x16x32_bf16 v[14:17], v[150:153], v[182:185], v[14:17]
	v_mfma_f32_16x16x32_bf16 v[14:17], v[154:157], v[186:189], v[14:17]
	v_mfma_f32_16x16x32_bf16 v[10:13], v[158:161], v[182:185], v[10:13]
	v_mfma_f32_16x16x32_bf16 v[10:13], v[162:165], v[186:189], v[10:13]
	v_mfma_f32_16x16x32_bf16 v[2:5], v[158:161], v[190:193], v[2:5]
	v_mfma_f32_16x16x32_bf16 v[2:5], v[162:165], v[194:197], v[2:5]
	v_mfma_f32_16x16x32_bf16 v[6:9], v[150:153], v[190:193], v[6:9]
	v_mfma_f32_16x16x32_bf16 v[6:9], v[154:157], v[194:197], v[6:9]
	v_mfma_f32_16x16x32_bf16 v[18:21], v[142:145], v[190:193], v[18:21]
	v_mfma_f32_16x16x32_bf16 v[18:21], v[146:149], v[194:197], v[18:21]
	v_mfma_f32_16x16x32_bf16 v[26:29], v[134:137], v[190:193], v[26:29]
	v_mfma_f32_16x16x32_bf16 v[26:29], v[138:141], v[194:197], v[26:29]
	s_setprio 0
	s_barrier
	ds_read_b128 v[134:137], v211
	ds_read_b128 v[138:141], v211 offset:1024
	ds_read_b128 v[142:145], v211 offset:2048
	ds_read_b128 v[146:149], v211 offset:3072
	ds_read_b128 v[150:153], v212
	ds_read_b128 v[154:157], v212 offset:1024
	ds_read_b128 v[158:161], v212 offset:2048
	ds_read_b128 v[162:165], v212 offset:3072
	s_mov_b32 m0, s52
	s_add_i32 s86, s83, 0x2b0000
	ds_read_b128 v[166:169], v210 offset:32768
	ds_read_b128 v[170:173], v210 offset:33792
	ds_read_b128 v[174:177], v210 offset:34816
	ds_read_b128 v[178:181], v210 offset:35840
	ds_read_b128 v[182:185], v210 offset:36864
	ds_read_b128 v[186:189], v210 offset:37888
	ds_read_b128 v[190:193], v210 offset:38912
	ds_read_b128 v[194:197], v210 offset:39936
	buffer_load_dwordx4 v206, s[12:15], s86 offen lds
	s_add_i32 s86, s83, 0x408000
	s_mov_b32 m0, s53
	s_nop 0
	buffer_load_dwordx4 v206, s[12:15], s86 offen lds
	s_waitcnt vmcnt(8)
	s_waitcnt lgkmcnt(0)
	s_setprio 1
	v_mfma_f32_16x16x32_bf16 v[126:129], v[134:137], v[166:169], v[126:129]
	s_barrier
	v_mfma_f32_16x16x32_bf16 v[126:129], v[138:141], v[170:173], v[126:129]
	v_mfma_f32_16x16x32_bf16 v[122:125], v[142:145], v[166:169], v[122:125]
	v_mfma_f32_16x16x32_bf16 v[122:125], v[146:149], v[170:173], v[122:125]
	v_mfma_f32_16x16x32_bf16 v[110:113], v[150:153], v[166:169], v[110:113]
	v_mfma_f32_16x16x32_bf16 v[110:113], v[154:157], v[170:173], v[110:113]
	v_mfma_f32_16x16x32_bf16 v[102:105], v[158:161], v[166:169], v[102:105]
	v_mfma_f32_16x16x32_bf16 v[102:105], v[162:165], v[170:173], v[102:105]
	v_mfma_f32_16x16x32_bf16 v[86:89], v[158:161], v[174:177], v[86:89]
	v_mfma_f32_16x16x32_bf16 v[86:89], v[162:165], v[178:181], v[86:89]
	v_mfma_f32_16x16x32_bf16 v[94:97], v[150:153], v[174:177], v[94:97]
	v_mfma_f32_16x16x32_bf16 v[94:97], v[154:157], v[178:181], v[94:97]
	v_mfma_f32_16x16x32_bf16 v[114:117], v[142:145], v[174:177], v[114:117]
	v_mfma_f32_16x16x32_bf16 v[114:117], v[146:149], v[178:181], v[114:117]
	v_mfma_f32_16x16x32_bf16 v[118:121], v[134:137], v[174:177], v[118:121]
	v_mfma_f32_16x16x32_bf16 v[118:121], v[138:141], v[178:181], v[118:121]
	v_mfma_f32_16x16x32_bf16 v[106:109], v[134:137], v[182:185], v[106:109]
	v_mfma_f32_16x16x32_bf16 v[106:109], v[138:141], v[186:189], v[106:109]
	v_mfma_f32_16x16x32_bf16 v[98:101], v[142:145], v[182:185], v[98:101]
	v_mfma_f32_16x16x32_bf16 v[98:101], v[146:149], v[186:189], v[98:101]
	v_mfma_f32_16x16x32_bf16 v[78:81], v[150:153], v[182:185], v[78:81]
	v_mfma_f32_16x16x32_bf16 v[78:81], v[154:157], v[186:189], v[78:81]
	v_mfma_f32_16x16x32_bf16 v[74:77], v[158:161], v[182:185], v[74:77]
	v_mfma_f32_16x16x32_bf16 v[74:77], v[162:165], v[186:189], v[74:77]
	v_mfma_f32_16x16x32_bf16 v[66:69], v[158:161], v[190:193], v[66:69]
	v_mfma_f32_16x16x32_bf16 v[66:69], v[162:165], v[194:197], v[66:69]
	v_mfma_f32_16x16x32_bf16 v[70:73], v[150:153], v[190:193], v[70:73]
	v_mfma_f32_16x16x32_bf16 v[70:73], v[154:157], v[194:197], v[70:73]
	v_mfma_f32_16x16x32_bf16 v[82:85], v[142:145], v[190:193], v[82:85]
	v_mfma_f32_16x16x32_bf16 v[82:85], v[146:149], v[194:197], v[82:85]
	v_mfma_f32_16x16x32_bf16 v[90:93], v[134:137], v[190:193], v[90:93]
	v_mfma_f32_16x16x32_bf16 v[90:93], v[138:141], v[194:197], v[90:93]
	s_setprio 0
	s_barrier
	s_mov_b32 m0, s57
	s_or_b32 s86, s85, 0x80
	ds_read_b128 v[166:169], v210 offset:49152
	ds_read_b128 v[170:173], v210 offset:50176
	ds_read_b128 v[174:177], v210 offset:51200
	ds_read_b128 v[178:181], v210 offset:52224
	ds_read_b128 v[182:185], v210 offset:53248
	ds_read_b128 v[186:189], v210 offset:54272
	ds_read_b128 v[190:193], v210 offset:55296
	ds_read_b128 v[194:197], v210 offset:56320
	buffer_load_dwordx4 v207, s[16:19], s86 offen lds
	s_add_i32 s86, s85, 0x158080
	s_mov_b32 m0, s58
	s_add_i32 s83, s83, 0x158080
	buffer_load_dwordx4 v207, s[16:19], s86 offen lds
	s_add_i32 s86, s85, 0x2b0080
	s_mov_b32 m0, s61
	s_add_i32 s85, s85, 0x408080
	buffer_load_dwordx4 v207, s[16:19], s86 offen lds
	s_mov_b32 m0, s62
	s_nop 0
	buffer_load_dwordx4 v207, s[16:19], s85 offen lds
	s_mov_b32 m0, s59
	s_nop 0
	buffer_load_dwordx4 v206, s[12:15], s84 offen lds
	s_mov_b32 m0, s60
	s_nop 0
	buffer_load_dwordx4 v206, s[12:15], s83 offen lds
	s_waitcnt vmcnt(8)
	s_waitcnt lgkmcnt(0)
	s_setprio 1
	v_mfma_f32_16x16x32_bf16 v[62:65], v[134:137], v[166:169], v[62:65]
	s_barrier
	v_mfma_f32_16x16x32_bf16 v[62:65], v[138:141], v[170:173], v[62:65]
	v_mfma_f32_16x16x32_bf16 v[58:61], v[142:145], v[166:169], v[58:61]
	v_mfma_f32_16x16x32_bf16 v[58:61], v[146:149], v[170:173], v[58:61]
	v_mfma_f32_16x16x32_bf16 v[46:49], v[150:153], v[166:169], v[46:49]
	v_mfma_f32_16x16x32_bf16 v[46:49], v[154:157], v[170:173], v[46:49]
	v_mfma_f32_16x16x32_bf16 v[38:41], v[158:161], v[166:169], v[38:41]
	v_mfma_f32_16x16x32_bf16 v[38:41], v[162:165], v[170:173], v[38:41]
	v_mfma_f32_16x16x32_bf16 v[22:25], v[158:161], v[174:177], v[22:25]
	v_mfma_f32_16x16x32_bf16 v[22:25], v[162:165], v[178:181], v[22:25]
	v_mfma_f32_16x16x32_bf16 v[30:33], v[150:153], v[174:177], v[30:33]
	v_mfma_f32_16x16x32_bf16 v[30:33], v[154:157], v[178:181], v[30:33]
	v_mfma_f32_16x16x32_bf16 v[50:53], v[142:145], v[174:177], v[50:53]
	v_mfma_f32_16x16x32_bf16 v[50:53], v[146:149], v[178:181], v[50:53]
	v_mfma_f32_16x16x32_bf16 v[54:57], v[134:137], v[174:177], v[54:57]
	v_mfma_f32_16x16x32_bf16 v[54:57], v[138:141], v[178:181], v[54:57]
	v_mfma_f32_16x16x32_bf16 v[42:45], v[134:137], v[182:185], v[42:45]
	v_mfma_f32_16x16x32_bf16 v[42:45], v[138:141], v[186:189], v[42:45]
	v_mfma_f32_16x16x32_bf16 v[34:37], v[142:145], v[182:185], v[34:37]
	v_mfma_f32_16x16x32_bf16 v[34:37], v[146:149], v[186:189], v[34:37]
	v_mfma_f32_16x16x32_bf16 v[14:17], v[150:153], v[182:185], v[14:17]
	v_mfma_f32_16x16x32_bf16 v[14:17], v[154:157], v[186:189], v[14:17]
	v_mfma_f32_16x16x32_bf16 v[10:13], v[158:161], v[182:185], v[10:13]
	v_mfma_f32_16x16x32_bf16 v[10:13], v[162:165], v[186:189], v[10:13]
	v_mfma_f32_16x16x32_bf16 v[2:5], v[158:161], v[190:193], v[2:5]
	v_mfma_f32_16x16x32_bf16 v[2:5], v[162:165], v[194:197], v[2:5]
	v_mfma_f32_16x16x32_bf16 v[6:9], v[150:153], v[190:193], v[6:9]
	v_mfma_f32_16x16x32_bf16 v[6:9], v[154:157], v[194:197], v[6:9]
	v_mfma_f32_16x16x32_bf16 v[18:21], v[142:145], v[190:193], v[18:21]
	v_mfma_f32_16x16x32_bf16 v[18:21], v[146:149], v[194:197], v[18:21]
	v_mfma_f32_16x16x32_bf16 v[26:29], v[134:137], v[190:193], v[26:29]
	v_mfma_f32_16x16x32_bf16 v[26:29], v[138:141], v[194:197], v[26:29]
	s_setprio 0
	s_barrier
	s_add_i32 s82, s82, 2
	s_addk_i32 s80, 0x100
	s_addk_i32 s81, 0x100
	s_cmp_ge_i32 s82, s3
	s_cbranch_scc0 .LBB0_1519
	v_pk_mul_f32 v[182:183], v[128:129], 0.5 op_sel_hi:[1,0]
	v_pk_mul_f32 v[184:185], v[126:127], 0.5 op_sel_hi:[1,0]
	v_pk_mul_f32 v[186:187], v[124:125], 0.5 op_sel_hi:[1,0]
	v_pk_mul_f32 v[188:189], v[122:123], 0.5 op_sel_hi:[1,0]
	v_pk_mul_f32 v[196:197], v[112:113], 0.5 op_sel_hi:[1,0]
	v_pk_mul_f32 v[194:195], v[110:111], 0.5 op_sel_hi:[1,0]
	v_pk_mul_f32 v[192:193], v[104:105], 0.5 op_sel_hi:[1,0]
	v_pk_mul_f32 v[190:191], v[102:103], 0.5 op_sel_hi:[1,0]
	v_pk_mul_f32 v[180:181], v[120:121], 0.5 op_sel_hi:[1,0]
	v_pk_mul_f32 v[178:179], v[118:119], 0.5 op_sel_hi:[1,0]
	v_pk_mul_f32 v[176:177], v[116:117], 0.5 op_sel_hi:[1,0]
	v_pk_mul_f32 v[174:175], v[114:115], 0.5 op_sel_hi:[1,0]
	v_pk_mul_f32 v[170:171], v[96:97], 0.5 op_sel_hi:[1,0]
	v_pk_mul_f32 v[168:169], v[94:95], 0.5 op_sel_hi:[1,0]
	v_pk_mul_f32 v[166:167], v[88:89], 0.5 op_sel_hi:[1,0]
	v_pk_mul_f32 v[164:165], v[86:87], 0.5 op_sel_hi:[1,0]
	v_pk_mul_f32 v[162:163], v[108:109], 0.5 op_sel_hi:[1,0]
	v_pk_mul_f32 v[160:161], v[106:107], 0.5 op_sel_hi:[1,0]
	v_pk_mul_f32 v[158:159], v[100:101], 0.5 op_sel_hi:[1,0]
	v_pk_mul_f32 v[156:157], v[98:99], 0.5 op_sel_hi:[1,0]
	v_pk_mul_f32 v[154:155], v[80:81], 0.5 op_sel_hi:[1,0]
	v_pk_mul_f32 v[152:153], v[78:79], 0.5 op_sel_hi:[1,0]
	v_pk_mul_f32 v[150:151], v[76:77], 0.5 op_sel_hi:[1,0]
	v_pk_mul_f32 v[148:149], v[74:75], 0.5 op_sel_hi:[1,0]
	v_pk_mul_f32 v[144:145], v[92:93], 0.5 op_sel_hi:[1,0]
	v_pk_mul_f32 v[142:143], v[90:91], 0.5 op_sel_hi:[1,0]
	v_pk_mul_f32 v[140:141], v[84:85], 0.5 op_sel_hi:[1,0]
	v_pk_mul_f32 v[138:139], v[82:83], 0.5 op_sel_hi:[1,0]
	v_pk_mul_f32 v[136:137], v[72:73], 0.5 op_sel_hi:[1,0]
	v_pk_mul_f32 v[134:135], v[70:71], 0.5 op_sel_hi:[1,0]
	v_pk_mul_f32 v[128:129], v[68:69], 0.5 op_sel_hi:[1,0]
	v_pk_mul_f32 v[126:127], v[66:67], 0.5 op_sel_hi:[1,0]
	v_pk_mul_f32 v[122:123], v[64:65], 0.5 op_sel_hi:[1,0]
	v_pk_mul_f32 v[120:121], v[62:63], 0.5 op_sel_hi:[1,0]
	v_pk_mul_f32 v[118:119], v[60:61], 0.5 op_sel_hi:[1,0]
	v_pk_mul_f32 v[116:117], v[58:59], 0.5 op_sel_hi:[1,0]
	v_pk_mul_f32 v[112:113], v[48:49], 0.5 op_sel_hi:[1,0]
	v_pk_mul_f32 v[110:111], v[46:47], 0.5 op_sel_hi:[1,0]
	v_pk_mul_f32 v[108:109], v[40:41], 0.5 op_sel_hi:[1,0]
	v_pk_mul_f32 v[106:107], v[38:39], 0.5 op_sel_hi:[1,0]
	v_pk_mul_f32 v[104:105], v[56:57], 0.5 op_sel_hi:[1,0]
	v_pk_mul_f32 v[102:103], v[54:55], 0.5 op_sel_hi:[1,0]
	v_pk_mul_f32 v[100:101], v[52:53], 0.5 op_sel_hi:[1,0]
	v_pk_mul_f32 v[98:99], v[50:51], 0.5 op_sel_hi:[1,0]
	v_pk_mul_f32 v[96:97], v[32:33], 0.5 op_sel_hi:[1,0]
	v_pk_mul_f32 v[94:95], v[30:31], 0.5 op_sel_hi:[1,0]
	v_pk_mul_f32 v[92:93], v[24:25], 0.5 op_sel_hi:[1,0]
	v_pk_mul_f32 v[90:91], v[22:23], 0.5 op_sel_hi:[1,0]
	v_pk_mul_f32 v[88:89], v[44:45], 0.5 op_sel_hi:[1,0]
	v_pk_mul_f32 v[86:87], v[42:43], 0.5 op_sel_hi:[1,0]
	v_pk_mul_f32 v[84:85], v[36:37], 0.5 op_sel_hi:[1,0]
	v_pk_mul_f32 v[82:83], v[34:35], 0.5 op_sel_hi:[1,0]
	v_pk_mul_f32 v[80:81], v[16:17], 0.5 op_sel_hi:[1,0]
	v_pk_mul_f32 v[78:79], v[14:15], 0.5 op_sel_hi:[1,0]
	v_pk_mul_f32 v[76:77], v[12:13], 0.5 op_sel_hi:[1,0]
	v_pk_mul_f32 v[74:75], v[10:11], 0.5 op_sel_hi:[1,0]
	v_pk_mul_f32 v[72:73], v[28:29], 0.5 op_sel_hi:[1,0]
	v_pk_mul_f32 v[70:71], v[26:27], 0.5 op_sel_hi:[1,0]
	v_pk_mul_f32 v[68:69], v[20:21], 0.5 op_sel_hi:[1,0]
	v_pk_mul_f32 v[66:67], v[18:19], 0.5 op_sel_hi:[1,0]
	v_pk_mul_f32 v[64:65], v[8:9], 0.5 op_sel_hi:[1,0]
	v_pk_mul_f32 v[62:63], v[6:7], 0.5 op_sel_hi:[1,0]
	v_pk_mul_f32 v[60:61], v[4:5], 0.5 op_sel_hi:[1,0]
	v_pk_mul_f32 v[58:59], v[2:3], 0.5 op_sel_hi:[1,0]
	s_and_b64 vcc, exec, s[40:41]
	s_cbranch_vccz .LBB0_1522
